# v93 plus the four B-fragment LDS read base addresses precomputed once per unit in v241-v244 (two fewer VALU at the head of each X load segment)
# speedup vs baseline: 1.0187x; 1.0007x over previous
; #define PG8_STAGE(bufoff, gbase, voff) do { _Pragma("unroll") for (int _i = 0; _i < 2; ++_i) \
;         __builtin_amdgcn_global_load_lds((const unsigned*)((const char*)(gbase) + (voff)[_i]), (LAS unsigned*)(lds + (bufoff) + ldsw + _i * 8192), 16, 0, 0); } while (0)
; #define PG8_LDA(dst, b, h) do { _Pragma("unroll") for (int m = 0; m < 4; ++m) _Pragma("unroll") for (int k = 0; k < 2; ++k) dst[m][k] = *(const LAS bf16x8*)(lds + PG8_SA(b, h) + aoff + m * 2048 + k * 1024); } while (0)
; #define PG8_LDB(dst, b, h) do { _Pragma("unroll") for (int n = 0; n < 2; ++n) _Pragma("unroll") for (int k = 0; k < 2; ++k) dst[n][k] = *(const LAS bf16x8*)(lds + PG8_SB(b, h) + boff + n * 2048 + k * 1024); } while (0)
; #define PG8_SCHED __builtin_amdgcn_sched_barrier(0)
; template <class Epi, bool ALIGN_EPI>
; __device__ __forceinline__ void gemm_phase(LAS unsigned char* lds, const Gemm g, const StaticOrder& S, const Epi& E, const int tid) {
;     ...
;             const bool last = (t == nt - 2);
;             const char* a1 = cA + (size_t)(t + 1) * kstepA;
;             const char* a2 = last ? nA : cA + (size_t)(t + 2) * kstepA; const char* b2 = last ? nB : cB + (size_t)(t + 2) * kstepB;
;             const char* a3 = a2 + kstepA; const char* b3 = b2 + kstepB;
;             PG8_LDB(B0, 0, 0); PG8_LDB(B1, 0, 1); PG8_SCHED; PG8_LDA(At, 0, 0); PG8_STAGE(PG8_SA(1, 1), a1 + hstepA, voffA);
.LBB0_211:
	s_add_u32 s50, s48, 0x4000
	s_addc_u32 s51, s49, 0
	s_cmp_eq_u32 s89, 28
	s_cselect_b32 s54, s87, s50
	s_cselect_b32 s55, s43, s51
	s_cselect_b32 s52, vcc_lo, vcc_hi
	s_cselect_b32 s53, s35, s88
	s_add_u32 s50, s54, 0x8000
	s_addc_u32 s51, s55, 0
	s_add_i32 s90, 0, 0x10000

; #define PG8_STAGE(bufoff, gbase, voff) do { _Pragma("unroll") for (int _i = 0; _i < 2; ++_i) \
;         __builtin_amdgcn_global_load_lds((const unsigned*)((const char*)(gbase) + (voff)[_i]), (LAS unsigned*)(lds + (bufoff) + ldsw + _i * 8192), 16, 0, 0); } while (0)
; #define PG8_LDA(dst, b, h) do { _Pragma("unroll") for (int m = 0; m < 4; ++m) _Pragma("unroll") for (int k = 0; k < 2; ++k) dst[m][k] = *(const LAS bf16x8*)(lds + PG8_SA(b, h) + aoff + m * 2048 + k * 1024); } while (0)
; #define PG8_LDB(dst, b, h) do { _Pragma("unroll") for (int n = 0; n < 2; ++n) _Pragma("unroll") for (int k = 0; k < 2; ++k) dst[n][k] = *(const LAS bf16x8*)(lds + PG8_SB(b, h) + boff + n * 2048 + k * 1024); } while (0)
; #define PG8_SCHED __builtin_amdgcn_sched_barrier(0)
; template <class Epi, bool ALIGN_EPI>
; __device__ __forceinline__ void gemm_phase(LAS unsigned char* lds, const Gemm g, const StaticOrder& S, const Epi& E, const int tid) {
;     ...
;             PG8_LDB(B0, 0, 0); PG8_LDB(B1, 0, 1); PG8_SCHED; PG8_LDA(At, 0, 0); PG8_STAGE(PG8_SA(1, 1), a1 + hstepA, voffA);
	s_add_i32 s92, 0, 0x14000
	ds_read_b128 v[132:135], v241
	ds_read_b128 v[136:139], v241 offset:1024
	ds_read_b128 v[152:155], v241 offset:2048
	ds_read_b128 v[156:159], v241 offset:3072

; #define PG8_STAGE(bufoff, gbase, voff) do { _Pragma("unroll") for (int _i = 0; _i < 2; ++_i) \
;         __builtin_amdgcn_global_load_lds((const unsigned*)((const char*)(gbase) + (voff)[_i]), (LAS unsigned*)(lds + (bufoff) + ldsw + _i * 8192), 16, 0, 0); } while (0)
; #define PG8_LDA(dst, b, h) do { _Pragma("unroll") for (int m = 0; m < 4; ++m) _Pragma("unroll") for (int k = 0; k < 2; ++k) dst[m][k] = *(const LAS bf16x8*)(lds + PG8_SA(b, h) + aoff + m * 2048 + k * 1024); } while (0)
; #define PG8_LDB(dst, b, h) do { _Pragma("unroll") for (int n = 0; n < 2; ++n) _Pragma("unroll") for (int k = 0; k < 2; ++k) dst[n][k] = *(const LAS bf16x8*)(lds + PG8_SB(b, h) + boff + n * 2048 + k * 1024); } while (0)
; #define PG8_SCHED __builtin_amdgcn_sched_barrier(0)
; template <class Epi, bool ALIGN_EPI>
; __device__ __forceinline__ void gemm_phase(LAS unsigned char* lds, const Gemm g, const StaticOrder& S, const Epi& E, const int tid) {
;     ...
;             PG8_LDB(B0, 0, 0); PG8_LDB(B1, 0, 1); PG8_SCHED; PG8_LDA(At, 0, 0); PG8_STAGE(PG8_SA(1, 1), a1 + hstepA, voffA);
	ds_read_b128 v[162:165], v242
	ds_read_b128 v[166:169], v242 offset:1024
	ds_read_b128 v[170:173], v242 offset:2048
	ds_read_b128 v[174:177], v242 offset:3072
	s_add_i32 m0, s72, 0xc000
	ds_read_b128 v[178:181], v161
	ds_read_b128 v[182:185], v161 offset:1024
	ds_read_b128 v[186:189], v161 offset:2048
	ds_read_b128 v[190:193], v161 offset:3072
	ds_read_b128 v[194:197], v161 offset:4096
	ds_read_b128 v[198:201], v161 offset:5120
	ds_read_b128 v[214:217], v161 offset:6144

; #define PG8_STAGE(bufoff, gbase, voff) do { _Pragma("unroll") for (int _i = 0; _i < 2; ++_i) \
;         __builtin_amdgcn_global_load_lds((const unsigned*)((const char*)(gbase) + (voff)[_i]), (LAS unsigned*)(lds + (bufoff) + ldsw + _i * 8192), 16, 0, 0); } while (0)
; #define PG8_LDA(dst, b, h) do { _Pragma("unroll") for (int m = 0; m < 4; ++m) _Pragma("unroll") for (int k = 0; k < 2; ++k) dst[m][k] = *(const LAS bf16x8*)(lds + PG8_SA(b, h) + aoff + m * 2048 + k * 1024); } while (0)
; #define PG8_LDB(dst, b, h) do { _Pragma("unroll") for (int n = 0; n < 2; ++n) _Pragma("unroll") for (int k = 0; k < 2; ++k) dst[n][k] = *(const LAS bf16x8*)(lds + PG8_SB(b, h) + boff + n * 2048 + k * 1024); } while (0)
; #define PG8_MMA(ai, bj, At, Bt) do { __builtin_amdgcn_s_setprio(1); _Pragma("unroll") for (int m = 0; m < 4; ++m) _Pragma("unroll") for (int n = 0; n < 2; ++n) _Pragma("unroll") for (int k = 0; k < 2; ++k) \
;         acc[ai][bj][m][n] = __builtin_amdgcn_mfma_f32_16x16x32_bf16(Bt[n][k], At[m][k], acc[ai][bj][m][n], 0, 0, 0); __builtin_amdgcn_s_setprio(0); } while (0)
; #define PG8_WAIT_V(n) asm volatile("s_waitcnt vmcnt(" #n ")" ::: "memory")
; #define PG8_WAIT_L(n) asm volatile("s_waitcnt lgkmcnt(" #n ")" ::: "memory")
; #define PG8_BAR __builtin_amdgcn_s_barrier()
; #define PG8_SCHED __builtin_amdgcn_sched_barrier(0)
; template <class Epi, bool ALIGN_EPI>
; __device__ __forceinline__ void gemm_phase(LAS unsigned char* lds, const Gemm g, const StaticOrder& S, const Epi& E, const int tid) {
;     ...
;             PG8_LDB(B0, 0, 0); PG8_LDB(B1, 0, 1); PG8_SCHED; PG8_LDA(At, 0, 0); PG8_STAGE(PG8_SA(1, 1), a1 + hstepA, voffA);
;             PG8_WAIT_V(8); PG8_WAIT_L(0); PG8_BAR; PG8_MMA(0, 0, At, B0); PG8_MMA(0, 1, At, B1); PG8_BAR; PG8_SCHED;
	global_load_lds_dwordx4 v148, s[48:49]
	s_add_i32 m0, s72, 0xe000
	ds_read_b128 v[218:221], v161 offset:7168
	global_load_lds_dwordx4 v150, s[48:49]
	s_waitcnt vmcnt(8)
	s_waitcnt lgkmcnt(0)
	s_barrier


; #define PG8_MMA(ai, bj, At, Bt) do { __builtin_amdgcn_s_setprio(1); _Pragma("unroll") for (int m = 0; m < 4; ++m) _Pragma("unroll") for (int n = 0; n < 2; ++n) _Pragma("unroll") for (int k = 0; k < 2; ++k) \
;         acc[ai][bj][m][n] = __builtin_amdgcn_mfma_f32_16x16x32_bf16(Bt[n][k], At[m][k], acc[ai][bj][m][n], 0, 0, 0); __builtin_amdgcn_s_setprio(0); } while (0)
; #define PG8_WAIT_V(n) asm volatile("s_waitcnt vmcnt(" #n ")" ::: "memory")
; #define PG8_WAIT_L(n) asm volatile("s_waitcnt lgkmcnt(" #n ")" ::: "memory")
; #define PG8_BAR __builtin_amdgcn_s_barrier()
; #define PG8_SCHED __builtin_amdgcn_sched_barrier(0)
; template <class Epi, bool ALIGN_EPI>
; __device__ __forceinline__ void gemm_phase(LAS unsigned char* lds, const Gemm g, const StaticOrder& S, const Epi& E, const int tid) {
;     ...
;             PG8_WAIT_V(8); PG8_WAIT_L(0); PG8_BAR; PG8_MMA(0, 0, At, B0); PG8_MMA(0, 1, At, B1); PG8_BAR; PG8_SCHED;
	v_mfma_f32_16x16x32_bf16 v[88:91], v[132:135], v[178:181], v[88:91]
	v_mfma_f32_16x16x32_bf16 v[88:91], v[136:139], v[182:185], v[88:91]
	v_mfma_f32_16x16x32_bf16 v[124:127], v[156:159], v[182:185], v[124:127]
	v_mfma_f32_16x16x32_bf16 v[124:127], v[152:155], v[178:181], v[124:127]
	v_mfma_f32_16x16x32_bf16 v[128:131], v[170:173], v[178:181], v[128:131]
	v_mfma_f32_16x16x32_bf16 v[128:131], v[174:177], v[182:185], v[128:131]
	v_mfma_f32_16x16x32_bf16 v[80:83], v[166:169], v[182:185], v[80:83]
	v_mfma_f32_16x16x32_bf16 v[80:83], v[162:165], v[178:181], v[80:83]
	v_mfma_f32_16x16x32_bf16 v[68:71], v[162:165], v[186:189], v[68:71]
	v_mfma_f32_16x16x32_bf16 v[68:71], v[166:169], v[190:193], v[68:71]
	v_mfma_f32_16x16x32_bf16 v[108:111], v[174:177], v[190:193], v[108:111]
	v_mfma_f32_16x16x32_bf16 v[108:111], v[170:173], v[186:189], v[108:111]
	v_mfma_f32_16x16x32_bf16 v[120:123], v[152:155], v[186:189], v[120:123]
	v_mfma_f32_16x16x32_bf16 v[120:123], v[156:159], v[190:193], v[120:123]
	v_mfma_f32_16x16x32_bf16 v[52:55], v[136:139], v[190:193], v[52:55]
	v_mfma_f32_16x16x32_bf16 v[52:55], v[132:135], v[186:189], v[52:55]


; #define PG8_MMA(ai, bj, At, Bt) do { __builtin_amdgcn_s_setprio(1); _Pragma("unroll") for (int m = 0; m < 4; ++m) _Pragma("unroll") for (int n = 0; n < 2; ++n) _Pragma("unroll") for (int k = 0; k < 2; ++k) \
;         acc[ai][bj][m][n] = __builtin_amdgcn_mfma_f32_16x16x32_bf16(Bt[n][k], At[m][k], acc[ai][bj][m][n], 0, 0, 0); __builtin_amdgcn_s_setprio(0); } while (0)
; #define PG8_WAIT_V(n) asm volatile("s_waitcnt vmcnt(" #n ")" ::: "memory")
; #define PG8_WAIT_L(n) asm volatile("s_waitcnt lgkmcnt(" #n ")" ::: "memory")
; #define PG8_BAR __builtin_amdgcn_s_barrier()
; #define PG8_SCHED __builtin_amdgcn_sched_barrier(0)
; template <class Epi, bool ALIGN_EPI>
; __device__ __forceinline__ void gemm_phase(LAS unsigned char* lds, const Gemm g, const StaticOrder& S, const Epi& E, const int tid) {
;     ...
;             PG8_WAIT_V(8); PG8_WAIT_L(0); PG8_BAR; PG8_MMA(0, 0, At, B0); PG8_MMA(0, 1, At, B1); PG8_BAR; PG8_SCHED;
	v_mfma_f32_16x16x32_bf16 v[40:43], v[132:135], v[194:197], v[40:43]
	v_mfma_f32_16x16x32_bf16 v[40:43], v[136:139], v[198:201], v[40:43]
	v_mfma_f32_16x16x32_bf16 v[116:119], v[156:159], v[198:201], v[116:119]
	v_mfma_f32_16x16x32_bf16 v[116:119], v[152:155], v[194:197], v[116:119]
	v_mfma_f32_16x16x32_bf16 v[104:107], v[170:173], v[194:197], v[104:107]
	v_mfma_f32_16x16x32_bf16 v[104:107], v[174:177], v[198:201], v[104:107]
	v_mfma_f32_16x16x32_bf16 v[60:63], v[166:169], v[198:201], v[60:63]
	v_mfma_f32_16x16x32_bf16 v[60:63], v[162:165], v[194:197], v[60:63]
	v_mfma_f32_16x16x32_bf16 v[48:51], v[162:165], v[214:217], v[48:51]
	v_mfma_f32_16x16x32_bf16 v[48:51], v[166:169], v[218:221], v[48:51]
	v_mfma_f32_16x16x32_bf16 v[100:103], v[174:177], v[218:221], v[100:103]
	v_mfma_f32_16x16x32_bf16 v[100:103], v[170:173], v[214:217], v[100:103]
	v_mfma_f32_16x16x32_bf16 v[112:115], v[152:155], v[214:217], v[112:115]
	v_mfma_f32_16x16x32_bf16 v[112:115], v[156:159], v[218:221], v[112:115]
	v_mfma_f32_16x16x32_bf16 v[36:39], v[136:139], v[218:221], v[36:39]
	v_mfma_f32_16x16x32_bf16 v[36:39], v[132:135], v[214:217], v[36:39]

; #define PG8_STAGE(bufoff, gbase, voff) do { _Pragma("unroll") for (int _i = 0; _i < 2; ++_i) \
;         __builtin_amdgcn_global_load_lds((const unsigned*)((const char*)(gbase) + (voff)[_i]), (LAS unsigned*)(lds + (bufoff) + ldsw + _i * 8192), 16, 0, 0); } while (0)
; #define PG8_LDA(dst, b, h) do { _Pragma("unroll") for (int m = 0; m < 4; ++m) _Pragma("unroll") for (int k = 0; k < 2; ++k) dst[m][k] = *(const LAS bf16x8*)(lds + PG8_SA(b, h) + aoff + m * 2048 + k * 1024); } while (0)
; #define PG8_MMA(ai, bj, At, Bt) do { __builtin_amdgcn_s_setprio(1); _Pragma("unroll") for (int m = 0; m < 4; ++m) _Pragma("unroll") for (int n = 0; n < 2; ++n) _Pragma("unroll") for (int k = 0; k < 2; ++k) \
;         acc[ai][bj][m][n] = __builtin_amdgcn_mfma_f32_16x16x32_bf16(Bt[n][k], At[m][k], acc[ai][bj][m][n], 0, 0, 0); __builtin_amdgcn_s_setprio(0); } while (0)
; #define PG8_WAIT_V(n) asm volatile("s_waitcnt vmcnt(" #n ")" ::: "memory")
; #define PG8_WAIT_L(n) asm volatile("s_waitcnt lgkmcnt(" #n ")" ::: "memory")
; #define PG8_BAR __builtin_amdgcn_s_barrier()
; #define PG8_SCHED __builtin_amdgcn_sched_barrier(0)
; template <class Epi, bool ALIGN_EPI>
; __device__ __forceinline__ void gemm_phase(LAS unsigned char* lds, const Gemm g, const StaticOrder& S, const Epi& E, const int tid) {
;     ...
;             PG8_WAIT_V(8); PG8_WAIT_L(0); PG8_BAR; PG8_MMA(0, 0, At, B0); PG8_MMA(0, 1, At, B1); PG8_BAR; PG8_SCHED;
;             PG8_LDA(At, 0, 1); PG8_STAGE(PG8_SB(0, 0), b2, voffB); PG8_STAGE(PG8_SB(0, 1), b2 + hstepB, voffB); PG8_STAGE(PG8_SA(0, 0), a2, voffA);
	s_barrier
	s_add_i32 s90, s90, s71
	s_mov_b32 m0, s90
	ds_read_b128 v[178:181], v161 offset:16384
	ds_read_b128 v[182:185], v161 offset:17408
	ds_read_b128 v[186:189], v161 offset:18432
	ds_read_b128 v[190:193], v161 offset:19456


; #define PG8_STAGE(bufoff, gbase, voff) do { _Pragma("unroll") for (int _i = 0; _i < 2; ++_i) \
;         __builtin_amdgcn_global_load_lds((const unsigned*)((const char*)(gbase) + (voff)[_i]), (LAS unsigned*)(lds + (bufoff) + ldsw + _i * 8192), 16, 0, 0); } while (0)
; #define PG8_LDA(dst, b, h) do { _Pragma("unroll") for (int m = 0; m < 4; ++m) _Pragma("unroll") for (int k = 0; k < 2; ++k) dst[m][k] = *(const LAS bf16x8*)(lds + PG8_SA(b, h) + aoff + m * 2048 + k * 1024); } while (0)
; #define PG8_MMA(ai, bj, At, Bt) do { __builtin_amdgcn_s_setprio(1); _Pragma("unroll") for (int m = 0; m < 4; ++m) _Pragma("unroll") for (int n = 0; n < 2; ++n) _Pragma("unroll") for (int k = 0; k < 2; ++k) \
;         acc[ai][bj][m][n] = __builtin_amdgcn_mfma_f32_16x16x32_bf16(Bt[n][k], At[m][k], acc[ai][bj][m][n], 0, 0, 0); __builtin_amdgcn_s_setprio(0); } while (0)
; #define PG8_WAIT_V(n) asm volatile("s_waitcnt vmcnt(" #n ")" ::: "memory")
; #define PG8_WAIT_L(n) asm volatile("s_waitcnt lgkmcnt(" #n ")" ::: "memory")
; #define PG8_BAR __builtin_amdgcn_s_barrier()
; #define PG8_SCHED __builtin_amdgcn_sched_barrier(0)
; template <class Epi, bool ALIGN_EPI>
; __device__ __forceinline__ void gemm_phase(LAS unsigned char* lds, const Gemm g, const StaticOrder& S, const Epi& E, const int tid) {
;     ...
;             PG8_LDA(At, 0, 1); PG8_STAGE(PG8_SB(0, 0), b2, voffB); PG8_STAGE(PG8_SB(0, 1), b2 + hstepB, voffB); PG8_STAGE(PG8_SA(0, 0), a2, voffA);
;             PG8_WAIT_V(8); PG8_WAIT_L(0); PG8_BAR; PG8_MMA(1, 0, At, B0); PG8_MMA(1, 1, At, B1); PG8_BAR; PG8_SCHED;
	global_load_lds_dwordx4 v144, s[52:53]
	s_add_i32 m0, s90, 0x2000
	s_add_u32 s90, s52, 0x4000
	s_addc_u32 s91, s53, 0
	s_add_i32 s92, s92, s71
	global_load_lds_dwordx4 v140, s[52:53]
	s_mov_b32 m0, s92
	ds_read_b128 v[218:221], v161 offset:23552
	global_load_lds_dwordx4 v144, s[90:91]
	s_add_i32 m0, s92, 0x2000
	ds_read_b128 v[214:217], v161 offset:22528
	global_load_lds_dwordx4 v140, s[90:91]
	s_mov_b32 m0, s72
	ds_read_b128 v[198:201], v161 offset:21504
	global_load_lds_dwordx4 v146, s[54:55]
	s_mov_b32 m0, s73
	ds_read_b128 v[194:197], v161 offset:20480
	global_load_lds_dwordx4 v142, s[54:55]
	s_waitcnt vmcnt(8)
	s_waitcnt lgkmcnt(0)
	s_barrier


; #define PG8_MMA(ai, bj, At, Bt) do { __builtin_amdgcn_s_setprio(1); _Pragma("unroll") for (int m = 0; m < 4; ++m) _Pragma("unroll") for (int n = 0; n < 2; ++n) _Pragma("unroll") for (int k = 0; k < 2; ++k) \
;         acc[ai][bj][m][n] = __builtin_amdgcn_mfma_f32_16x16x32_bf16(Bt[n][k], At[m][k], acc[ai][bj][m][n], 0, 0, 0); __builtin_amdgcn_s_setprio(0); } while (0)
; #define PG8_WAIT_V(n) asm volatile("s_waitcnt vmcnt(" #n ")" ::: "memory")
; #define PG8_WAIT_L(n) asm volatile("s_waitcnt lgkmcnt(" #n ")" ::: "memory")
; #define PG8_BAR __builtin_amdgcn_s_barrier()
; #define PG8_SCHED __builtin_amdgcn_sched_barrier(0)
; template <class Epi, bool ALIGN_EPI>
; __device__ __forceinline__ void gemm_phase(LAS unsigned char* lds, const Gemm g, const StaticOrder& S, const Epi& E, const int tid) {
;     ...
;             PG8_WAIT_V(8); PG8_WAIT_L(0); PG8_BAR; PG8_MMA(1, 0, At, B0); PG8_MMA(1, 1, At, B1); PG8_BAR; PG8_SCHED;
	v_mfma_f32_16x16x32_bf16 v[24:27], v[132:135], v[178:181], v[24:27]
	v_mfma_f32_16x16x32_bf16 v[24:27], v[136:139], v[182:185], v[24:27]
	v_mfma_f32_16x16x32_bf16 v[92:95], v[156:159], v[182:185], v[92:95]
	v_mfma_f32_16x16x32_bf16 v[92:95], v[152:155], v[178:181], v[92:95]
	v_mfma_f32_16x16x32_bf16 v[72:75], v[170:173], v[178:181], v[72:75]
	v_mfma_f32_16x16x32_bf16 v[72:75], v[174:177], v[182:185], v[72:75]
	v_mfma_f32_16x16x32_bf16 v[32:35], v[166:169], v[182:185], v[32:35]
	v_mfma_f32_16x16x32_bf16 v[32:35], v[162:165], v[178:181], v[32:35]
	v_mfma_f32_16x16x32_bf16 v[28:31], v[162:165], v[186:189], v[28:31]
	v_mfma_f32_16x16x32_bf16 v[28:31], v[166:169], v[190:193], v[28:31]
	v_mfma_f32_16x16x32_bf16 v[96:99], v[174:177], v[190:193], v[96:99]
	v_mfma_f32_16x16x32_bf16 v[96:99], v[170:173], v[186:189], v[96:99]
	v_mfma_f32_16x16x32_bf16 v[84:87], v[152:155], v[186:189], v[84:87]
	v_mfma_f32_16x16x32_bf16 v[84:87], v[156:159], v[190:193], v[84:87]
	v_mfma_f32_16x16x32_bf16 v[16:19], v[136:139], v[190:193], v[16:19]
	v_mfma_f32_16x16x32_bf16 v[16:19], v[132:135], v[186:189], v[16:19]


; #define PG8_MMA(ai, bj, At, Bt) do { __builtin_amdgcn_s_setprio(1); _Pragma("unroll") for (int m = 0; m < 4; ++m) _Pragma("unroll") for (int n = 0; n < 2; ++n) _Pragma("unroll") for (int k = 0; k < 2; ++k) \
;         acc[ai][bj][m][n] = __builtin_amdgcn_mfma_f32_16x16x32_bf16(Bt[n][k], At[m][k], acc[ai][bj][m][n], 0, 0, 0); __builtin_amdgcn_s_setprio(0); } while (0)
; #define PG8_WAIT_V(n) asm volatile("s_waitcnt vmcnt(" #n ")" ::: "memory")
; #define PG8_WAIT_L(n) asm volatile("s_waitcnt lgkmcnt(" #n ")" ::: "memory")
; #define PG8_BAR __builtin_amdgcn_s_barrier()
; #define PG8_SCHED __builtin_amdgcn_sched_barrier(0)
; template <class Epi, bool ALIGN_EPI>
; __device__ __forceinline__ void gemm_phase(LAS unsigned char* lds, const Gemm g, const StaticOrder& S, const Epi& E, const int tid) {
;     ...
;             PG8_WAIT_V(8); PG8_WAIT_L(0); PG8_BAR; PG8_MMA(1, 0, At, B0); PG8_MMA(1, 1, At, B1); PG8_BAR; PG8_SCHED;
	v_mfma_f32_16x16x32_bf16 v[8:11], v[132:135], v[194:197], v[8:11]
	v_mfma_f32_16x16x32_bf16 v[8:11], v[136:139], v[198:201], v[8:11]
	v_mfma_f32_16x16x32_bf16 v[76:79], v[156:159], v[198:201], v[76:79]
	v_mfma_f32_16x16x32_bf16 v[76:79], v[152:155], v[194:197], v[76:79]
	v_mfma_f32_16x16x32_bf16 v[56:59], v[170:173], v[194:197], v[56:59]
	v_mfma_f32_16x16x32_bf16 v[56:59], v[174:177], v[198:201], v[56:59]
	v_mfma_f32_16x16x32_bf16 v[20:23], v[166:169], v[198:201], v[20:23]
	v_mfma_f32_16x16x32_bf16 v[20:23], v[162:165], v[194:197], v[20:23]
	v_mfma_f32_16x16x32_bf16 v[12:15], v[162:165], v[214:217], v[12:15]
	v_mfma_f32_16x16x32_bf16 v[12:15], v[166:169], v[218:221], v[12:15]
	v_mfma_f32_16x16x32_bf16 v[44:47], v[174:177], v[218:221], v[44:47]
	v_mfma_f32_16x16x32_bf16 v[44:47], v[170:173], v[214:217], v[44:47]
	v_mfma_f32_16x16x32_bf16 v[64:67], v[152:155], v[214:217], v[64:67]
	v_mfma_f32_16x16x32_bf16 v[64:67], v[156:159], v[218:221], v[64:67]
	v_mfma_f32_16x16x32_bf16 v[2:5], v[132:135], v[214:217], v[4:7]
	v_mfma_f32_16x16x32_bf16 v[2:5], v[136:139], v[218:221], v[2:5]

; #define PG8_STAGE(bufoff, gbase, voff) do { _Pragma("unroll") for (int _i = 0; _i < 2; ++_i) \
;         __builtin_amdgcn_global_load_lds((const unsigned*)((const char*)(gbase) + (voff)[_i]), (LAS unsigned*)(lds + (bufoff) + ldsw + _i * 8192), 16, 0, 0); } while (0)
; #define PG8_LDA(dst, b, h) do { _Pragma("unroll") for (int m = 0; m < 4; ++m) _Pragma("unroll") for (int k = 0; k < 2; ++k) dst[m][k] = *(const LAS bf16x8*)(lds + PG8_SA(b, h) + aoff + m * 2048 + k * 1024); } while (0)
; #define PG8_LDB(dst, b, h) do { _Pragma("unroll") for (int n = 0; n < 2; ++n) _Pragma("unroll") for (int k = 0; k < 2; ++k) dst[n][k] = *(const LAS bf16x8*)(lds + PG8_SB(b, h) + boff + n * 2048 + k * 1024); } while (0)
; #define PG8_MMA(ai, bj, At, Bt) do { __builtin_amdgcn_s_setprio(1); _Pragma("unroll") for (int m = 0; m < 4; ++m) _Pragma("unroll") for (int n = 0; n < 2; ++n) _Pragma("unroll") for (int k = 0; k < 2; ++k) \
;         acc[ai][bj][m][n] = __builtin_amdgcn_mfma_f32_16x16x32_bf16(Bt[n][k], At[m][k], acc[ai][bj][m][n], 0, 0, 0); __builtin_amdgcn_s_setprio(0); } while (0)
; #define PG8_WAIT_V(n) asm volatile("s_waitcnt vmcnt(" #n ")" ::: "memory")
; #define PG8_WAIT_L(n) asm volatile("s_waitcnt lgkmcnt(" #n ")" ::: "memory")
; #define PG8_BAR __builtin_amdgcn_s_barrier()
; #define PG8_SCHED __builtin_amdgcn_sched_barrier(0)
; template <class Epi, bool ALIGN_EPI>
; __device__ __forceinline__ void gemm_phase(LAS unsigned char* lds, const Gemm g, const StaticOrder& S, const Epi& E, const int tid) {
;     ...
;             PG8_WAIT_V(8); PG8_WAIT_L(0); PG8_BAR; PG8_MMA(1, 0, At, B0); PG8_MMA(1, 1, At, B1); PG8_BAR; PG8_SCHED;
;             PG8_LDB(B0, 1, 0); PG8_LDB(B1, 1, 1); PG8_SCHED; PG8_LDA(At, 1, 0); PG8_STAGE(PG8_SA(0, 1), a2 + hstepA, voffA);
	s_barrier
	s_add_i32 s90, 0, 0x18000

; #define PG8_STAGE(bufoff, gbase, voff) do { _Pragma("unroll") for (int _i = 0; _i < 2; ++_i) \
;         __builtin_amdgcn_global_load_lds((const unsigned*)((const char*)(gbase) + (voff)[_i]), (LAS unsigned*)(lds + (bufoff) + ldsw + _i * 8192), 16, 0, 0); } while (0)
; #define PG8_LDA(dst, b, h) do { _Pragma("unroll") for (int m = 0; m < 4; ++m) _Pragma("unroll") for (int k = 0; k < 2; ++k) dst[m][k] = *(const LAS bf16x8*)(lds + PG8_SA(b, h) + aoff + m * 2048 + k * 1024); } while (0)
; #define PG8_LDB(dst, b, h) do { _Pragma("unroll") for (int n = 0; n < 2; ++n) _Pragma("unroll") for (int k = 0; k < 2; ++k) dst[n][k] = *(const LAS bf16x8*)(lds + PG8_SB(b, h) + boff + n * 2048 + k * 1024); } while (0)
; #define PG8_SCHED __builtin_amdgcn_sched_barrier(0)
; template <class Epi, bool ALIGN_EPI>
; __device__ __forceinline__ void gemm_phase(LAS unsigned char* lds, const Gemm g, const StaticOrder& S, const Epi& E, const int tid) {
;     ...
;             PG8_LDB(B0, 1, 0); PG8_LDB(B1, 1, 1); PG8_SCHED; PG8_LDA(At, 1, 0); PG8_STAGE(PG8_SA(0, 1), a2 + hstepA, voffA);
	s_add_i32 s91, 0, 0x1c000
	ds_read_b128 v[132:135], v243
	ds_read_b128 v[136:139], v243 offset:1024
	ds_read_b128 v[152:155], v243 offset:2048
	ds_read_b128 v[156:159], v243 offset:3072

; #define PG8_STAGE(bufoff, gbase, voff) do { _Pragma("unroll") for (int _i = 0; _i < 2; ++_i) \
;         __builtin_amdgcn_global_load_lds((const unsigned*)((const char*)(gbase) + (voff)[_i]), (LAS unsigned*)(lds + (bufoff) + ldsw + _i * 8192), 16, 0, 0); } while (0)
; #define PG8_LDA(dst, b, h) do { _Pragma("unroll") for (int m = 0; m < 4; ++m) _Pragma("unroll") for (int k = 0; k < 2; ++k) dst[m][k] = *(const LAS bf16x8*)(lds + PG8_SA(b, h) + aoff + m * 2048 + k * 1024); } while (0)
; #define PG8_LDB(dst, b, h) do { _Pragma("unroll") for (int n = 0; n < 2; ++n) _Pragma("unroll") for (int k = 0; k < 2; ++k) dst[n][k] = *(const LAS bf16x8*)(lds + PG8_SB(b, h) + boff + n * 2048 + k * 1024); } while (0)
; #define PG8_SCHED __builtin_amdgcn_sched_barrier(0)
; template <class Epi, bool ALIGN_EPI>
; __device__ __forceinline__ void gemm_phase(LAS unsigned char* lds, const Gemm g, const StaticOrder& S, const Epi& E, const int tid) {
;     ...
;             PG8_LDB(B0, 1, 0); PG8_LDB(B1, 1, 1); PG8_SCHED; PG8_LDA(At, 1, 0); PG8_STAGE(PG8_SA(0, 1), a2 + hstepA, voffA);
	ds_read_b128 v[162:165], v244
	ds_read_b128 v[166:169], v244 offset:1024
	ds_read_b128 v[170:173], v244 offset:2048
	ds_read_b128 v[174:177], v244 offset:3072
	s_add_u32 s54, s54, 0x4000
	s_addc_u32 s55, s55, 0
	s_mov_b32 m0, s74
	ds_read_b128 v[178:181], v161 offset:32768
	ds_read_b128 v[182:185], v161 offset:33792
	ds_read_b128 v[186:189], v161 offset:34816
	ds_read_b128 v[190:193], v161 offset:35840
	ds_read_b128 v[194:197], v161 offset:36864
	ds_read_b128 v[198:201], v161 offset:37888
	ds_read_b128 v[214:217], v161 offset:38912

; #define PG8_STAGE(bufoff, gbase, voff) do { _Pragma("unroll") for (int _i = 0; _i < 2; ++_i) \
;         __builtin_amdgcn_global_load_lds((const unsigned*)((const char*)(gbase) + (voff)[_i]), (LAS unsigned*)(lds + (bufoff) + ldsw + _i * 8192), 16, 0, 0); } while (0)
; #define PG8_LDA(dst, b, h) do { _Pragma("unroll") for (int m = 0; m < 4; ++m) _Pragma("unroll") for (int k = 0; k < 2; ++k) dst[m][k] = *(const LAS bf16x8*)(lds + PG8_SA(b, h) + aoff + m * 2048 + k * 1024); } while (0)
; #define PG8_LDB(dst, b, h) do { _Pragma("unroll") for (int n = 0; n < 2; ++n) _Pragma("unroll") for (int k = 0; k < 2; ++k) dst[n][k] = *(const LAS bf16x8*)(lds + PG8_SB(b, h) + boff + n * 2048 + k * 1024); } while (0)
; #define PG8_MMA(ai, bj, At, Bt) do { __builtin_amdgcn_s_setprio(1); _Pragma("unroll") for (int m = 0; m < 4; ++m) _Pragma("unroll") for (int n = 0; n < 2; ++n) _Pragma("unroll") for (int k = 0; k < 2; ++k) \
;         acc[ai][bj][m][n] = __builtin_amdgcn_mfma_f32_16x16x32_bf16(Bt[n][k], At[m][k], acc[ai][bj][m][n], 0, 0, 0); __builtin_amdgcn_s_setprio(0); } while (0)
; #define PG8_WAIT_V(n) asm volatile("s_waitcnt vmcnt(" #n ")" ::: "memory")
; #define PG8_WAIT_L(n) asm volatile("s_waitcnt lgkmcnt(" #n ")" ::: "memory")
; #define PG8_BAR __builtin_amdgcn_s_barrier()
; #define PG8_SCHED __builtin_amdgcn_sched_barrier(0)
; template <class Epi, bool ALIGN_EPI>
; __device__ __forceinline__ void gemm_phase(LAS unsigned char* lds, const Gemm g, const StaticOrder& S, const Epi& E, const int tid) {
;     ...
;             PG8_LDB(B0, 1, 0); PG8_LDB(B1, 1, 1); PG8_SCHED; PG8_LDA(At, 1, 0); PG8_STAGE(PG8_SA(0, 1), a2 + hstepA, voffA);
;             PG8_WAIT_V(8); PG8_WAIT_L(0); PG8_BAR; PG8_MMA(0, 0, At, B0); PG8_MMA(0, 1, At, B1); PG8_BAR; PG8_SCHED;
	global_load_lds_dwordx4 v146, s[54:55]
	s_mov_b32 m0, s75
	ds_read_b128 v[218:221], v161 offset:39936
	global_load_lds_dwordx4 v142, s[54:55]
	s_waitcnt vmcnt(8)
	s_waitcnt lgkmcnt(0)
	s_barrier


; #define PG8_MMA(ai, bj, At, Bt) do { __builtin_amdgcn_s_setprio(1); _Pragma("unroll") for (int m = 0; m < 4; ++m) _Pragma("unroll") for (int n = 0; n < 2; ++n) _Pragma("unroll") for (int k = 0; k < 2; ++k) \
;         acc[ai][bj][m][n] = __builtin_amdgcn_mfma_f32_16x16x32_bf16(Bt[n][k], At[m][k], acc[ai][bj][m][n], 0, 0, 0); __builtin_amdgcn_s_setprio(0); } while (0)
; #define PG8_WAIT_V(n) asm volatile("s_waitcnt vmcnt(" #n ")" ::: "memory")
; #define PG8_WAIT_L(n) asm volatile("s_waitcnt lgkmcnt(" #n ")" ::: "memory")
; #define PG8_BAR __builtin_amdgcn_s_barrier()
; #define PG8_SCHED __builtin_amdgcn_sched_barrier(0)
; template <class Epi, bool ALIGN_EPI>
; __device__ __forceinline__ void gemm_phase(LAS unsigned char* lds, const Gemm g, const StaticOrder& S, const Epi& E, const int tid) {
;     ...
;             PG8_WAIT_V(8); PG8_WAIT_L(0); PG8_BAR; PG8_MMA(0, 0, At, B0); PG8_MMA(0, 1, At, B1); PG8_BAR; PG8_SCHED;
	v_mfma_f32_16x16x32_bf16 v[88:91], v[132:135], v[178:181], v[88:91]
	v_mfma_f32_16x16x32_bf16 v[88:91], v[136:139], v[182:185], v[88:91]
	v_mfma_f32_16x16x32_bf16 v[124:127], v[156:159], v[182:185], v[124:127]
	v_mfma_f32_16x16x32_bf16 v[124:127], v[152:155], v[178:181], v[124:127]
	v_mfma_f32_16x16x32_bf16 v[128:131], v[170:173], v[178:181], v[128:131]
	v_mfma_f32_16x16x32_bf16 v[128:131], v[174:177], v[182:185], v[128:131]
	v_mfma_f32_16x16x32_bf16 v[80:83], v[166:169], v[182:185], v[80:83]
	v_mfma_f32_16x16x32_bf16 v[80:83], v[162:165], v[178:181], v[80:83]
	v_mfma_f32_16x16x32_bf16 v[68:71], v[162:165], v[186:189], v[68:71]
	v_mfma_f32_16x16x32_bf16 v[68:71], v[166:169], v[190:193], v[68:71]
	v_mfma_f32_16x16x32_bf16 v[108:111], v[174:177], v[190:193], v[108:111]
	v_mfma_f32_16x16x32_bf16 v[108:111], v[170:173], v[186:189], v[108:111]
	v_mfma_f32_16x16x32_bf16 v[120:123], v[152:155], v[186:189], v[120:123]
	v_mfma_f32_16x16x32_bf16 v[120:123], v[156:159], v[190:193], v[120:123]
	v_mfma_f32_16x16x32_bf16 v[52:55], v[136:139], v[190:193], v[52:55]
	v_mfma_f32_16x16x32_bf16 v[52:55], v[132:135], v[186:189], v[52:55]


; #define PG8_MMA(ai, bj, At, Bt) do { __builtin_amdgcn_s_setprio(1); _Pragma("unroll") for (int m = 0; m < 4; ++m) _Pragma("unroll") for (int n = 0; n < 2; ++n) _Pragma("unroll") for (int k = 0; k < 2; ++k) \
;         acc[ai][bj][m][n] = __builtin_amdgcn_mfma_f32_16x16x32_bf16(Bt[n][k], At[m][k], acc[ai][bj][m][n], 0, 0, 0); __builtin_amdgcn_s_setprio(0); } while (0)
; #define PG8_WAIT_V(n) asm volatile("s_waitcnt vmcnt(" #n ")" ::: "memory")
; #define PG8_WAIT_L(n) asm volatile("s_waitcnt lgkmcnt(" #n ")" ::: "memory")
; #define PG8_BAR __builtin_amdgcn_s_barrier()
; #define PG8_SCHED __builtin_amdgcn_sched_barrier(0)
; template <class Epi, bool ALIGN_EPI>
; __device__ __forceinline__ void gemm_phase(LAS unsigned char* lds, const Gemm g, const StaticOrder& S, const Epi& E, const int tid) {
;     ...
;             PG8_WAIT_V(8); PG8_WAIT_L(0); PG8_BAR; PG8_MMA(0, 0, At, B0); PG8_MMA(0, 1, At, B1); PG8_BAR; PG8_SCHED;
	v_mfma_f32_16x16x32_bf16 v[40:43], v[132:135], v[194:197], v[40:43]
	v_mfma_f32_16x16x32_bf16 v[40:43], v[136:139], v[198:201], v[40:43]
	v_mfma_f32_16x16x32_bf16 v[116:119], v[156:159], v[198:201], v[116:119]
	v_mfma_f32_16x16x32_bf16 v[116:119], v[152:155], v[194:197], v[116:119]
	v_mfma_f32_16x16x32_bf16 v[104:107], v[170:173], v[194:197], v[104:107]
	v_mfma_f32_16x16x32_bf16 v[104:107], v[174:177], v[198:201], v[104:107]
	v_mfma_f32_16x16x32_bf16 v[60:63], v[166:169], v[198:201], v[60:63]
	v_mfma_f32_16x16x32_bf16 v[60:63], v[162:165], v[194:197], v[60:63]
	v_mfma_f32_16x16x32_bf16 v[48:51], v[162:165], v[214:217], v[48:51]
	v_mfma_f32_16x16x32_bf16 v[48:51], v[166:169], v[218:221], v[48:51]
	v_mfma_f32_16x16x32_bf16 v[100:103], v[174:177], v[218:221], v[100:103]
	v_mfma_f32_16x16x32_bf16 v[100:103], v[170:173], v[214:217], v[100:103]
	v_mfma_f32_16x16x32_bf16 v[112:115], v[152:155], v[214:217], v[112:115]
	v_mfma_f32_16x16x32_bf16 v[112:115], v[156:159], v[218:221], v[112:115]
	v_mfma_f32_16x16x32_bf16 v[36:39], v[136:139], v[218:221], v[36:39]
	v_mfma_f32_16x16x32_bf16 v[36:39], v[132:135], v[214:217], v[36:39]

; #define PG8_STAGE(bufoff, gbase, voff) do { _Pragma("unroll") for (int _i = 0; _i < 2; ++_i) \
;         __builtin_amdgcn_global_load_lds((const unsigned*)((const char*)(gbase) + (voff)[_i]), (LAS unsigned*)(lds + (bufoff) + ldsw + _i * 8192), 16, 0, 0); } while (0)
; #define PG8_LDA(dst, b, h) do { _Pragma("unroll") for (int m = 0; m < 4; ++m) _Pragma("unroll") for (int k = 0; k < 2; ++k) dst[m][k] = *(const LAS bf16x8*)(lds + PG8_SA(b, h) + aoff + m * 2048 + k * 1024); } while (0)
; #define PG8_MMA(ai, bj, At, Bt) do { __builtin_amdgcn_s_setprio(1); _Pragma("unroll") for (int m = 0; m < 4; ++m) _Pragma("unroll") for (int n = 0; n < 2; ++n) _Pragma("unroll") for (int k = 0; k < 2; ++k) \
;         acc[ai][bj][m][n] = __builtin_amdgcn_mfma_f32_16x16x32_bf16(Bt[n][k], At[m][k], acc[ai][bj][m][n], 0, 0, 0); __builtin_amdgcn_s_setprio(0); } while (0)
; #define PG8_WAIT_V(n) asm volatile("s_waitcnt vmcnt(" #n ")" ::: "memory")
; #define PG8_WAIT_L(n) asm volatile("s_waitcnt lgkmcnt(" #n ")" ::: "memory")
; #define PG8_BAR __builtin_amdgcn_s_barrier()
; #define PG8_SCHED __builtin_amdgcn_sched_barrier(0)
; template <class Epi, bool ALIGN_EPI>
; __device__ __forceinline__ void gemm_phase(LAS unsigned char* lds, const Gemm g, const StaticOrder& S, const Epi& E, const int tid) {
;     ...
;             PG8_WAIT_V(8); PG8_WAIT_L(0); PG8_BAR; PG8_MMA(0, 0, At, B0); PG8_MMA(0, 1, At, B1); PG8_BAR; PG8_SCHED;
;             PG8_LDA(At, 1, 1); PG8_STAGE(PG8_SB(1, 0), b3, voffB); PG8_STAGE(PG8_SB(1, 1), b3 + hstepB, voffB); PG8_STAGE(PG8_SA(1, 0), a3, voffA);
	s_barrier
	s_add_u32 s54, s52, 0x8000
	s_addc_u32 s55, s53, 0
	s_add_i32 s90, s90, s71
	s_mov_b32 m0, s90
	ds_read_b128 v[178:181], v161 offset:49152
	ds_read_b128 v[182:185], v161 offset:50176
	ds_read_b128 v[186:189], v161 offset:51200
	ds_read_b128 v[190:193], v161 offset:52224


; #define PG8_STAGE(bufoff, gbase, voff) do { _Pragma("unroll") for (int _i = 0; _i < 2; ++_i) \
;         __builtin_amdgcn_global_load_lds((const unsigned*)((const char*)(gbase) + (voff)[_i]), (LAS unsigned*)(lds + (bufoff) + ldsw + _i * 8192), 16, 0, 0); } while (0)
; #define PG8_LDA(dst, b, h) do { _Pragma("unroll") for (int m = 0; m < 4; ++m) _Pragma("unroll") for (int k = 0; k < 2; ++k) dst[m][k] = *(const LAS bf16x8*)(lds + PG8_SA(b, h) + aoff + m * 2048 + k * 1024); } while (0)
; #define PG8_MMA(ai, bj, At, Bt) do { __builtin_amdgcn_s_setprio(1); _Pragma("unroll") for (int m = 0; m < 4; ++m) _Pragma("unroll") for (int n = 0; n < 2; ++n) _Pragma("unroll") for (int k = 0; k < 2; ++k) \
;         acc[ai][bj][m][n] = __builtin_amdgcn_mfma_f32_16x16x32_bf16(Bt[n][k], At[m][k], acc[ai][bj][m][n], 0, 0, 0); __builtin_amdgcn_s_setprio(0); } while (0)
; #define PG8_WAIT_V(n) asm volatile("s_waitcnt vmcnt(" #n ")" ::: "memory")
; #define PG8_WAIT_L(n) asm volatile("s_waitcnt lgkmcnt(" #n ")" ::: "memory")
; #define PG8_BAR __builtin_amdgcn_s_barrier()
; #define PG8_SCHED __builtin_amdgcn_sched_barrier(0)
; template <class Epi, bool ALIGN_EPI>
; __device__ __forceinline__ void gemm_phase(LAS unsigned char* lds, const Gemm g, const StaticOrder& S, const Epi& E, const int tid) {
;     ...
;             PG8_LDA(At, 1, 1); PG8_STAGE(PG8_SB(1, 0), b3, voffB); PG8_STAGE(PG8_SB(1, 1), b3 + hstepB, voffB); PG8_STAGE(PG8_SA(1, 0), a3, voffA);
;             PG8_WAIT_V(8); PG8_WAIT_L(0); PG8_BAR; PG8_MMA(1, 0, At, B0); PG8_MMA(1, 1, At, B1); PG8_BAR; PG8_SCHED;
	global_load_lds_dwordx4 v144, s[54:55]
	s_add_i32 m0, s90, 0x2000
	s_add_u32 s52, s52, 0xc000
	s_addc_u32 s53, s53, 0
	global_load_lds_dwordx4 v140, s[54:55]
	s_add_i32 s54, s91, s71
	s_mov_b32 m0, s54
	ds_read_b128 v[218:221], v161 offset:56320
	global_load_lds_dwordx4 v144, s[52:53]
	s_add_i32 m0, s54, 0x2000
	ds_read_b128 v[214:217], v161 offset:55296
	global_load_lds_dwordx4 v140, s[52:53]
	s_mov_b32 m0, s79
	ds_read_b128 v[198:201], v161 offset:54272
	global_load_lds_dwordx4 v146, s[50:51]
	s_mov_b32 m0, s80
	ds_read_b128 v[194:197], v161 offset:53248
	global_load_lds_dwordx4 v142, s[50:51]
	s_waitcnt vmcnt(8)
	s_waitcnt lgkmcnt(0)
	s_barrier


; #define PG8_MMA(ai, bj, At, Bt) do { __builtin_amdgcn_s_setprio(1); _Pragma("unroll") for (int m = 0; m < 4; ++m) _Pragma("unroll") for (int n = 0; n < 2; ++n) _Pragma("unroll") for (int k = 0; k < 2; ++k) \
;         acc[ai][bj][m][n] = __builtin_amdgcn_mfma_f32_16x16x32_bf16(Bt[n][k], At[m][k], acc[ai][bj][m][n], 0, 0, 0); __builtin_amdgcn_s_setprio(0); } while (0)
; #define PG8_WAIT_V(n) asm volatile("s_waitcnt vmcnt(" #n ")" ::: "memory")
; #define PG8_WAIT_L(n) asm volatile("s_waitcnt lgkmcnt(" #n ")" ::: "memory")
; #define PG8_BAR __builtin_amdgcn_s_barrier()
; #define PG8_SCHED __builtin_amdgcn_sched_barrier(0)
; template <class Epi, bool ALIGN_EPI>
; __device__ __forceinline__ void gemm_phase(LAS unsigned char* lds, const Gemm g, const StaticOrder& S, const Epi& E, const int tid) {
;     ...
;             PG8_WAIT_V(8); PG8_WAIT_L(0); PG8_BAR; PG8_MMA(1, 0, At, B0); PG8_MMA(1, 1, At, B1); PG8_BAR; PG8_SCHED;
	v_mfma_f32_16x16x32_bf16 v[24:27], v[132:135], v[178:181], v[24:27]
	v_mfma_f32_16x16x32_bf16 v[24:27], v[136:139], v[182:185], v[24:27]
	v_mfma_f32_16x16x32_bf16 v[92:95], v[156:159], v[182:185], v[92:95]
	v_mfma_f32_16x16x32_bf16 v[92:95], v[152:155], v[178:181], v[92:95]
	v_mfma_f32_16x16x32_bf16 v[72:75], v[170:173], v[178:181], v[72:75]
	v_mfma_f32_16x16x32_bf16 v[72:75], v[174:177], v[182:185], v[72:75]
	v_mfma_f32_16x16x32_bf16 v[32:35], v[166:169], v[182:185], v[32:35]
	v_mfma_f32_16x16x32_bf16 v[32:35], v[162:165], v[178:181], v[32:35]
	v_mfma_f32_16x16x32_bf16 v[28:31], v[162:165], v[186:189], v[28:31]
	v_mfma_f32_16x16x32_bf16 v[28:31], v[166:169], v[190:193], v[28:31]
	v_mfma_f32_16x16x32_bf16 v[96:99], v[174:177], v[190:193], v[96:99]
	v_mfma_f32_16x16x32_bf16 v[96:99], v[170:173], v[186:189], v[96:99]
	v_mfma_f32_16x16x32_bf16 v[84:87], v[152:155], v[186:189], v[84:87]
	v_mfma_f32_16x16x32_bf16 v[84:87], v[156:159], v[190:193], v[84:87]
	v_mfma_f32_16x16x32_bf16 v[16:19], v[136:139], v[190:193], v[16:19]
	v_mfma_f32_16x16x32_bf16 v[16:19], v[132:135], v[186:189], v[16:19]


; #define PG8_MMA(ai, bj, At, Bt) do { __builtin_amdgcn_s_setprio(1); _Pragma("unroll") for (int m = 0; m < 4; ++m) _Pragma("unroll") for (int n = 0; n < 2; ++n) _Pragma("unroll") for (int k = 0; k < 2; ++k) \
;         acc[ai][bj][m][n] = __builtin_amdgcn_mfma_f32_16x16x32_bf16(Bt[n][k], At[m][k], acc[ai][bj][m][n], 0, 0, 0); __builtin_amdgcn_s_setprio(0); } while (0)
; #define PG8_WAIT_V(n) asm volatile("s_waitcnt vmcnt(" #n ")" ::: "memory")
; #define PG8_WAIT_L(n) asm volatile("s_waitcnt lgkmcnt(" #n ")" ::: "memory")
; #define PG8_BAR __builtin_amdgcn_s_barrier()
; #define PG8_SCHED __builtin_amdgcn_sched_barrier(0)
; template <class Epi, bool ALIGN_EPI>
; __device__ __forceinline__ void gemm_phase(LAS unsigned char* lds, const Gemm g, const StaticOrder& S, const Epi& E, const int tid) {
;     ...
;             PG8_WAIT_V(8); PG8_WAIT_L(0); PG8_BAR; PG8_MMA(1, 0, At, B0); PG8_MMA(1, 1, At, B1); PG8_BAR; PG8_SCHED;
	v_mfma_f32_16x16x32_bf16 v[6:9], v[132:135], v[194:197], v[8:11]
	v_mfma_f32_16x16x32_bf16 v[8:11], v[136:139], v[198:201], v[6:9]
	v_mfma_f32_16x16x32_bf16 v[76:79], v[156:159], v[198:201], v[76:79]
	v_mfma_f32_16x16x32_bf16 v[76:79], v[152:155], v[194:197], v[76:79]
	v_mfma_f32_16x16x32_bf16 v[56:59], v[170:173], v[194:197], v[56:59]
	v_mfma_f32_16x16x32_bf16 v[56:59], v[174:177], v[198:201], v[56:59]
	v_mfma_f32_16x16x32_bf16 v[20:23], v[166:169], v[198:201], v[20:23]
	v_mfma_f32_16x16x32_bf16 v[20:23], v[162:165], v[194:197], v[20:23]
	v_mfma_f32_16x16x32_bf16 v[12:15], v[162:165], v[214:217], v[12:15]
	v_mfma_f32_16x16x32_bf16 v[12:15], v[166:169], v[218:221], v[12:15]
	v_mfma_f32_16x16x32_bf16 v[44:47], v[174:177], v[218:221], v[44:47]
	v_mfma_f32_16x16x32_bf16 v[44:47], v[170:173], v[214:217], v[44:47]
	v_mfma_f32_16x16x32_bf16 v[64:67], v[152:155], v[214:217], v[64:67]
	v_mfma_f32_16x16x32_bf16 v[64:67], v[156:159], v[218:221], v[64:67]
	v_mfma_f32_16x16x32_bf16 v[2:5], v[132:135], v[214:217], v[2:5]
	v_mfma_f32_16x16x32_bf16 v[4:7], v[136:139], v[218:221], v[2:5]

; #define PG8_STAGE(bufoff, gbase, voff) do { _Pragma("unroll") for (int _i = 0; _i < 2; ++_i) \
;         __builtin_amdgcn_global_load_lds((const unsigned*)((const char*)(gbase) + (voff)[_i]), (LAS unsigned*)(lds + (bufoff) + ldsw + _i * 8192), 16, 0, 0); } while (0)
; #define PG8_LDA(dst, b, h) do { _Pragma("unroll") for (int m = 0; m < 4; ++m) _Pragma("unroll") for (int k = 0; k < 2; ++k) dst[m][k] = *(const LAS bf16x8*)(lds + PG8_SA(b, h) + aoff + m * 2048 + k * 1024); } while (0)
; #define PG8_LDB(dst, b, h) do { _Pragma("unroll") for (int n = 0; n < 2; ++n) _Pragma("unroll") for (int k = 0; k < 2; ++k) dst[n][k] = *(const LAS bf16x8*)(lds + PG8_SB(b, h) + boff + n * 2048 + k * 1024); } while (0)
; #define PG8_BAR __builtin_amdgcn_s_barrier()
; template <class Epi, bool ALIGN_EPI>
; __device__ __forceinline__ void gemm_phase(LAS unsigned char* lds, const Gemm g, const StaticOrder& S, const Epi& E, const int tid) {
;     ...
;         for (int t = 0; t < nt; t += 2) {
;             const bool last = (t == nt - 2);
;             const char* a1 = cA + (size_t)(t + 1) * kstepA;
;             const char* a2 = last ? nA : cA + (size_t)(t + 2) * kstepA; const char* b2 = last ? nB : cB + (size_t)(t + 2) * kstepB;
;             const char* a3 = a2 + kstepA; const char* b3 = b2 + kstepB;
;             PG8_LDB(B0, 0, 0); PG8_LDB(B1, 0, 1); PG8_SCHED; PG8_LDA(At, 0, 0); PG8_STAGE(PG8_SA(1, 1), a1 + hstepA, voffA);
;             PG8_WAIT_V(8); PG8_WAIT_L(0); PG8_BAR; PG8_MMA(0, 0, At, B0); PG8_MMA(0, 1, At, B1); PG8_BAR; PG8_SCHED;
;             PG8_LDA(At, 0, 1); PG8_STAGE(PG8_SB(0, 0), b2, voffB); PG8_STAGE(PG8_SB(0, 1), b2 + hstepB, voffB); PG8_STAGE(PG8_SA(0, 0), a2, voffA);
;             PG8_WAIT_V(8); PG8_WAIT_L(0); PG8_BAR; PG8_MMA(1, 0, At, B0); PG8_MMA(1, 1, At, B1); PG8_BAR; PG8_SCHED;
;             PG8_LDB(B0, 1, 0); PG8_LDB(B1, 1, 1); PG8_SCHED; PG8_LDA(At, 1, 0); PG8_STAGE(PG8_SA(0, 1), a2 + hstepA, voffA);
;             PG8_WAIT_V(8); PG8_WAIT_L(0); PG8_BAR; PG8_MMA(0, 0, At, B0); PG8_MMA(0, 1, At, B1); PG8_BAR; PG8_SCHED;
;             PG8_LDA(At, 1, 1); PG8_STAGE(PG8_SB(1, 0), b3, voffB); PG8_STAGE(PG8_SB(1, 1), b3 + hstepB, voffB); PG8_STAGE(PG8_SA(1, 0), a3, voffA);
;             PG8_WAIT_V(8); PG8_WAIT_L(0); PG8_BAR; PG8_MMA(1, 0, At, B0); PG8_MMA(1, 1, At, B1); PG8_BAR; PG8_SCHED;
;         }
;         if constexpr (ALIGN_EPI) { if (wr == 0) PG8_BAR; }
	s_barrier
	s_add_i32 s89, s89, 2
	s_add_u32 s48, s48, 0x10000
	s_addc_u32 s49, s49, 0
	s_add_u32 vcc_hi, vcc_hi, 0x10000
	s_addc_u32 s88, s88, 0
	s_cmp_gt_u32 s89, 29
	s_cbranch_scc0 .LBB0_211
	s_and_b64 vcc, exec, s[22:23]
	s_cbranch_vccz .LBB0_214
	s_barrier

; #define PG8_STAGE(bufoff, gbase, voff) do { _Pragma("unroll") for (int _i = 0; _i < 2; ++_i) \
;         __builtin_amdgcn_global_load_lds((const unsigned*)((const char*)(gbase) + (voff)[_i]), (LAS unsigned*)(lds + (bufoff) + ldsw + _i * 8192), 16, 0, 0); } while (0)
; #define PG8_LDA(dst, b, h) do { _Pragma("unroll") for (int m = 0; m < 4; ++m) _Pragma("unroll") for (int k = 0; k < 2; ++k) dst[m][k] = *(const LAS bf16x8*)(lds + PG8_SA(b, h) + aoff + m * 2048 + k * 1024); } while (0)
; #define PG8_LDB(dst, b, h) do { _Pragma("unroll") for (int n = 0; n < 2; ++n) _Pragma("unroll") for (int k = 0; k < 2; ++k) dst[n][k] = *(const LAS bf16x8*)(lds + PG8_SB(b, h) + boff + n * 2048 + k * 1024); } while (0)
; #define PG8_SCHED __builtin_amdgcn_sched_barrier(0)
; template <class Epi, bool ALIGN_EPI>
; __device__ __forceinline__ void gemm_phase(LAS unsigned char* lds, const Gemm g, const StaticOrder& S, const Epi& E, const int tid) {
;     ...
;             const bool last = (t == nt - 2);
;             const char* a1 = cA + (size_t)(t + 1) * kstepA;
;             const char* a2 = last ? nA : cA + (size_t)(t + 2) * kstepA; const char* b2 = last ? nB : cB + (size_t)(t + 2) * kstepB;
;             const char* a3 = a2 + kstepA; const char* b3 = b2 + kstepB;
;             PG8_LDB(B0, 0, 0); PG8_LDB(B1, 0, 1); PG8_SCHED; PG8_LDA(At, 0, 0); PG8_STAGE(PG8_SA(1, 1), a1 + hstepA, voffA);
.LBB0_294:
	s_add_u32 s22, s10, 0x4000
	s_addc_u32 s23, s11, 0
	s_cmpk_eq_i32 s86, 0x54
	s_cselect_b32 s42, s48, s22
	s_cselect_b32 s43, s49, s23
	s_cselect_b32 s34, s50, s84
	s_cselect_b32 s35, s51, s85
	s_add_u32 s22, s42, 0x8000
	s_addc_u32 s23, s43, 0
	s_add_i32 s87, 0, 0x10000

; #define PG8_STAGE(bufoff, gbase, voff) do { _Pragma("unroll") for (int _i = 0; _i < 2; ++_i) \
;         __builtin_amdgcn_global_load_lds((const unsigned*)((const char*)(gbase) + (voff)[_i]), (LAS unsigned*)(lds + (bufoff) + ldsw + _i * 8192), 16, 0, 0); } while (0)
; #define PG8_LDA(dst, b, h) do { _Pragma("unroll") for (int m = 0; m < 4; ++m) _Pragma("unroll") for (int k = 0; k < 2; ++k) dst[m][k] = *(const LAS bf16x8*)(lds + PG8_SA(b, h) + aoff + m * 2048 + k * 1024); } while (0)
; #define PG8_LDB(dst, b, h) do { _Pragma("unroll") for (int n = 0; n < 2; ++n) _Pragma("unroll") for (int k = 0; k < 2; ++k) dst[n][k] = *(const LAS bf16x8*)(lds + PG8_SB(b, h) + boff + n * 2048 + k * 1024); } while (0)
; #define PG8_SCHED __builtin_amdgcn_sched_barrier(0)
; template <class Epi, bool ALIGN_EPI>
; __device__ __forceinline__ void gemm_phase(LAS unsigned char* lds, const Gemm g, const StaticOrder& S, const Epi& E, const int tid) {
;     ...
;             PG8_LDB(B0, 0, 0); PG8_LDB(B1, 0, 1); PG8_SCHED; PG8_LDA(At, 0, 0); PG8_STAGE(PG8_SA(1, 1), a1 + hstepA, voffA);
	s_add_i32 s90, 0, 0x14000
	s_waitcnt lgkmcnt(0)
	ds_read_b128 v[132:135], v241
	ds_read_b128 v[148:151], v241 offset:1024
	ds_read_b128 v[156:159], v241 offset:2048
	ds_read_b128 v[160:163], v241 offset:3072

; #define PG8_STAGE(bufoff, gbase, voff) do { _Pragma("unroll") for (int _i = 0; _i < 2; ++_i) \
;         __builtin_amdgcn_global_load_lds((const unsigned*)((const char*)(gbase) + (voff)[_i]), (LAS unsigned*)(lds + (bufoff) + ldsw + _i * 8192), 16, 0, 0); } while (0)
; #define PG8_LDA(dst, b, h) do { _Pragma("unroll") for (int m = 0; m < 4; ++m) _Pragma("unroll") for (int k = 0; k < 2; ++k) dst[m][k] = *(const LAS bf16x8*)(lds + PG8_SA(b, h) + aoff + m * 2048 + k * 1024); } while (0)
; #define PG8_LDB(dst, b, h) do { _Pragma("unroll") for (int n = 0; n < 2; ++n) _Pragma("unroll") for (int k = 0; k < 2; ++k) dst[n][k] = *(const LAS bf16x8*)(lds + PG8_SB(b, h) + boff + n * 2048 + k * 1024); } while (0)
; #define PG8_SCHED __builtin_amdgcn_sched_barrier(0)
; template <class Epi, bool ALIGN_EPI>
; __device__ __forceinline__ void gemm_phase(LAS unsigned char* lds, const Gemm g, const StaticOrder& S, const Epi& E, const int tid) {
;     ...
;             PG8_LDB(B0, 0, 0); PG8_LDB(B1, 0, 1); PG8_SCHED; PG8_LDA(At, 0, 0); PG8_STAGE(PG8_SA(1, 1), a1 + hstepA, voffA);
	ds_read_b128 v[164:167], v242
	ds_read_b128 v[168:171], v242 offset:1024
	ds_read_b128 v[172:175], v242 offset:2048
	ds_read_b128 v[176:179], v242 offset:3072
	s_add_i32 m0, s57, 0xc000
	ds_read_b128 v[180:183], v155
	ds_read_b128 v[184:187], v155 offset:1024
	ds_read_b128 v[188:191], v155 offset:2048
	ds_read_b128 v[192:195], v155 offset:3072
	ds_read_b128 v[196:199], v155 offset:4096
	ds_read_b128 v[214:217], v155 offset:5120
	ds_read_b128 v[218:221], v155 offset:6144

; #define PG8_STAGE(bufoff, gbase, voff) do { _Pragma("unroll") for (int _i = 0; _i < 2; ++_i) \
;         __builtin_amdgcn_global_load_lds((const unsigned*)((const char*)(gbase) + (voff)[_i]), (LAS unsigned*)(lds + (bufoff) + ldsw + _i * 8192), 16, 0, 0); } while (0)
; #define PG8_LDA(dst, b, h) do { _Pragma("unroll") for (int m = 0; m < 4; ++m) _Pragma("unroll") for (int k = 0; k < 2; ++k) dst[m][k] = *(const LAS bf16x8*)(lds + PG8_SA(b, h) + aoff + m * 2048 + k * 1024); } while (0)
; #define PG8_LDB(dst, b, h) do { _Pragma("unroll") for (int n = 0; n < 2; ++n) _Pragma("unroll") for (int k = 0; k < 2; ++k) dst[n][k] = *(const LAS bf16x8*)(lds + PG8_SB(b, h) + boff + n * 2048 + k * 1024); } while (0)
; #define PG8_MMA(ai, bj, At, Bt) do { __builtin_amdgcn_s_setprio(1); _Pragma("unroll") for (int m = 0; m < 4; ++m) _Pragma("unroll") for (int n = 0; n < 2; ++n) _Pragma("unroll") for (int k = 0; k < 2; ++k) \
;         acc[ai][bj][m][n] = __builtin_amdgcn_mfma_f32_16x16x32_bf16(Bt[n][k], At[m][k], acc[ai][bj][m][n], 0, 0, 0); __builtin_amdgcn_s_setprio(0); } while (0)
; #define PG8_WAIT_V(n) asm volatile("s_waitcnt vmcnt(" #n ")" ::: "memory")
; #define PG8_WAIT_L(n) asm volatile("s_waitcnt lgkmcnt(" #n ")" ::: "memory")
; #define PG8_BAR __builtin_amdgcn_s_barrier()
; #define PG8_SCHED __builtin_amdgcn_sched_barrier(0)
; template <class Epi, bool ALIGN_EPI>
; __device__ __forceinline__ void gemm_phase(LAS unsigned char* lds, const Gemm g, const StaticOrder& S, const Epi& E, const int tid) {
;     ...
;             PG8_LDB(B0, 0, 0); PG8_LDB(B1, 0, 1); PG8_SCHED; PG8_LDA(At, 0, 0); PG8_STAGE(PG8_SA(1, 1), a1 + hstepA, voffA);
;             PG8_WAIT_V(8); PG8_WAIT_L(0); PG8_BAR; PG8_MMA(0, 0, At, B0); PG8_MMA(0, 1, At, B1); PG8_BAR; PG8_SCHED;
	global_load_lds_dwordx4 v144, s[10:11]
	s_add_i32 m0, s57, 0xe000
	ds_read_b128 v[222:225], v155 offset:7168
	global_load_lds_dwordx4 v146, s[10:11]
	s_waitcnt vmcnt(8)
	s_waitcnt lgkmcnt(0)
	s_barrier


; #define PG8_MMA(ai, bj, At, Bt) do { __builtin_amdgcn_s_setprio(1); _Pragma("unroll") for (int m = 0; m < 4; ++m) _Pragma("unroll") for (int n = 0; n < 2; ++n) _Pragma("unroll") for (int k = 0; k < 2; ++k) \
;         acc[ai][bj][m][n] = __builtin_amdgcn_mfma_f32_16x16x32_bf16(Bt[n][k], At[m][k], acc[ai][bj][m][n], 0, 0, 0); __builtin_amdgcn_s_setprio(0); } while (0)
; #define PG8_WAIT_V(n) asm volatile("s_waitcnt vmcnt(" #n ")" ::: "memory")
; #define PG8_WAIT_L(n) asm volatile("s_waitcnt lgkmcnt(" #n ")" ::: "memory")
; #define PG8_BAR __builtin_amdgcn_s_barrier()
; #define PG8_SCHED __builtin_amdgcn_sched_barrier(0)
; template <class Epi, bool ALIGN_EPI>
; __device__ __forceinline__ void gemm_phase(LAS unsigned char* lds, const Gemm g, const StaticOrder& S, const Epi& E, const int tid) {
;     ...
;             PG8_WAIT_V(8); PG8_WAIT_L(0); PG8_BAR; PG8_MMA(0, 0, At, B0); PG8_MMA(0, 1, At, B1); PG8_BAR; PG8_SCHED;
	v_mfma_f32_16x16x32_bf16 v[8:11], v[132:135], v[180:183], v[8:11]
	v_mfma_f32_16x16x32_bf16 v[8:11], v[148:151], v[184:187], v[8:11]
	v_mfma_f32_16x16x32_bf16 v[56:59], v[160:163], v[184:187], v[56:59]
	v_mfma_f32_16x16x32_bf16 v[56:59], v[156:159], v[180:183], v[56:59]
	v_mfma_f32_16x16x32_bf16 v[28:31], v[172:175], v[180:183], v[28:31]
	v_mfma_f32_16x16x32_bf16 v[28:31], v[176:179], v[184:187], v[28:31]
	v_mfma_f32_16x16x32_bf16 v[2:5], v[164:167], v[180:183], v[4:7]
	v_mfma_f32_16x16x32_bf16 v[2:5], v[168:171], v[184:187], v[2:5]
	v_mfma_f32_16x16x32_bf16 v[96:99], v[168:171], v[192:195], v[96:99]
	v_mfma_f32_16x16x32_bf16 v[96:99], v[164:167], v[188:191], v[96:99]
	v_mfma_f32_16x16x32_bf16 v[92:95], v[172:175], v[188:191], v[92:95]
	v_mfma_f32_16x16x32_bf16 v[92:95], v[176:179], v[192:195], v[92:95]
	v_mfma_f32_16x16x32_bf16 v[48:51], v[160:163], v[192:195], v[48:51]
	v_mfma_f32_16x16x32_bf16 v[48:51], v[156:159], v[188:191], v[48:51]
	v_mfma_f32_16x16x32_bf16 v[52:55], v[132:135], v[188:191], v[52:55]
	v_mfma_f32_16x16x32_bf16 v[52:55], v[148:151], v[192:195], v[52:55]


; #define PG8_MMA(ai, bj, At, Bt) do { __builtin_amdgcn_s_setprio(1); _Pragma("unroll") for (int m = 0; m < 4; ++m) _Pragma("unroll") for (int n = 0; n < 2; ++n) _Pragma("unroll") for (int k = 0; k < 2; ++k) \
;         acc[ai][bj][m][n] = __builtin_amdgcn_mfma_f32_16x16x32_bf16(Bt[n][k], At[m][k], acc[ai][bj][m][n], 0, 0, 0); __builtin_amdgcn_s_setprio(0); } while (0)
; #define PG8_WAIT_V(n) asm volatile("s_waitcnt vmcnt(" #n ")" ::: "memory")
; #define PG8_WAIT_L(n) asm volatile("s_waitcnt lgkmcnt(" #n ")" ::: "memory")
; #define PG8_BAR __builtin_amdgcn_s_barrier()
; #define PG8_SCHED __builtin_amdgcn_sched_barrier(0)
; template <class Epi, bool ALIGN_EPI>
; __device__ __forceinline__ void gemm_phase(LAS unsigned char* lds, const Gemm g, const StaticOrder& S, const Epi& E, const int tid) {
;     ...
;             PG8_WAIT_V(8); PG8_WAIT_L(0); PG8_BAR; PG8_MMA(0, 0, At, B0); PG8_MMA(0, 1, At, B1); PG8_BAR; PG8_SCHED;
	v_mfma_f32_16x16x32_bf16 v[44:47], v[148:151], v[214:217], v[44:47]
	v_mfma_f32_16x16x32_bf16 v[44:47], v[132:135], v[196:199], v[44:47]
	v_mfma_f32_16x16x32_bf16 v[40:43], v[156:159], v[196:199], v[40:43]
	v_mfma_f32_16x16x32_bf16 v[40:43], v[160:163], v[214:217], v[40:43]
	v_mfma_f32_16x16x32_bf16 v[84:87], v[176:179], v[214:217], v[84:87]
	v_mfma_f32_16x16x32_bf16 v[84:87], v[172:175], v[196:199], v[84:87]
	v_mfma_f32_16x16x32_bf16 v[88:91], v[164:167], v[196:199], v[88:91]
	v_mfma_f32_16x16x32_bf16 v[88:91], v[168:171], v[214:217], v[88:91]
	v_mfma_f32_16x16x32_bf16 v[80:83], v[168:171], v[222:225], v[80:83]
	v_mfma_f32_16x16x32_bf16 v[80:83], v[164:167], v[218:221], v[80:83]
	v_mfma_f32_16x16x32_bf16 v[76:79], v[172:175], v[218:221], v[76:79]
	v_mfma_f32_16x16x32_bf16 v[76:79], v[176:179], v[222:225], v[76:79]
	v_mfma_f32_16x16x32_bf16 v[32:35], v[160:163], v[222:225], v[32:35]
	v_mfma_f32_16x16x32_bf16 v[32:35], v[156:159], v[218:221], v[32:35]
	v_mfma_f32_16x16x32_bf16 v[36:39], v[132:135], v[218:221], v[36:39]
	v_mfma_f32_16x16x32_bf16 v[36:39], v[148:151], v[222:225], v[36:39]

; #define PG8_STAGE(bufoff, gbase, voff) do { _Pragma("unroll") for (int _i = 0; _i < 2; ++_i) \
;         __builtin_amdgcn_global_load_lds((const unsigned*)((const char*)(gbase) + (voff)[_i]), (LAS unsigned*)(lds + (bufoff) + ldsw + _i * 8192), 16, 0, 0); } while (0)
; #define PG8_LDA(dst, b, h) do { _Pragma("unroll") for (int m = 0; m < 4; ++m) _Pragma("unroll") for (int k = 0; k < 2; ++k) dst[m][k] = *(const LAS bf16x8*)(lds + PG8_SA(b, h) + aoff + m * 2048 + k * 1024); } while (0)
; #define PG8_MMA(ai, bj, At, Bt) do { __builtin_amdgcn_s_setprio(1); _Pragma("unroll") for (int m = 0; m < 4; ++m) _Pragma("unroll") for (int n = 0; n < 2; ++n) _Pragma("unroll") for (int k = 0; k < 2; ++k) \
;         acc[ai][bj][m][n] = __builtin_amdgcn_mfma_f32_16x16x32_bf16(Bt[n][k], At[m][k], acc[ai][bj][m][n], 0, 0, 0); __builtin_amdgcn_s_setprio(0); } while (0)
; #define PG8_WAIT_V(n) asm volatile("s_waitcnt vmcnt(" #n ")" ::: "memory")
; #define PG8_WAIT_L(n) asm volatile("s_waitcnt lgkmcnt(" #n ")" ::: "memory")
; #define PG8_BAR __builtin_amdgcn_s_barrier()
; #define PG8_SCHED __builtin_amdgcn_sched_barrier(0)
; template <class Epi, bool ALIGN_EPI>
; __device__ __forceinline__ void gemm_phase(LAS unsigned char* lds, const Gemm g, const StaticOrder& S, const Epi& E, const int tid) {
;     ...
;             PG8_WAIT_V(8); PG8_WAIT_L(0); PG8_BAR; PG8_MMA(0, 0, At, B0); PG8_MMA(0, 1, At, B1); PG8_BAR; PG8_SCHED;
;             PG8_LDA(At, 0, 1); PG8_STAGE(PG8_SB(0, 0), b2, voffB); PG8_STAGE(PG8_SB(0, 1), b2 + hstepB, voffB); PG8_STAGE(PG8_SA(0, 0), a2, voffA);
	s_barrier
	s_add_i32 s87, s87, s56
	s_mov_b32 m0, s87
	ds_read_b128 v[180:183], v155 offset:16384
	ds_read_b128 v[184:187], v155 offset:17408
	ds_read_b128 v[188:191], v155 offset:18432
	ds_read_b128 v[192:195], v155 offset:19456


; #define PG8_STAGE(bufoff, gbase, voff) do { _Pragma("unroll") for (int _i = 0; _i < 2; ++_i) \
;         __builtin_amdgcn_global_load_lds((const unsigned*)((const char*)(gbase) + (voff)[_i]), (LAS unsigned*)(lds + (bufoff) + ldsw + _i * 8192), 16, 0, 0); } while (0)
; #define PG8_LDA(dst, b, h) do { _Pragma("unroll") for (int m = 0; m < 4; ++m) _Pragma("unroll") for (int k = 0; k < 2; ++k) dst[m][k] = *(const LAS bf16x8*)(lds + PG8_SA(b, h) + aoff + m * 2048 + k * 1024); } while (0)
; #define PG8_MMA(ai, bj, At, Bt) do { __builtin_amdgcn_s_setprio(1); _Pragma("unroll") for (int m = 0; m < 4; ++m) _Pragma("unroll") for (int n = 0; n < 2; ++n) _Pragma("unroll") for (int k = 0; k < 2; ++k) \
;         acc[ai][bj][m][n] = __builtin_amdgcn_mfma_f32_16x16x32_bf16(Bt[n][k], At[m][k], acc[ai][bj][m][n], 0, 0, 0); __builtin_amdgcn_s_setprio(0); } while (0)
; #define PG8_WAIT_V(n) asm volatile("s_waitcnt vmcnt(" #n ")" ::: "memory")
; #define PG8_WAIT_L(n) asm volatile("s_waitcnt lgkmcnt(" #n ")" ::: "memory")
; #define PG8_BAR __builtin_amdgcn_s_barrier()
; #define PG8_SCHED __builtin_amdgcn_sched_barrier(0)
; template <class Epi, bool ALIGN_EPI>
; __device__ __forceinline__ void gemm_phase(LAS unsigned char* lds, const Gemm g, const StaticOrder& S, const Epi& E, const int tid) {
;     ...
;             PG8_LDA(At, 0, 1); PG8_STAGE(PG8_SB(0, 0), b2, voffB); PG8_STAGE(PG8_SB(0, 1), b2 + hstepB, voffB); PG8_STAGE(PG8_SA(0, 0), a2, voffA);
;             PG8_WAIT_V(8); PG8_WAIT_L(0); PG8_BAR; PG8_MMA(1, 0, At, B0); PG8_MMA(1, 1, At, B1); PG8_BAR; PG8_SCHED;
	global_load_lds_dwordx4 v140, s[34:35]
	s_add_i32 m0, s87, 0x2000
	s_add_u32 s88, s34, 0x4000
	s_addc_u32 s89, s35, 0
	s_add_i32 s87, s90, s56
	global_load_lds_dwordx4 v136, s[34:35]
	s_mov_b32 m0, s87
	ds_read_b128 v[222:225], v155 offset:23552
	global_load_lds_dwordx4 v140, s[88:89]
	s_add_i32 m0, s87, 0x2000
	ds_read_b128 v[218:221], v155 offset:22528
	global_load_lds_dwordx4 v136, s[88:89]
	s_mov_b32 m0, s57
	ds_read_b128 v[214:217], v155 offset:21504
	global_load_lds_dwordx4 v142, s[42:43]
	s_mov_b32 m0, s60
	ds_read_b128 v[196:199], v155 offset:20480
	global_load_lds_dwordx4 v138, s[42:43]
	s_waitcnt vmcnt(8)
	s_waitcnt lgkmcnt(0)
	s_barrier


; #define PG8_MMA(ai, bj, At, Bt) do { __builtin_amdgcn_s_setprio(1); _Pragma("unroll") for (int m = 0; m < 4; ++m) _Pragma("unroll") for (int n = 0; n < 2; ++n) _Pragma("unroll") for (int k = 0; k < 2; ++k) \
;         acc[ai][bj][m][n] = __builtin_amdgcn_mfma_f32_16x16x32_bf16(Bt[n][k], At[m][k], acc[ai][bj][m][n], 0, 0, 0); __builtin_amdgcn_s_setprio(0); } while (0)
; #define PG8_WAIT_V(n) asm volatile("s_waitcnt vmcnt(" #n ")" ::: "memory")
; #define PG8_WAIT_L(n) asm volatile("s_waitcnt lgkmcnt(" #n ")" ::: "memory")
; #define PG8_BAR __builtin_amdgcn_s_barrier()
; #define PG8_SCHED __builtin_amdgcn_sched_barrier(0)
; template <class Epi, bool ALIGN_EPI>
; __device__ __forceinline__ void gemm_phase(LAS unsigned char* lds, const Gemm g, const StaticOrder& S, const Epi& E, const int tid) {
;     ...
;             PG8_WAIT_V(8); PG8_WAIT_L(0); PG8_BAR; PG8_MMA(1, 0, At, B0); PG8_MMA(1, 1, At, B1); PG8_BAR; PG8_SCHED;
	v_mfma_f32_16x16x32_bf16 v[24:27], v[132:135], v[180:183], v[24:27]
	v_mfma_f32_16x16x32_bf16 v[24:27], v[148:151], v[184:187], v[24:27]
	v_mfma_f32_16x16x32_bf16 v[20:23], v[160:163], v[184:187], v[20:23]
	v_mfma_f32_16x16x32_bf16 v[20:23], v[156:159], v[180:183], v[20:23]
	v_mfma_f32_16x16x32_bf16 v[124:127], v[172:175], v[180:183], v[124:127]
	v_mfma_f32_16x16x32_bf16 v[124:127], v[176:179], v[184:187], v[124:127]
	v_mfma_f32_16x16x32_bf16 v[128:131], v[168:171], v[184:187], v[128:131]
	v_mfma_f32_16x16x32_bf16 v[128:131], v[164:167], v[180:183], v[128:131]
	v_mfma_f32_16x16x32_bf16 v[120:123], v[164:167], v[188:191], v[120:123]
	v_mfma_f32_16x16x32_bf16 v[120:123], v[168:171], v[192:195], v[120:123]
	v_mfma_f32_16x16x32_bf16 v[116:119], v[176:179], v[192:195], v[116:119]
	v_mfma_f32_16x16x32_bf16 v[116:119], v[172:175], v[188:191], v[116:119]
	v_mfma_f32_16x16x32_bf16 v[72:75], v[156:159], v[188:191], v[72:75]
	v_mfma_f32_16x16x32_bf16 v[72:75], v[160:163], v[192:195], v[72:75]
	v_mfma_f32_16x16x32_bf16 v[64:67], v[148:151], v[192:195], v[64:67]
	v_mfma_f32_16x16x32_bf16 v[64:67], v[132:135], v[188:191], v[64:67]


; #define PG8_MMA(ai, bj, At, Bt) do { __builtin_amdgcn_s_setprio(1); _Pragma("unroll") for (int m = 0; m < 4; ++m) _Pragma("unroll") for (int n = 0; n < 2; ++n) _Pragma("unroll") for (int k = 0; k < 2; ++k) \
;         acc[ai][bj][m][n] = __builtin_amdgcn_mfma_f32_16x16x32_bf16(Bt[n][k], At[m][k], acc[ai][bj][m][n], 0, 0, 0); __builtin_amdgcn_s_setprio(0); } while (0)
; #define PG8_WAIT_V(n) asm volatile("s_waitcnt vmcnt(" #n ")" ::: "memory")
; #define PG8_WAIT_L(n) asm volatile("s_waitcnt lgkmcnt(" #n ")" ::: "memory")
; #define PG8_BAR __builtin_amdgcn_s_barrier()
; #define PG8_SCHED __builtin_amdgcn_sched_barrier(0)
; template <class Epi, bool ALIGN_EPI>
; __device__ __forceinline__ void gemm_phase(LAS unsigned char* lds, const Gemm g, const StaticOrder& S, const Epi& E, const int tid) {
;     ...
;             PG8_WAIT_V(8); PG8_WAIT_L(0); PG8_BAR; PG8_MMA(1, 0, At, B0); PG8_MMA(1, 1, At, B1); PG8_BAR; PG8_SCHED;
	v_mfma_f32_16x16x32_bf16 v[16:19], v[132:135], v[196:199], v[16:19]
	v_mfma_f32_16x16x32_bf16 v[16:19], v[148:151], v[214:217], v[16:19]
	v_mfma_f32_16x16x32_bf16 v[12:15], v[160:163], v[214:217], v[12:15]
	v_mfma_f32_16x16x32_bf16 v[12:15], v[156:159], v[196:199], v[12:15]
	v_mfma_f32_16x16x32_bf16 v[108:111], v[172:175], v[196:199], v[108:111]
	v_mfma_f32_16x16x32_bf16 v[108:111], v[176:179], v[214:217], v[108:111]
	v_mfma_f32_16x16x32_bf16 v[112:115], v[168:171], v[214:217], v[112:115]
	v_mfma_f32_16x16x32_bf16 v[112:115], v[164:167], v[196:199], v[112:115]
	v_mfma_f32_16x16x32_bf16 v[104:107], v[164:167], v[218:221], v[104:107]
	v_mfma_f32_16x16x32_bf16 v[104:107], v[168:171], v[222:225], v[104:107]
	v_mfma_f32_16x16x32_bf16 v[100:103], v[176:179], v[222:225], v[100:103]
	v_mfma_f32_16x16x32_bf16 v[100:103], v[172:175], v[218:221], v[100:103]
	v_mfma_f32_16x16x32_bf16 v[68:71], v[156:159], v[218:221], v[68:71]
	v_mfma_f32_16x16x32_bf16 v[68:71], v[160:163], v[222:225], v[68:71]
	v_mfma_f32_16x16x32_bf16 v[60:63], v[148:151], v[222:225], v[60:63]
	v_mfma_f32_16x16x32_bf16 v[60:63], v[132:135], v[218:221], v[60:63]

; #define PG8_STAGE(bufoff, gbase, voff) do { _Pragma("unroll") for (int _i = 0; _i < 2; ++_i) \
;         __builtin_amdgcn_global_load_lds((const unsigned*)((const char*)(gbase) + (voff)[_i]), (LAS unsigned*)(lds + (bufoff) + ldsw + _i * 8192), 16, 0, 0); } while (0)
; #define PG8_LDA(dst, b, h) do { _Pragma("unroll") for (int m = 0; m < 4; ++m) _Pragma("unroll") for (int k = 0; k < 2; ++k) dst[m][k] = *(const LAS bf16x8*)(lds + PG8_SA(b, h) + aoff + m * 2048 + k * 1024); } while (0)
; #define PG8_LDB(dst, b, h) do { _Pragma("unroll") for (int n = 0; n < 2; ++n) _Pragma("unroll") for (int k = 0; k < 2; ++k) dst[n][k] = *(const LAS bf16x8*)(lds + PG8_SB(b, h) + boff + n * 2048 + k * 1024); } while (0)
; #define PG8_MMA(ai, bj, At, Bt) do { __builtin_amdgcn_s_setprio(1); _Pragma("unroll") for (int m = 0; m < 4; ++m) _Pragma("unroll") for (int n = 0; n < 2; ++n) _Pragma("unroll") for (int k = 0; k < 2; ++k) \
;         acc[ai][bj][m][n] = __builtin_amdgcn_mfma_f32_16x16x32_bf16(Bt[n][k], At[m][k], acc[ai][bj][m][n], 0, 0, 0); __builtin_amdgcn_s_setprio(0); } while (0)
; #define PG8_WAIT_V(n) asm volatile("s_waitcnt vmcnt(" #n ")" ::: "memory")
; #define PG8_WAIT_L(n) asm volatile("s_waitcnt lgkmcnt(" #n ")" ::: "memory")
; #define PG8_BAR __builtin_amdgcn_s_barrier()
; #define PG8_SCHED __builtin_amdgcn_sched_barrier(0)
; template <class Epi, bool ALIGN_EPI>
; __device__ __forceinline__ void gemm_phase(LAS unsigned char* lds, const Gemm g, const StaticOrder& S, const Epi& E, const int tid) {
;     ...
;             PG8_WAIT_V(8); PG8_WAIT_L(0); PG8_BAR; PG8_MMA(1, 0, At, B0); PG8_MMA(1, 1, At, B1); PG8_BAR; PG8_SCHED;
;             PG8_LDB(B0, 1, 0); PG8_LDB(B1, 1, 1); PG8_SCHED; PG8_LDA(At, 1, 0); PG8_STAGE(PG8_SA(0, 1), a2 + hstepA, voffA);
	s_barrier
	s_add_i32 s87, 0, 0x18000

; #define PG8_STAGE(bufoff, gbase, voff) do { _Pragma("unroll") for (int _i = 0; _i < 2; ++_i) \
;         __builtin_amdgcn_global_load_lds((const unsigned*)((const char*)(gbase) + (voff)[_i]), (LAS unsigned*)(lds + (bufoff) + ldsw + _i * 8192), 16, 0, 0); } while (0)
; #define PG8_LDA(dst, b, h) do { _Pragma("unroll") for (int m = 0; m < 4; ++m) _Pragma("unroll") for (int k = 0; k < 2; ++k) dst[m][k] = *(const LAS bf16x8*)(lds + PG8_SA(b, h) + aoff + m * 2048 + k * 1024); } while (0)
; #define PG8_LDB(dst, b, h) do { _Pragma("unroll") for (int n = 0; n < 2; ++n) _Pragma("unroll") for (int k = 0; k < 2; ++k) dst[n][k] = *(const LAS bf16x8*)(lds + PG8_SB(b, h) + boff + n * 2048 + k * 1024); } while (0)
; #define PG8_SCHED __builtin_amdgcn_sched_barrier(0)
; template <class Epi, bool ALIGN_EPI>
; __device__ __forceinline__ void gemm_phase(LAS unsigned char* lds, const Gemm g, const StaticOrder& S, const Epi& E, const int tid) {
;     ...
;             PG8_LDB(B0, 1, 0); PG8_LDB(B1, 1, 1); PG8_SCHED; PG8_LDA(At, 1, 0); PG8_STAGE(PG8_SA(0, 1), a2 + hstepA, voffA);
	s_add_i32 s88, 0, 0x1c000
	ds_read_b128 v[132:135], v243
	ds_read_b128 v[148:151], v243 offset:1024
	ds_read_b128 v[156:159], v243 offset:2048
	ds_read_b128 v[160:163], v243 offset:3072

; #define PG8_STAGE(bufoff, gbase, voff) do { _Pragma("unroll") for (int _i = 0; _i < 2; ++_i) \
;         __builtin_amdgcn_global_load_lds((const unsigned*)((const char*)(gbase) + (voff)[_i]), (LAS unsigned*)(lds + (bufoff) + ldsw + _i * 8192), 16, 0, 0); } while (0)
; #define PG8_LDA(dst, b, h) do { _Pragma("unroll") for (int m = 0; m < 4; ++m) _Pragma("unroll") for (int k = 0; k < 2; ++k) dst[m][k] = *(const LAS bf16x8*)(lds + PG8_SA(b, h) + aoff + m * 2048 + k * 1024); } while (0)
; #define PG8_LDB(dst, b, h) do { _Pragma("unroll") for (int n = 0; n < 2; ++n) _Pragma("unroll") for (int k = 0; k < 2; ++k) dst[n][k] = *(const LAS bf16x8*)(lds + PG8_SB(b, h) + boff + n * 2048 + k * 1024); } while (0)
; #define PG8_SCHED __builtin_amdgcn_sched_barrier(0)
; template <class Epi, bool ALIGN_EPI>
; __device__ __forceinline__ void gemm_phase(LAS unsigned char* lds, const Gemm g, const StaticOrder& S, const Epi& E, const int tid) {
;     ...
;             PG8_LDB(B0, 1, 0); PG8_LDB(B1, 1, 1); PG8_SCHED; PG8_LDA(At, 1, 0); PG8_STAGE(PG8_SA(0, 1), a2 + hstepA, voffA);
	ds_read_b128 v[164:167], v244
	ds_read_b128 v[168:171], v244 offset:1024
	ds_read_b128 v[172:175], v244 offset:2048
	ds_read_b128 v[176:179], v244 offset:3072
	s_add_u32 s42, s42, 0x4000
	s_addc_u32 s43, s43, 0
	s_mov_b32 m0, s61
	ds_read_b128 v[180:183], v155 offset:32768
	ds_read_b128 v[184:187], v155 offset:33792
	ds_read_b128 v[188:191], v155 offset:34816
	ds_read_b128 v[192:195], v155 offset:35840
	ds_read_b128 v[196:199], v155 offset:36864
	ds_read_b128 v[214:217], v155 offset:37888
	ds_read_b128 v[218:221], v155 offset:38912

; #define PG8_STAGE(bufoff, gbase, voff) do { _Pragma("unroll") for (int _i = 0; _i < 2; ++_i) \
;         __builtin_amdgcn_global_load_lds((const unsigned*)((const char*)(gbase) + (voff)[_i]), (LAS unsigned*)(lds + (bufoff) + ldsw + _i * 8192), 16, 0, 0); } while (0)
; #define PG8_LDA(dst, b, h) do { _Pragma("unroll") for (int m = 0; m < 4; ++m) _Pragma("unroll") for (int k = 0; k < 2; ++k) dst[m][k] = *(const LAS bf16x8*)(lds + PG8_SA(b, h) + aoff + m * 2048 + k * 1024); } while (0)
; #define PG8_LDB(dst, b, h) do { _Pragma("unroll") for (int n = 0; n < 2; ++n) _Pragma("unroll") for (int k = 0; k < 2; ++k) dst[n][k] = *(const LAS bf16x8*)(lds + PG8_SB(b, h) + boff + n * 2048 + k * 1024); } while (0)
; #define PG8_MMA(ai, bj, At, Bt) do { __builtin_amdgcn_s_setprio(1); _Pragma("unroll") for (int m = 0; m < 4; ++m) _Pragma("unroll") for (int n = 0; n < 2; ++n) _Pragma("unroll") for (int k = 0; k < 2; ++k) \
;         acc[ai][bj][m][n] = __builtin_amdgcn_mfma_f32_16x16x32_bf16(Bt[n][k], At[m][k], acc[ai][bj][m][n], 0, 0, 0); __builtin_amdgcn_s_setprio(0); } while (0)
; #define PG8_WAIT_V(n) asm volatile("s_waitcnt vmcnt(" #n ")" ::: "memory")
; #define PG8_WAIT_L(n) asm volatile("s_waitcnt lgkmcnt(" #n ")" ::: "memory")
; #define PG8_BAR __builtin_amdgcn_s_barrier()
; #define PG8_SCHED __builtin_amdgcn_sched_barrier(0)
; template <class Epi, bool ALIGN_EPI>
; __device__ __forceinline__ void gemm_phase(LAS unsigned char* lds, const Gemm g, const StaticOrder& S, const Epi& E, const int tid) {
;     ...
;             PG8_LDB(B0, 1, 0); PG8_LDB(B1, 1, 1); PG8_SCHED; PG8_LDA(At, 1, 0); PG8_STAGE(PG8_SA(0, 1), a2 + hstepA, voffA);
;             PG8_WAIT_V(8); PG8_WAIT_L(0); PG8_BAR; PG8_MMA(0, 0, At, B0); PG8_MMA(0, 1, At, B1); PG8_BAR; PG8_SCHED;
	global_load_lds_dwordx4 v142, s[42:43]
	s_mov_b32 m0, s71
	ds_read_b128 v[222:225], v155 offset:39936
	global_load_lds_dwordx4 v138, s[42:43]
	s_waitcnt vmcnt(8)
	s_waitcnt lgkmcnt(0)
	s_barrier


; #define PG8_MMA(ai, bj, At, Bt) do { __builtin_amdgcn_s_setprio(1); _Pragma("unroll") for (int m = 0; m < 4; ++m) _Pragma("unroll") for (int n = 0; n < 2; ++n) _Pragma("unroll") for (int k = 0; k < 2; ++k) \
;         acc[ai][bj][m][n] = __builtin_amdgcn_mfma_f32_16x16x32_bf16(Bt[n][k], At[m][k], acc[ai][bj][m][n], 0, 0, 0); __builtin_amdgcn_s_setprio(0); } while (0)
; #define PG8_WAIT_V(n) asm volatile("s_waitcnt vmcnt(" #n ")" ::: "memory")
; #define PG8_WAIT_L(n) asm volatile("s_waitcnt lgkmcnt(" #n ")" ::: "memory")
; #define PG8_BAR __builtin_amdgcn_s_barrier()
; #define PG8_SCHED __builtin_amdgcn_sched_barrier(0)
; template <class Epi, bool ALIGN_EPI>
; __device__ __forceinline__ void gemm_phase(LAS unsigned char* lds, const Gemm g, const StaticOrder& S, const Epi& E, const int tid) {
;     ...
;             PG8_WAIT_V(8); PG8_WAIT_L(0); PG8_BAR; PG8_MMA(0, 0, At, B0); PG8_MMA(0, 1, At, B1); PG8_BAR; PG8_SCHED;
	v_mfma_f32_16x16x32_bf16 v[6:9], v[132:135], v[180:183], v[8:11]
	v_mfma_f32_16x16x32_bf16 v[8:11], v[148:151], v[184:187], v[6:9]
	v_mfma_f32_16x16x32_bf16 v[56:59], v[160:163], v[184:187], v[56:59]
	v_mfma_f32_16x16x32_bf16 v[56:59], v[156:159], v[180:183], v[56:59]
	v_mfma_f32_16x16x32_bf16 v[28:31], v[172:175], v[180:183], v[28:31]
	v_mfma_f32_16x16x32_bf16 v[28:31], v[176:179], v[184:187], v[28:31]
	v_mfma_f32_16x16x32_bf16 v[2:5], v[164:167], v[180:183], v[2:5]
	v_mfma_f32_16x16x32_bf16 v[4:7], v[168:171], v[184:187], v[2:5]
	v_mfma_f32_16x16x32_bf16 v[96:99], v[168:171], v[192:195], v[96:99]
	v_mfma_f32_16x16x32_bf16 v[96:99], v[164:167], v[188:191], v[96:99]
	v_mfma_f32_16x16x32_bf16 v[92:95], v[172:175], v[188:191], v[92:95]
	v_mfma_f32_16x16x32_bf16 v[92:95], v[176:179], v[192:195], v[92:95]
	v_mfma_f32_16x16x32_bf16 v[48:51], v[160:163], v[192:195], v[48:51]
	v_mfma_f32_16x16x32_bf16 v[48:51], v[156:159], v[188:191], v[48:51]
	v_mfma_f32_16x16x32_bf16 v[52:55], v[132:135], v[188:191], v[52:55]
	v_mfma_f32_16x16x32_bf16 v[52:55], v[148:151], v[192:195], v[52:55]


; #define PG8_MMA(ai, bj, At, Bt) do { __builtin_amdgcn_s_setprio(1); _Pragma("unroll") for (int m = 0; m < 4; ++m) _Pragma("unroll") for (int n = 0; n < 2; ++n) _Pragma("unroll") for (int k = 0; k < 2; ++k) \
;         acc[ai][bj][m][n] = __builtin_amdgcn_mfma_f32_16x16x32_bf16(Bt[n][k], At[m][k], acc[ai][bj][m][n], 0, 0, 0); __builtin_amdgcn_s_setprio(0); } while (0)
; #define PG8_WAIT_V(n) asm volatile("s_waitcnt vmcnt(" #n ")" ::: "memory")
; #define PG8_WAIT_L(n) asm volatile("s_waitcnt lgkmcnt(" #n ")" ::: "memory")
; #define PG8_BAR __builtin_amdgcn_s_barrier()
; #define PG8_SCHED __builtin_amdgcn_sched_barrier(0)
; template <class Epi, bool ALIGN_EPI>
; __device__ __forceinline__ void gemm_phase(LAS unsigned char* lds, const Gemm g, const StaticOrder& S, const Epi& E, const int tid) {
;     ...
;             PG8_WAIT_V(8); PG8_WAIT_L(0); PG8_BAR; PG8_MMA(0, 0, At, B0); PG8_MMA(0, 1, At, B1); PG8_BAR; PG8_SCHED;
	v_mfma_f32_16x16x32_bf16 v[44:47], v[148:151], v[214:217], v[44:47]
	v_mfma_f32_16x16x32_bf16 v[44:47], v[132:135], v[196:199], v[44:47]
	v_mfma_f32_16x16x32_bf16 v[40:43], v[156:159], v[196:199], v[40:43]
	v_mfma_f32_16x16x32_bf16 v[40:43], v[160:163], v[214:217], v[40:43]
	v_mfma_f32_16x16x32_bf16 v[84:87], v[176:179], v[214:217], v[84:87]
	v_mfma_f32_16x16x32_bf16 v[84:87], v[172:175], v[196:199], v[84:87]
	v_mfma_f32_16x16x32_bf16 v[88:91], v[164:167], v[196:199], v[88:91]
	v_mfma_f32_16x16x32_bf16 v[88:91], v[168:171], v[214:217], v[88:91]
	v_mfma_f32_16x16x32_bf16 v[80:83], v[168:171], v[222:225], v[80:83]
	v_mfma_f32_16x16x32_bf16 v[80:83], v[164:167], v[218:221], v[80:83]
	v_mfma_f32_16x16x32_bf16 v[76:79], v[172:175], v[218:221], v[76:79]
	v_mfma_f32_16x16x32_bf16 v[76:79], v[176:179], v[222:225], v[76:79]
	v_mfma_f32_16x16x32_bf16 v[32:35], v[160:163], v[222:225], v[32:35]
	v_mfma_f32_16x16x32_bf16 v[32:35], v[156:159], v[218:221], v[32:35]
	v_mfma_f32_16x16x32_bf16 v[36:39], v[132:135], v[218:221], v[36:39]
	v_mfma_f32_16x16x32_bf16 v[36:39], v[148:151], v[222:225], v[36:39]

; #define PG8_STAGE(bufoff, gbase, voff) do { _Pragma("unroll") for (int _i = 0; _i < 2; ++_i) \
;         __builtin_amdgcn_global_load_lds((const unsigned*)((const char*)(gbase) + (voff)[_i]), (LAS unsigned*)(lds + (bufoff) + ldsw + _i * 8192), 16, 0, 0); } while (0)
; #define PG8_LDA(dst, b, h) do { _Pragma("unroll") for (int m = 0; m < 4; ++m) _Pragma("unroll") for (int k = 0; k < 2; ++k) dst[m][k] = *(const LAS bf16x8*)(lds + PG8_SA(b, h) + aoff + m * 2048 + k * 1024); } while (0)
; #define PG8_MMA(ai, bj, At, Bt) do { __builtin_amdgcn_s_setprio(1); _Pragma("unroll") for (int m = 0; m < 4; ++m) _Pragma("unroll") for (int n = 0; n < 2; ++n) _Pragma("unroll") for (int k = 0; k < 2; ++k) \
;         acc[ai][bj][m][n] = __builtin_amdgcn_mfma_f32_16x16x32_bf16(Bt[n][k], At[m][k], acc[ai][bj][m][n], 0, 0, 0); __builtin_amdgcn_s_setprio(0); } while (0)
; #define PG8_WAIT_V(n) asm volatile("s_waitcnt vmcnt(" #n ")" ::: "memory")
; #define PG8_WAIT_L(n) asm volatile("s_waitcnt lgkmcnt(" #n ")" ::: "memory")
; #define PG8_BAR __builtin_amdgcn_s_barrier()
; #define PG8_SCHED __builtin_amdgcn_sched_barrier(0)
; template <class Epi, bool ALIGN_EPI>
; __device__ __forceinline__ void gemm_phase(LAS unsigned char* lds, const Gemm g, const StaticOrder& S, const Epi& E, const int tid) {
;     ...
;             PG8_WAIT_V(8); PG8_WAIT_L(0); PG8_BAR; PG8_MMA(0, 0, At, B0); PG8_MMA(0, 1, At, B1); PG8_BAR; PG8_SCHED;
;             PG8_LDA(At, 1, 1); PG8_STAGE(PG8_SB(1, 0), b3, voffB); PG8_STAGE(PG8_SB(1, 1), b3 + hstepB, voffB); PG8_STAGE(PG8_SA(1, 0), a3, voffA);
	s_barrier
	s_add_u32 s42, s34, 0x8000
	s_addc_u32 s43, s35, 0
	s_add_i32 s87, s87, s56
	s_mov_b32 m0, s87
	ds_read_b128 v[180:183], v155 offset:49152
	ds_read_b128 v[184:187], v155 offset:50176
	ds_read_b128 v[188:191], v155 offset:51200
	ds_read_b128 v[192:195], v155 offset:52224


; #define PG8_STAGE(bufoff, gbase, voff) do { _Pragma("unroll") for (int _i = 0; _i < 2; ++_i) \
;         __builtin_amdgcn_global_load_lds((const unsigned*)((const char*)(gbase) + (voff)[_i]), (LAS unsigned*)(lds + (bufoff) + ldsw + _i * 8192), 16, 0, 0); } while (0)
; #define PG8_LDA(dst, b, h) do { _Pragma("unroll") for (int m = 0; m < 4; ++m) _Pragma("unroll") for (int k = 0; k < 2; ++k) dst[m][k] = *(const LAS bf16x8*)(lds + PG8_SA(b, h) + aoff + m * 2048 + k * 1024); } while (0)
; #define PG8_MMA(ai, bj, At, Bt) do { __builtin_amdgcn_s_setprio(1); _Pragma("unroll") for (int m = 0; m < 4; ++m) _Pragma("unroll") for (int n = 0; n < 2; ++n) _Pragma("unroll") for (int k = 0; k < 2; ++k) \
;         acc[ai][bj][m][n] = __builtin_amdgcn_mfma_f32_16x16x32_bf16(Bt[n][k], At[m][k], acc[ai][bj][m][n], 0, 0, 0); __builtin_amdgcn_s_setprio(0); } while (0)
; #define PG8_WAIT_V(n) asm volatile("s_waitcnt vmcnt(" #n ")" ::: "memory")
; #define PG8_WAIT_L(n) asm volatile("s_waitcnt lgkmcnt(" #n ")" ::: "memory")
; #define PG8_BAR __builtin_amdgcn_s_barrier()
; #define PG8_SCHED __builtin_amdgcn_sched_barrier(0)
; template <class Epi, bool ALIGN_EPI>
; __device__ __forceinline__ void gemm_phase(LAS unsigned char* lds, const Gemm g, const StaticOrder& S, const Epi& E, const int tid) {
;     ...
;             PG8_LDA(At, 1, 1); PG8_STAGE(PG8_SB(1, 0), b3, voffB); PG8_STAGE(PG8_SB(1, 1), b3 + hstepB, voffB); PG8_STAGE(PG8_SA(1, 0), a3, voffA);
;             PG8_WAIT_V(8); PG8_WAIT_L(0); PG8_BAR; PG8_MMA(1, 0, At, B0); PG8_MMA(1, 1, At, B1); PG8_BAR; PG8_SCHED;
	global_load_lds_dwordx4 v140, s[42:43]
	s_add_i32 m0, s87, 0x2000
	s_add_u32 s34, s34, 0xc000
	s_addc_u32 s35, s35, 0
	global_load_lds_dwordx4 v136, s[42:43]
	s_add_i32 s42, s88, s56
	s_mov_b32 m0, s42
	ds_read_b128 v[222:225], v155 offset:56320
	global_load_lds_dwordx4 v140, s[34:35]
	s_add_i32 m0, s42, 0x2000
	ds_read_b128 v[218:221], v155 offset:55296
	global_load_lds_dwordx4 v136, s[34:35]
	s_mov_b32 m0, s76
	ds_read_b128 v[214:217], v155 offset:54272
	global_load_lds_dwordx4 v142, s[22:23]
	s_mov_b32 m0, s77
	ds_read_b128 v[196:199], v155 offset:53248
	global_load_lds_dwordx4 v138, s[22:23]
	s_waitcnt vmcnt(8)
	s_waitcnt lgkmcnt(0)
	s_barrier


; #define PG8_MMA(ai, bj, At, Bt) do { __builtin_amdgcn_s_setprio(1); _Pragma("unroll") for (int m = 0; m < 4; ++m) _Pragma("unroll") for (int n = 0; n < 2; ++n) _Pragma("unroll") for (int k = 0; k < 2; ++k) \
;         acc[ai][bj][m][n] = __builtin_amdgcn_mfma_f32_16x16x32_bf16(Bt[n][k], At[m][k], acc[ai][bj][m][n], 0, 0, 0); __builtin_amdgcn_s_setprio(0); } while (0)
; #define PG8_WAIT_V(n) asm volatile("s_waitcnt vmcnt(" #n ")" ::: "memory")
; #define PG8_WAIT_L(n) asm volatile("s_waitcnt lgkmcnt(" #n ")" ::: "memory")
; #define PG8_BAR __builtin_amdgcn_s_barrier()
; #define PG8_SCHED __builtin_amdgcn_sched_barrier(0)
; template <class Epi, bool ALIGN_EPI>
; __device__ __forceinline__ void gemm_phase(LAS unsigned char* lds, const Gemm g, const StaticOrder& S, const Epi& E, const int tid) {
;     ...
;             PG8_WAIT_V(8); PG8_WAIT_L(0); PG8_BAR; PG8_MMA(1, 0, At, B0); PG8_MMA(1, 1, At, B1); PG8_BAR; PG8_SCHED;
	v_mfma_f32_16x16x32_bf16 v[24:27], v[132:135], v[180:183], v[24:27]
	v_mfma_f32_16x16x32_bf16 v[24:27], v[148:151], v[184:187], v[24:27]
	v_mfma_f32_16x16x32_bf16 v[20:23], v[160:163], v[184:187], v[20:23]
	v_mfma_f32_16x16x32_bf16 v[20:23], v[156:159], v[180:183], v[20:23]
	v_mfma_f32_16x16x32_bf16 v[124:127], v[172:175], v[180:183], v[124:127]
	v_mfma_f32_16x16x32_bf16 v[124:127], v[176:179], v[184:187], v[124:127]
	v_mfma_f32_16x16x32_bf16 v[128:131], v[168:171], v[184:187], v[128:131]
	v_mfma_f32_16x16x32_bf16 v[128:131], v[164:167], v[180:183], v[128:131]
	v_mfma_f32_16x16x32_bf16 v[120:123], v[164:167], v[188:191], v[120:123]
	v_mfma_f32_16x16x32_bf16 v[120:123], v[168:171], v[192:195], v[120:123]
	v_mfma_f32_16x16x32_bf16 v[116:119], v[176:179], v[192:195], v[116:119]
	v_mfma_f32_16x16x32_bf16 v[116:119], v[172:175], v[188:191], v[116:119]
	v_mfma_f32_16x16x32_bf16 v[72:75], v[156:159], v[188:191], v[72:75]
	v_mfma_f32_16x16x32_bf16 v[72:75], v[160:163], v[192:195], v[72:75]
	v_mfma_f32_16x16x32_bf16 v[64:67], v[148:151], v[192:195], v[64:67]
	v_mfma_f32_16x16x32_bf16 v[64:67], v[132:135], v[188:191], v[64:67]


; #define PG8_MMA(ai, bj, At, Bt) do { __builtin_amdgcn_s_setprio(1); _Pragma("unroll") for (int m = 0; m < 4; ++m) _Pragma("unroll") for (int n = 0; n < 2; ++n) _Pragma("unroll") for (int k = 0; k < 2; ++k) \
;         acc[ai][bj][m][n] = __builtin_amdgcn_mfma_f32_16x16x32_bf16(Bt[n][k], At[m][k], acc[ai][bj][m][n], 0, 0, 0); __builtin_amdgcn_s_setprio(0); } while (0)
; #define PG8_WAIT_V(n) asm volatile("s_waitcnt vmcnt(" #n ")" ::: "memory")
; #define PG8_WAIT_L(n) asm volatile("s_waitcnt lgkmcnt(" #n ")" ::: "memory")
; #define PG8_BAR __builtin_amdgcn_s_barrier()
; #define PG8_SCHED __builtin_amdgcn_sched_barrier(0)
; template <class Epi, bool ALIGN_EPI>
; __device__ __forceinline__ void gemm_phase(LAS unsigned char* lds, const Gemm g, const StaticOrder& S, const Epi& E, const int tid) {
;     ...
;             PG8_WAIT_V(8); PG8_WAIT_L(0); PG8_BAR; PG8_MMA(1, 0, At, B0); PG8_MMA(1, 1, At, B1); PG8_BAR; PG8_SCHED;
	v_mfma_f32_16x16x32_bf16 v[16:19], v[132:135], v[196:199], v[16:19]
	v_mfma_f32_16x16x32_bf16 v[16:19], v[148:151], v[214:217], v[16:19]
	v_mfma_f32_16x16x32_bf16 v[12:15], v[160:163], v[214:217], v[12:15]
	v_mfma_f32_16x16x32_bf16 v[12:15], v[156:159], v[196:199], v[12:15]
	v_mfma_f32_16x16x32_bf16 v[108:111], v[172:175], v[196:199], v[108:111]
	v_mfma_f32_16x16x32_bf16 v[108:111], v[176:179], v[214:217], v[108:111]
	v_mfma_f32_16x16x32_bf16 v[112:115], v[168:171], v[214:217], v[112:115]
	v_mfma_f32_16x16x32_bf16 v[112:115], v[164:167], v[196:199], v[112:115]
	v_mfma_f32_16x16x32_bf16 v[104:107], v[164:167], v[218:221], v[104:107]
	v_mfma_f32_16x16x32_bf16 v[104:107], v[168:171], v[222:225], v[104:107]
	v_mfma_f32_16x16x32_bf16 v[100:103], v[176:179], v[222:225], v[100:103]
	v_mfma_f32_16x16x32_bf16 v[100:103], v[172:175], v[218:221], v[100:103]
	v_mfma_f32_16x16x32_bf16 v[68:71], v[156:159], v[218:221], v[68:71]
	v_mfma_f32_16x16x32_bf16 v[68:71], v[160:163], v[222:225], v[68:71]
	v_mfma_f32_16x16x32_bf16 v[60:63], v[148:151], v[222:225], v[60:63]
	v_mfma_f32_16x16x32_bf16 v[60:63], v[132:135], v[218:221], v[60:63]

; template <class Epi, bool ALIGN_EPI>
; __device__ __forceinline__ void gemm_phase(LAS unsigned char* lds, const Gemm g, const StaticOrder& S, const Epi& E, const int tid) {
;     ...
;         for (int t = 0; t < nt; t += 2) {
;             const bool last = (t == nt - 2);
;             const char* a1 = cA + (size_t)(t + 1) * kstepA;
;             const char* a2 = last ? nA : cA + (size_t)(t + 2) * kstepA; const char* b2 = last ? nB : cB + (size_t)(t + 2) * kstepB;
;             const char* a3 = a2 + kstepA; const char* b3 = b2 + kstepB;
;             PG8_LDB(B0, 0, 0); PG8_LDB(B1, 0, 1); PG8_SCHED; PG8_LDA(At, 0, 0); PG8_STAGE(PG8_SA(1, 1), a1 + hstepA, voffA);
;             PG8_WAIT_V(8); PG8_WAIT_L(0); PG8_BAR; PG8_MMA(0, 0, At, B0); PG8_MMA(0, 1, At, B1); PG8_BAR; PG8_SCHED;
;             PG8_LDA(At, 0, 1); PG8_STAGE(PG8_SB(0, 0), b2, voffB); PG8_STAGE(PG8_SB(0, 1), b2 + hstepB, voffB); PG8_STAGE(PG8_SA(0, 0), a2, voffA);
;             PG8_WAIT_V(8); PG8_WAIT_L(0); PG8_BAR; PG8_MMA(1, 0, At, B0); PG8_MMA(1, 1, At, B1); PG8_BAR; PG8_SCHED;
;             PG8_LDB(B0, 1, 0); PG8_LDB(B1, 1, 1); PG8_SCHED; PG8_LDA(At, 1, 0); PG8_STAGE(PG8_SA(0, 1), a2 + hstepA, voffA);
;             PG8_WAIT_V(8); PG8_WAIT_L(0); PG8_BAR; PG8_MMA(0, 0, At, B0); PG8_MMA(0, 1, At, B1); PG8_BAR; PG8_SCHED;
;             PG8_LDA(At, 1, 1); PG8_STAGE(PG8_SB(1, 0), b3, voffB); PG8_STAGE(PG8_SB(1, 1), b3 + hstepB, voffB); PG8_STAGE(PG8_SA(1, 0), a3, voffA);
;             PG8_WAIT_V(8); PG8_WAIT_L(0); PG8_BAR; PG8_MMA(1, 0, At, B0); PG8_MMA(1, 1, At, B1); PG8_BAR; PG8_SCHED;
;         }
;         if constexpr (ALIGN_EPI) { if (wr == 0) PG8_BAR; }
;     __device__ __forceinline__ void operator()(f32x4 (&acc)[2][2][4][2], const Unit& u, int wr, int wc, LAS unsigned char* lds, int& rs_pm) const {
;         int fr, fq; epi_lane(fr, fq);
;         const int row0 = u.pm * BM + wr * 64 + fr, col0 = u.pn * BM + wc * 32 + 8 * fq; u32x4 zb = zero_frag();
; #pragma unroll
;         for (int ai = 0; ai < 2; ++ai)
; #pragma unroll
;             for (int m = 0; m < 4; ++m) { float ss = 0.f;
;                 bf16* const xrow = xb + (((size_t)(u.pm * 32 + u.pn * 4 + (wc >> 1)) * BM + (wr * 64 + fr + ai * HALF + m * 16)) * 64 + (wc & 1) * 32 + 8 * fq);
; #pragma unroll
;                 for (int bj = 0; bj < 2; ++bj) {
;                     const u32x4 xw = *(const u32x4*)(xrow + (size_t)bj * (2 * BM * 64));
	s_barrier
	s_add_i32 s86, s86, 2
	s_add_u32 s84, s84, 0x10000
	s_addc_u32 s85, s85, 0
	s_add_u32 s10, s10, 0x10000
	s_addc_u32 s11, s11, 0
	s_cmpk_gt_u32 s86, 0x55
	s_cbranch_scc0 .LBB0_294
	v_and_b32_e32 v222, 15, v238
	v_lshrrev_b32_e32 v156, 4, v238
	s_lshl_b32 s100, s82, 5
	s_lshl_b32 s101, s83, 2
	v_lshlrev_b32_e32 v222, 7, v222
	s_add_i32 s100, s100, s101
	s_or_b32 s100, s100, s78
	v_lshl_or_b32 v222, v156, 4, v222
	s_ashr_i32 s101, s100, 31
	s_lshl_b64 s[100:101], s[100:101], 15
	s_add_u32 s98, s72, s100
	s_addc_u32 s99, s73, s101
	s_add_u32 s98, s98, s30
	s_addc_u32 s99, s99, s31
	s_lshl_b32 s100, s75, 7
	s_add_u32 s98, s98, s100
	s_addc_u32 s99, s99, 0
	s_lshl_b32 s100, s82, 15
	s_lshl_b32 s101, s75, 7
	s_add_i32 s100, s100, s101
	s_lshl_b32 s101, s83, 4
	s_add_i32 s100, s100, s101
	s_lshl_b32 s101, s74, 2
	s_add_i32 s100, s100, s101
	s_add_u32 s22, s44, s100
	s_addc_u32 s23, s45, 0
	global_load_dwordx4 v[176:179], v222, s[98:99]
	s_add_u32 s100, s98, 0x10000
	s_addc_u32 s101, s99, 0
	global_load_dwordx4 v[180:183], v222, s[100:101]
	global_load_dwordx4 v[184:187], v222, s[98:99] offset:2048
	s_add_u32 s100, s98, 0x10000
	s_addc_u32 s101, s99, 0
	global_load_dwordx4 v[188:191], v222, s[100:101] offset:2048
	s_add_u32 s100, s98, 0x1000
	s_addc_u32 s101, s99, 0
	global_load_dwordx4 v[192:195], v222, s[100:101]
	s_add_u32 s100, s98, 0x11000
	s_addc_u32 s101, s99, 0
	global_load_dwordx4 v[196:199], v222, s[100:101]
	s_add_u32 s100, s98, 0x1000
	s_addc_u32 s101, s99, 0
	global_load_dwordx4 v[214:217], v222, s[100:101] offset:2048
	s_add_u32 s100, s98, 0x11000
	s_addc_u32 s101, s99, 0
	global_load_dwordx4 v[218:221], v222, s[100:101] offset:2048
	s_and_b64 vcc, exec, s[46:47]
	s_cbranch_vccz .LBB0_297
	s_barrier

; #define PG8_STAGE(bufoff, gbase, voff) do { _Pragma("unroll") for (int _i = 0; _i < 2; ++_i) \
;         __builtin_amdgcn_global_load_lds((const unsigned*)((const char*)(gbase) + (voff)[_i]), (LAS unsigned*)(lds + (bufoff) + ldsw + _i * 8192), 16, 0, 0); } while (0)
; #define PG8_LDA(dst, b, h) do { _Pragma("unroll") for (int m = 0; m < 4; ++m) _Pragma("unroll") for (int k = 0; k < 2; ++k) dst[m][k] = *(const LAS bf16x8*)(lds + PG8_SA(b, h) + aoff + m * 2048 + k * 1024); } while (0)
; #define PG8_LDB(dst, b, h) do { _Pragma("unroll") for (int n = 0; n < 2; ++n) _Pragma("unroll") for (int k = 0; k < 2; ++k) dst[n][k] = *(const LAS bf16x8*)(lds + PG8_SB(b, h) + boff + n * 2048 + k * 1024); } while (0)
; #define PG8_SCHED __builtin_amdgcn_sched_barrier(0)
; template <class Epi, bool ALIGN_EPI>
; __device__ __forceinline__ void gemm_phase(LAS unsigned char* lds, const Gemm g, const StaticOrder& S, const Epi& E, const int tid) {
;     ...
;             const bool last = (t == nt - 2);
;             const char* a1 = cA + (size_t)(t + 1) * kstepA;
;             const char* a2 = last ? nA : cA + (size_t)(t + 2) * kstepA; const char* b2 = last ? nB : cB + (size_t)(t + 2) * kstepB;
;             const char* a3 = a2 + kstepA; const char* b3 = b2 + kstepB;
;             PG8_LDB(B0, 0, 0); PG8_LDB(B1, 0, 1); PG8_SCHED; PG8_LDA(At, 0, 0); PG8_STAGE(PG8_SA(1, 1), a1 + hstepA, voffA);
.LBB0_385:
	s_add_u32 s50, s48, 0x4000
	s_addc_u32 s51, s49, 0
	s_cmp_eq_u32 s88, 28
	s_cselect_b32 s54, s84, s50
	s_cselect_b32 s55, s43, s51
	s_cselect_b32 s52, s85, s86
	s_cselect_b32 s53, s41, s87
	s_add_u32 s50, s54, 0x8000
	s_addc_u32 s51, s55, 0
	s_add_i32 s89, 0, 0x10000

; #define PG8_STAGE(bufoff, gbase, voff) do { _Pragma("unroll") for (int _i = 0; _i < 2; ++_i) \
;         __builtin_amdgcn_global_load_lds((const unsigned*)((const char*)(gbase) + (voff)[_i]), (LAS unsigned*)(lds + (bufoff) + ldsw + _i * 8192), 16, 0, 0); } while (0)
; #define PG8_LDA(dst, b, h) do { _Pragma("unroll") for (int m = 0; m < 4; ++m) _Pragma("unroll") for (int k = 0; k < 2; ++k) dst[m][k] = *(const LAS bf16x8*)(lds + PG8_SA(b, h) + aoff + m * 2048 + k * 1024); } while (0)
; #define PG8_LDB(dst, b, h) do { _Pragma("unroll") for (int n = 0; n < 2; ++n) _Pragma("unroll") for (int k = 0; k < 2; ++k) dst[n][k] = *(const LAS bf16x8*)(lds + PG8_SB(b, h) + boff + n * 2048 + k * 1024); } while (0)
; #define PG8_SCHED __builtin_amdgcn_sched_barrier(0)
; template <class Epi, bool ALIGN_EPI>
; __device__ __forceinline__ void gemm_phase(LAS unsigned char* lds, const Gemm g, const StaticOrder& S, const Epi& E, const int tid) {
;     ...
;             PG8_LDB(B0, 0, 0); PG8_LDB(B1, 0, 1); PG8_SCHED; PG8_LDA(At, 0, 0); PG8_STAGE(PG8_SA(1, 1), a1 + hstepA, voffA);
	s_add_i32 s92, 0, 0x14000
	ds_read_b128 v[132:135], v241
	ds_read_b128 v[136:139], v241 offset:1024
	ds_read_b128 v[152:155], v241 offset:2048
	ds_read_b128 v[156:159], v241 offset:3072

; #define PG8_STAGE(bufoff, gbase, voff) do { _Pragma("unroll") for (int _i = 0; _i < 2; ++_i) \
;         __builtin_amdgcn_global_load_lds((const unsigned*)((const char*)(gbase) + (voff)[_i]), (LAS unsigned*)(lds + (bufoff) + ldsw + _i * 8192), 16, 0, 0); } while (0)
; #define PG8_LDA(dst, b, h) do { _Pragma("unroll") for (int m = 0; m < 4; ++m) _Pragma("unroll") for (int k = 0; k < 2; ++k) dst[m][k] = *(const LAS bf16x8*)(lds + PG8_SA(b, h) + aoff + m * 2048 + k * 1024); } while (0)
; #define PG8_LDB(dst, b, h) do { _Pragma("unroll") for (int n = 0; n < 2; ++n) _Pragma("unroll") for (int k = 0; k < 2; ++k) dst[n][k] = *(const LAS bf16x8*)(lds + PG8_SB(b, h) + boff + n * 2048 + k * 1024); } while (0)
; #define PG8_SCHED __builtin_amdgcn_sched_barrier(0)
; template <class Epi, bool ALIGN_EPI>
; __device__ __forceinline__ void gemm_phase(LAS unsigned char* lds, const Gemm g, const StaticOrder& S, const Epi& E, const int tid) {
;     ...
;             PG8_LDB(B0, 0, 0); PG8_LDB(B1, 0, 1); PG8_SCHED; PG8_LDA(At, 0, 0); PG8_STAGE(PG8_SA(1, 1), a1 + hstepA, voffA);
	ds_read_b128 v[160:163], v242
	ds_read_b128 v[172:175], v242 offset:1024
	ds_read_b128 v[176:179], v242 offset:2048
	ds_read_b128 v[180:183], v242 offset:3072
	s_add_i32 m0, s71, 0xc000
	ds_read_b128 v[184:187], v171
	ds_read_b128 v[188:191], v171 offset:1024
	ds_read_b128 v[192:195], v171 offset:2048
	ds_read_b128 v[196:199], v171 offset:3072
	ds_read_b128 v[214:217], v171 offset:4096
	ds_read_b128 v[218:221], v171 offset:5120
	ds_read_b128 v[222:225], v171 offset:6144

; #define PG8_STAGE(bufoff, gbase, voff) do { _Pragma("unroll") for (int _i = 0; _i < 2; ++_i) \
;         __builtin_amdgcn_global_load_lds((const unsigned*)((const char*)(gbase) + (voff)[_i]), (LAS unsigned*)(lds + (bufoff) + ldsw + _i * 8192), 16, 0, 0); } while (0)
; #define PG8_LDA(dst, b, h) do { _Pragma("unroll") for (int m = 0; m < 4; ++m) _Pragma("unroll") for (int k = 0; k < 2; ++k) dst[m][k] = *(const LAS bf16x8*)(lds + PG8_SA(b, h) + aoff + m * 2048 + k * 1024); } while (0)
; #define PG8_LDB(dst, b, h) do { _Pragma("unroll") for (int n = 0; n < 2; ++n) _Pragma("unroll") for (int k = 0; k < 2; ++k) dst[n][k] = *(const LAS bf16x8*)(lds + PG8_SB(b, h) + boff + n * 2048 + k * 1024); } while (0)
; #define PG8_MMA(ai, bj, At, Bt) do { __builtin_amdgcn_s_setprio(1); _Pragma("unroll") for (int m = 0; m < 4; ++m) _Pragma("unroll") for (int n = 0; n < 2; ++n) _Pragma("unroll") for (int k = 0; k < 2; ++k) \
;         acc[ai][bj][m][n] = __builtin_amdgcn_mfma_f32_16x16x32_bf16(Bt[n][k], At[m][k], acc[ai][bj][m][n], 0, 0, 0); __builtin_amdgcn_s_setprio(0); } while (0)
; #define PG8_WAIT_V(n) asm volatile("s_waitcnt vmcnt(" #n ")" ::: "memory")
; #define PG8_WAIT_L(n) asm volatile("s_waitcnt lgkmcnt(" #n ")" ::: "memory")
; #define PG8_BAR __builtin_amdgcn_s_barrier()
; #define PG8_SCHED __builtin_amdgcn_sched_barrier(0)
; template <class Epi, bool ALIGN_EPI>
; __device__ __forceinline__ void gemm_phase(LAS unsigned char* lds, const Gemm g, const StaticOrder& S, const Epi& E, const int tid) {
;     ...
;             PG8_LDB(B0, 0, 0); PG8_LDB(B1, 0, 1); PG8_SCHED; PG8_LDA(At, 0, 0); PG8_STAGE(PG8_SA(1, 1), a1 + hstepA, voffA);
;             PG8_WAIT_V(8); PG8_WAIT_L(0); PG8_BAR; PG8_MMA(0, 0, At, B0); PG8_MMA(0, 1, At, B1); PG8_BAR; PG8_SCHED;
	global_load_lds_dwordx4 v148, s[48:49]
	s_add_i32 m0, s71, 0xe000
	ds_read_b128 v[226:229], v171 offset:7168
	global_load_lds_dwordx4 v150, s[48:49]
	s_waitcnt vmcnt(8)
	s_waitcnt lgkmcnt(0)
	s_barrier


; #define PG8_MMA(ai, bj, At, Bt) do { __builtin_amdgcn_s_setprio(1); _Pragma("unroll") for (int m = 0; m < 4; ++m) _Pragma("unroll") for (int n = 0; n < 2; ++n) _Pragma("unroll") for (int k = 0; k < 2; ++k) \
;         acc[ai][bj][m][n] = __builtin_amdgcn_mfma_f32_16x16x32_bf16(Bt[n][k], At[m][k], acc[ai][bj][m][n], 0, 0, 0); __builtin_amdgcn_s_setprio(0); } while (0)
; #define PG8_WAIT_V(n) asm volatile("s_waitcnt vmcnt(" #n ")" ::: "memory")
; #define PG8_WAIT_L(n) asm volatile("s_waitcnt lgkmcnt(" #n ")" ::: "memory")
; #define PG8_BAR __builtin_amdgcn_s_barrier()
; #define PG8_SCHED __builtin_amdgcn_sched_barrier(0)
; template <class Epi, bool ALIGN_EPI>
; __device__ __forceinline__ void gemm_phase(LAS unsigned char* lds, const Gemm g, const StaticOrder& S, const Epi& E, const int tid) {
;     ...
;             PG8_WAIT_V(8); PG8_WAIT_L(0); PG8_BAR; PG8_MMA(0, 0, At, B0); PG8_MMA(0, 1, At, B1); PG8_BAR; PG8_SCHED;
	v_mfma_f32_16x16x32_bf16 v[128:131], v[132:135], v[184:187], v[128:131]
	v_mfma_f32_16x16x32_bf16 v[128:131], v[136:139], v[188:191], v[128:131]
	v_mfma_f32_16x16x32_bf16 v[116:119], v[156:159], v[188:191], v[116:119]
	v_mfma_f32_16x16x32_bf16 v[116:119], v[152:155], v[184:187], v[116:119]
	v_mfma_f32_16x16x32_bf16 v[80:83], v[176:179], v[184:187], v[80:83]
	v_mfma_f32_16x16x32_bf16 v[80:83], v[180:183], v[188:191], v[80:83]
	v_mfma_f32_16x16x32_bf16 v[104:107], v[172:175], v[188:191], v[104:107]
	v_mfma_f32_16x16x32_bf16 v[104:107], v[160:163], v[184:187], v[104:107]
	v_mfma_f32_16x16x32_bf16 v[96:99], v[160:163], v[192:195], v[96:99]
	v_mfma_f32_16x16x32_bf16 v[96:99], v[172:175], v[196:199], v[96:99]
	v_mfma_f32_16x16x32_bf16 v[68:71], v[180:183], v[196:199], v[68:71]
	v_mfma_f32_16x16x32_bf16 v[68:71], v[176:179], v[192:195], v[68:71]
	v_mfma_f32_16x16x32_bf16 v[108:111], v[152:155], v[192:195], v[108:111]
	v_mfma_f32_16x16x32_bf16 v[108:111], v[156:159], v[196:199], v[108:111]
	v_mfma_f32_16x16x32_bf16 v[124:127], v[136:139], v[196:199], v[124:127]
	v_mfma_f32_16x16x32_bf16 v[124:127], v[132:135], v[192:195], v[124:127]


; #define PG8_MMA(ai, bj, At, Bt) do { __builtin_amdgcn_s_setprio(1); _Pragma("unroll") for (int m = 0; m < 4; ++m) _Pragma("unroll") for (int n = 0; n < 2; ++n) _Pragma("unroll") for (int k = 0; k < 2; ++k) \
;         acc[ai][bj][m][n] = __builtin_amdgcn_mfma_f32_16x16x32_bf16(Bt[n][k], At[m][k], acc[ai][bj][m][n], 0, 0, 0); __builtin_amdgcn_s_setprio(0); } while (0)
; #define PG8_WAIT_V(n) asm volatile("s_waitcnt vmcnt(" #n ")" ::: "memory")
; #define PG8_WAIT_L(n) asm volatile("s_waitcnt lgkmcnt(" #n ")" ::: "memory")
; #define PG8_BAR __builtin_amdgcn_s_barrier()
; #define PG8_SCHED __builtin_amdgcn_sched_barrier(0)
; template <class Epi, bool ALIGN_EPI>
; __device__ __forceinline__ void gemm_phase(LAS unsigned char* lds, const Gemm g, const StaticOrder& S, const Epi& E, const int tid) {
;     ...
;             PG8_WAIT_V(8); PG8_WAIT_L(0); PG8_BAR; PG8_MMA(0, 0, At, B0); PG8_MMA(0, 1, At, B1); PG8_BAR; PG8_SCHED;
	v_mfma_f32_16x16x32_bf16 v[120:123], v[132:135], v[214:217], v[120:123]
	v_mfma_f32_16x16x32_bf16 v[120:123], v[136:139], v[218:221], v[120:123]
	v_mfma_f32_16x16x32_bf16 v[100:103], v[156:159], v[218:221], v[100:103]
	v_mfma_f32_16x16x32_bf16 v[100:103], v[152:155], v[214:217], v[100:103]
	v_mfma_f32_16x16x32_bf16 v[60:63], v[176:179], v[214:217], v[60:63]
	v_mfma_f32_16x16x32_bf16 v[60:63], v[180:183], v[218:221], v[60:63]
	v_mfma_f32_16x16x32_bf16 v[88:91], v[172:175], v[218:221], v[88:91]
	v_mfma_f32_16x16x32_bf16 v[88:91], v[160:163], v[214:217], v[88:91]
	v_mfma_f32_16x16x32_bf16 v[76:79], v[160:163], v[222:225], v[76:79]
	v_mfma_f32_16x16x32_bf16 v[76:79], v[172:175], v[226:229], v[76:79]
	v_mfma_f32_16x16x32_bf16 v[48:51], v[180:183], v[226:229], v[48:51]
	v_mfma_f32_16x16x32_bf16 v[48:51], v[176:179], v[222:225], v[48:51]
	v_mfma_f32_16x16x32_bf16 v[92:95], v[152:155], v[222:225], v[92:95]
	v_mfma_f32_16x16x32_bf16 v[92:95], v[156:159], v[226:229], v[92:95]
	v_mfma_f32_16x16x32_bf16 v[112:115], v[136:139], v[226:229], v[112:115]
	v_mfma_f32_16x16x32_bf16 v[112:115], v[132:135], v[222:225], v[112:115]

; #define PG8_STAGE(bufoff, gbase, voff) do { _Pragma("unroll") for (int _i = 0; _i < 2; ++_i) \
;         __builtin_amdgcn_global_load_lds((const unsigned*)((const char*)(gbase) + (voff)[_i]), (LAS unsigned*)(lds + (bufoff) + ldsw + _i * 8192), 16, 0, 0); } while (0)
; #define PG8_LDA(dst, b, h) do { _Pragma("unroll") for (int m = 0; m < 4; ++m) _Pragma("unroll") for (int k = 0; k < 2; ++k) dst[m][k] = *(const LAS bf16x8*)(lds + PG8_SA(b, h) + aoff + m * 2048 + k * 1024); } while (0)
; #define PG8_MMA(ai, bj, At, Bt) do { __builtin_amdgcn_s_setprio(1); _Pragma("unroll") for (int m = 0; m < 4; ++m) _Pragma("unroll") for (int n = 0; n < 2; ++n) _Pragma("unroll") for (int k = 0; k < 2; ++k) \
;         acc[ai][bj][m][n] = __builtin_amdgcn_mfma_f32_16x16x32_bf16(Bt[n][k], At[m][k], acc[ai][bj][m][n], 0, 0, 0); __builtin_amdgcn_s_setprio(0); } while (0)
; #define PG8_WAIT_V(n) asm volatile("s_waitcnt vmcnt(" #n ")" ::: "memory")
; #define PG8_WAIT_L(n) asm volatile("s_waitcnt lgkmcnt(" #n ")" ::: "memory")
; #define PG8_BAR __builtin_amdgcn_s_barrier()
; #define PG8_SCHED __builtin_amdgcn_sched_barrier(0)
; template <class Epi, bool ALIGN_EPI>
; __device__ __forceinline__ void gemm_phase(LAS unsigned char* lds, const Gemm g, const StaticOrder& S, const Epi& E, const int tid) {
;     ...
;             PG8_WAIT_V(8); PG8_WAIT_L(0); PG8_BAR; PG8_MMA(0, 0, At, B0); PG8_MMA(0, 1, At, B1); PG8_BAR; PG8_SCHED;
;             PG8_LDA(At, 0, 1); PG8_STAGE(PG8_SB(0, 0), b2, voffB); PG8_STAGE(PG8_SB(0, 1), b2 + hstepB, voffB); PG8_STAGE(PG8_SA(0, 0), a2, voffA);
	s_barrier
	s_add_i32 s89, s89, s61
	s_mov_b32 m0, s89
	ds_read_b128 v[184:187], v171 offset:16384
	ds_read_b128 v[188:191], v171 offset:17408
	ds_read_b128 v[192:195], v171 offset:18432
	ds_read_b128 v[196:199], v171 offset:19456


; #define PG8_STAGE(bufoff, gbase, voff) do { _Pragma("unroll") for (int _i = 0; _i < 2; ++_i) \
;         __builtin_amdgcn_global_load_lds((const unsigned*)((const char*)(gbase) + (voff)[_i]), (LAS unsigned*)(lds + (bufoff) + ldsw + _i * 8192), 16, 0, 0); } while (0)
; #define PG8_LDA(dst, b, h) do { _Pragma("unroll") for (int m = 0; m < 4; ++m) _Pragma("unroll") for (int k = 0; k < 2; ++k) dst[m][k] = *(const LAS bf16x8*)(lds + PG8_SA(b, h) + aoff + m * 2048 + k * 1024); } while (0)
; #define PG8_MMA(ai, bj, At, Bt) do { __builtin_amdgcn_s_setprio(1); _Pragma("unroll") for (int m = 0; m < 4; ++m) _Pragma("unroll") for (int n = 0; n < 2; ++n) _Pragma("unroll") for (int k = 0; k < 2; ++k) \
;         acc[ai][bj][m][n] = __builtin_amdgcn_mfma_f32_16x16x32_bf16(Bt[n][k], At[m][k], acc[ai][bj][m][n], 0, 0, 0); __builtin_amdgcn_s_setprio(0); } while (0)
; #define PG8_WAIT_V(n) asm volatile("s_waitcnt vmcnt(" #n ")" ::: "memory")
; #define PG8_WAIT_L(n) asm volatile("s_waitcnt lgkmcnt(" #n ")" ::: "memory")
; #define PG8_BAR __builtin_amdgcn_s_barrier()
; #define PG8_SCHED __builtin_amdgcn_sched_barrier(0)
; template <class Epi, bool ALIGN_EPI>
; __device__ __forceinline__ void gemm_phase(LAS unsigned char* lds, const Gemm g, const StaticOrder& S, const Epi& E, const int tid) {
;     ...
;             PG8_LDA(At, 0, 1); PG8_STAGE(PG8_SB(0, 0), b2, voffB); PG8_STAGE(PG8_SB(0, 1), b2 + hstepB, voffB); PG8_STAGE(PG8_SA(0, 0), a2, voffA);
;             PG8_WAIT_V(8); PG8_WAIT_L(0); PG8_BAR; PG8_MMA(1, 0, At, B0); PG8_MMA(1, 1, At, B1); PG8_BAR; PG8_SCHED;
	global_load_lds_dwordx4 v144, s[52:53]
	s_add_i32 m0, s89, 0x2000
	s_add_u32 s90, s52, 0x4000
	s_addc_u32 s91, s53, 0
	s_add_i32 s89, s92, s61
	global_load_lds_dwordx4 v140, s[52:53]
	s_mov_b32 m0, s89
	ds_read_b128 v[226:229], v171 offset:23552
	global_load_lds_dwordx4 v144, s[90:91]
	s_add_i32 m0, s89, 0x2000
	ds_read_b128 v[222:225], v171 offset:22528
	global_load_lds_dwordx4 v140, s[90:91]
	s_mov_b32 m0, s71
	ds_read_b128 v[218:221], v171 offset:21504
	global_load_lds_dwordx4 v146, s[54:55]
	s_mov_b32 m0, s72
	ds_read_b128 v[214:217], v171 offset:20480
	global_load_lds_dwordx4 v142, s[54:55]
	s_waitcnt vmcnt(8)
	s_waitcnt lgkmcnt(0)
	s_barrier


; #define PG8_MMA(ai, bj, At, Bt) do { __builtin_amdgcn_s_setprio(1); _Pragma("unroll") for (int m = 0; m < 4; ++m) _Pragma("unroll") for (int n = 0; n < 2; ++n) _Pragma("unroll") for (int k = 0; k < 2; ++k) \
;         acc[ai][bj][m][n] = __builtin_amdgcn_mfma_f32_16x16x32_bf16(Bt[n][k], At[m][k], acc[ai][bj][m][n], 0, 0, 0); __builtin_amdgcn_s_setprio(0); } while (0)
; #define PG8_WAIT_V(n) asm volatile("s_waitcnt vmcnt(" #n ")" ::: "memory")
; #define PG8_WAIT_L(n) asm volatile("s_waitcnt lgkmcnt(" #n ")" ::: "memory")
; #define PG8_BAR __builtin_amdgcn_s_barrier()
; #define PG8_SCHED __builtin_amdgcn_sched_barrier(0)
; template <class Epi, bool ALIGN_EPI>
; __device__ __forceinline__ void gemm_phase(LAS unsigned char* lds, const Gemm g, const StaticOrder& S, const Epi& E, const int tid) {
;     ...
;             PG8_WAIT_V(8); PG8_WAIT_L(0); PG8_BAR; PG8_MMA(1, 0, At, B0); PG8_MMA(1, 1, At, B1); PG8_BAR; PG8_SCHED;
	v_mfma_f32_16x16x32_bf16 v[84:87], v[132:135], v[184:187], v[84:87]
	v_mfma_f32_16x16x32_bf16 v[84:87], v[136:139], v[188:191], v[84:87]
	v_mfma_f32_16x16x32_bf16 v[56:59], v[156:159], v[188:191], v[56:59]
	v_mfma_f32_16x16x32_bf16 v[56:59], v[152:155], v[184:187], v[56:59]
	v_mfma_f32_16x16x32_bf16 v[20:23], v[176:179], v[184:187], v[20:23]
	v_mfma_f32_16x16x32_bf16 v[20:23], v[180:183], v[188:191], v[20:23]
	v_mfma_f32_16x16x32_bf16 v[40:43], v[172:175], v[188:191], v[40:43]
	v_mfma_f32_16x16x32_bf16 v[40:43], v[160:163], v[184:187], v[40:43]
	v_mfma_f32_16x16x32_bf16 v[32:35], v[160:163], v[192:195], v[32:35]
	v_mfma_f32_16x16x32_bf16 v[32:35], v[172:175], v[196:199], v[32:35]
	v_mfma_f32_16x16x32_bf16 v[12:15], v[180:183], v[196:199], v[12:15]
	v_mfma_f32_16x16x32_bf16 v[12:15], v[176:179], v[192:195], v[12:15]
	v_mfma_f32_16x16x32_bf16 v[44:47], v[152:155], v[192:195], v[44:47]
	v_mfma_f32_16x16x32_bf16 v[44:47], v[156:159], v[196:199], v[44:47]
	v_mfma_f32_16x16x32_bf16 v[72:75], v[136:139], v[196:199], v[72:75]
	v_mfma_f32_16x16x32_bf16 v[72:75], v[132:135], v[192:195], v[72:75]


; #define PG8_MMA(ai, bj, At, Bt) do { __builtin_amdgcn_s_setprio(1); _Pragma("unroll") for (int m = 0; m < 4; ++m) _Pragma("unroll") for (int n = 0; n < 2; ++n) _Pragma("unroll") for (int k = 0; k < 2; ++k) \
;         acc[ai][bj][m][n] = __builtin_amdgcn_mfma_f32_16x16x32_bf16(Bt[n][k], At[m][k], acc[ai][bj][m][n], 0, 0, 0); __builtin_amdgcn_s_setprio(0); } while (0)
; #define PG8_WAIT_V(n) asm volatile("s_waitcnt vmcnt(" #n ")" ::: "memory")
; #define PG8_WAIT_L(n) asm volatile("s_waitcnt lgkmcnt(" #n ")" ::: "memory")
; #define PG8_BAR __builtin_amdgcn_s_barrier()
; #define PG8_SCHED __builtin_amdgcn_sched_barrier(0)
; template <class Epi, bool ALIGN_EPI>
; __device__ __forceinline__ void gemm_phase(LAS unsigned char* lds, const Gemm g, const StaticOrder& S, const Epi& E, const int tid) {
;     ...
;             PG8_WAIT_V(8); PG8_WAIT_L(0); PG8_BAR; PG8_MMA(1, 0, At, B0); PG8_MMA(1, 1, At, B1); PG8_BAR; PG8_SCHED;
	v_mfma_f32_16x16x32_bf16 v[64:67], v[132:135], v[214:217], v[64:67]
	v_mfma_f32_16x16x32_bf16 v[64:67], v[136:139], v[218:221], v[64:67]
	v_mfma_f32_16x16x32_bf16 v[36:39], v[156:159], v[218:221], v[36:39]
	v_mfma_f32_16x16x32_bf16 v[36:39], v[152:155], v[214:217], v[36:39]
	v_mfma_f32_16x16x32_bf16 v[8:11], v[176:179], v[214:217], v[8:11]
	v_mfma_f32_16x16x32_bf16 v[8:11], v[180:183], v[218:221], v[8:11]
	v_mfma_f32_16x16x32_bf16 v[24:27], v[172:175], v[218:221], v[24:27]
	v_mfma_f32_16x16x32_bf16 v[24:27], v[160:163], v[214:217], v[24:27]
	v_mfma_f32_16x16x32_bf16 v[16:19], v[160:163], v[222:225], v[16:19]
	v_mfma_f32_16x16x32_bf16 v[16:19], v[172:175], v[226:229], v[16:19]
	v_mfma_f32_16x16x32_bf16 v[2:5], v[176:179], v[222:225], v[4:7]
	v_mfma_f32_16x16x32_bf16 v[2:5], v[180:183], v[226:229], v[2:5]
	v_mfma_f32_16x16x32_bf16 v[28:31], v[156:159], v[226:229], v[28:31]
	v_mfma_f32_16x16x32_bf16 v[28:31], v[152:155], v[222:225], v[28:31]
	v_mfma_f32_16x16x32_bf16 v[52:55], v[132:135], v[222:225], v[52:55]
	v_mfma_f32_16x16x32_bf16 v[52:55], v[136:139], v[226:229], v[52:55]

; #define PG8_STAGE(bufoff, gbase, voff) do { _Pragma("unroll") for (int _i = 0; _i < 2; ++_i) \
;         __builtin_amdgcn_global_load_lds((const unsigned*)((const char*)(gbase) + (voff)[_i]), (LAS unsigned*)(lds + (bufoff) + ldsw + _i * 8192), 16, 0, 0); } while (0)
; #define PG8_LDA(dst, b, h) do { _Pragma("unroll") for (int m = 0; m < 4; ++m) _Pragma("unroll") for (int k = 0; k < 2; ++k) dst[m][k] = *(const LAS bf16x8*)(lds + PG8_SA(b, h) + aoff + m * 2048 + k * 1024); } while (0)
; #define PG8_LDB(dst, b, h) do { _Pragma("unroll") for (int n = 0; n < 2; ++n) _Pragma("unroll") for (int k = 0; k < 2; ++k) dst[n][k] = *(const LAS bf16x8*)(lds + PG8_SB(b, h) + boff + n * 2048 + k * 1024); } while (0)
; #define PG8_MMA(ai, bj, At, Bt) do { __builtin_amdgcn_s_setprio(1); _Pragma("unroll") for (int m = 0; m < 4; ++m) _Pragma("unroll") for (int n = 0; n < 2; ++n) _Pragma("unroll") for (int k = 0; k < 2; ++k) \
;         acc[ai][bj][m][n] = __builtin_amdgcn_mfma_f32_16x16x32_bf16(Bt[n][k], At[m][k], acc[ai][bj][m][n], 0, 0, 0); __builtin_amdgcn_s_setprio(0); } while (0)
; #define PG8_WAIT_V(n) asm volatile("s_waitcnt vmcnt(" #n ")" ::: "memory")
; #define PG8_WAIT_L(n) asm volatile("s_waitcnt lgkmcnt(" #n ")" ::: "memory")
; #define PG8_BAR __builtin_amdgcn_s_barrier()
; #define PG8_SCHED __builtin_amdgcn_sched_barrier(0)
; template <class Epi, bool ALIGN_EPI>
; __device__ __forceinline__ void gemm_phase(LAS unsigned char* lds, const Gemm g, const StaticOrder& S, const Epi& E, const int tid) {
;     ...
;             PG8_WAIT_V(8); PG8_WAIT_L(0); PG8_BAR; PG8_MMA(1, 0, At, B0); PG8_MMA(1, 1, At, B1); PG8_BAR; PG8_SCHED;
;             PG8_LDB(B0, 1, 0); PG8_LDB(B1, 1, 1); PG8_SCHED; PG8_LDA(At, 1, 0); PG8_STAGE(PG8_SA(0, 1), a2 + hstepA, voffA);
	s_barrier
	s_add_i32 s89, 0, 0x18000

; #define PG8_STAGE(bufoff, gbase, voff) do { _Pragma("unroll") for (int _i = 0; _i < 2; ++_i) \
;         __builtin_amdgcn_global_load_lds((const unsigned*)((const char*)(gbase) + (voff)[_i]), (LAS unsigned*)(lds + (bufoff) + ldsw + _i * 8192), 16, 0, 0); } while (0)
; #define PG8_LDA(dst, b, h) do { _Pragma("unroll") for (int m = 0; m < 4; ++m) _Pragma("unroll") for (int k = 0; k < 2; ++k) dst[m][k] = *(const LAS bf16x8*)(lds + PG8_SA(b, h) + aoff + m * 2048 + k * 1024); } while (0)
; #define PG8_LDB(dst, b, h) do { _Pragma("unroll") for (int n = 0; n < 2; ++n) _Pragma("unroll") for (int k = 0; k < 2; ++k) dst[n][k] = *(const LAS bf16x8*)(lds + PG8_SB(b, h) + boff + n * 2048 + k * 1024); } while (0)
; #define PG8_SCHED __builtin_amdgcn_sched_barrier(0)
; template <class Epi, bool ALIGN_EPI>
; __device__ __forceinline__ void gemm_phase(LAS unsigned char* lds, const Gemm g, const StaticOrder& S, const Epi& E, const int tid) {
;     ...
;             PG8_LDB(B0, 1, 0); PG8_LDB(B1, 1, 1); PG8_SCHED; PG8_LDA(At, 1, 0); PG8_STAGE(PG8_SA(0, 1), a2 + hstepA, voffA);
	s_add_i32 s90, 0, 0x1c000
	ds_read_b128 v[132:135], v243
	ds_read_b128 v[136:139], v243 offset:1024
	ds_read_b128 v[152:155], v243 offset:2048
	ds_read_b128 v[156:159], v243 offset:3072

; #define PG8_STAGE(bufoff, gbase, voff) do { _Pragma("unroll") for (int _i = 0; _i < 2; ++_i) \
;         __builtin_amdgcn_global_load_lds((const unsigned*)((const char*)(gbase) + (voff)[_i]), (LAS unsigned*)(lds + (bufoff) + ldsw + _i * 8192), 16, 0, 0); } while (0)
; #define PG8_LDA(dst, b, h) do { _Pragma("unroll") for (int m = 0; m < 4; ++m) _Pragma("unroll") for (int k = 0; k < 2; ++k) dst[m][k] = *(const LAS bf16x8*)(lds + PG8_SA(b, h) + aoff + m * 2048 + k * 1024); } while (0)
; #define PG8_LDB(dst, b, h) do { _Pragma("unroll") for (int n = 0; n < 2; ++n) _Pragma("unroll") for (int k = 0; k < 2; ++k) dst[n][k] = *(const LAS bf16x8*)(lds + PG8_SB(b, h) + boff + n * 2048 + k * 1024); } while (0)
; #define PG8_SCHED __builtin_amdgcn_sched_barrier(0)
; template <class Epi, bool ALIGN_EPI>
; __device__ __forceinline__ void gemm_phase(LAS unsigned char* lds, const Gemm g, const StaticOrder& S, const Epi& E, const int tid) {
;     ...
;             PG8_LDB(B0, 1, 0); PG8_LDB(B1, 1, 1); PG8_SCHED; PG8_LDA(At, 1, 0); PG8_STAGE(PG8_SA(0, 1), a2 + hstepA, voffA);
	ds_read_b128 v[160:163], v244
	ds_read_b128 v[172:175], v244 offset:1024
	ds_read_b128 v[176:179], v244 offset:2048
	ds_read_b128 v[180:183], v244 offset:3072
	s_add_u32 s54, s54, 0x4000
	s_addc_u32 s55, s55, 0
	s_mov_b32 m0, s73
	ds_read_b128 v[184:187], v171 offset:32768
	ds_read_b128 v[188:191], v171 offset:33792
	ds_read_b128 v[192:195], v171 offset:34816
	ds_read_b128 v[196:199], v171 offset:35840
	ds_read_b128 v[214:217], v171 offset:36864
	ds_read_b128 v[218:221], v171 offset:37888
	ds_read_b128 v[222:225], v171 offset:38912

; #define PG8_STAGE(bufoff, gbase, voff) do { _Pragma("unroll") for (int _i = 0; _i < 2; ++_i) \
;         __builtin_amdgcn_global_load_lds((const unsigned*)((const char*)(gbase) + (voff)[_i]), (LAS unsigned*)(lds + (bufoff) + ldsw + _i * 8192), 16, 0, 0); } while (0)
; #define PG8_LDA(dst, b, h) do { _Pragma("unroll") for (int m = 0; m < 4; ++m) _Pragma("unroll") for (int k = 0; k < 2; ++k) dst[m][k] = *(const LAS bf16x8*)(lds + PG8_SA(b, h) + aoff + m * 2048 + k * 1024); } while (0)
; #define PG8_LDB(dst, b, h) do { _Pragma("unroll") for (int n = 0; n < 2; ++n) _Pragma("unroll") for (int k = 0; k < 2; ++k) dst[n][k] = *(const LAS bf16x8*)(lds + PG8_SB(b, h) + boff + n * 2048 + k * 1024); } while (0)
; #define PG8_MMA(ai, bj, At, Bt) do { __builtin_amdgcn_s_setprio(1); _Pragma("unroll") for (int m = 0; m < 4; ++m) _Pragma("unroll") for (int n = 0; n < 2; ++n) _Pragma("unroll") for (int k = 0; k < 2; ++k) \
;         acc[ai][bj][m][n] = __builtin_amdgcn_mfma_f32_16x16x32_bf16(Bt[n][k], At[m][k], acc[ai][bj][m][n], 0, 0, 0); __builtin_amdgcn_s_setprio(0); } while (0)
; #define PG8_WAIT_V(n) asm volatile("s_waitcnt vmcnt(" #n ")" ::: "memory")
; #define PG8_WAIT_L(n) asm volatile("s_waitcnt lgkmcnt(" #n ")" ::: "memory")
; #define PG8_BAR __builtin_amdgcn_s_barrier()
; #define PG8_SCHED __builtin_amdgcn_sched_barrier(0)
; template <class Epi, bool ALIGN_EPI>
; __device__ __forceinline__ void gemm_phase(LAS unsigned char* lds, const Gemm g, const StaticOrder& S, const Epi& E, const int tid) {
;     ...
;             PG8_LDB(B0, 1, 0); PG8_LDB(B1, 1, 1); PG8_SCHED; PG8_LDA(At, 1, 0); PG8_STAGE(PG8_SA(0, 1), a2 + hstepA, voffA);
;             PG8_WAIT_V(8); PG8_WAIT_L(0); PG8_BAR; PG8_MMA(0, 0, At, B0); PG8_MMA(0, 1, At, B1); PG8_BAR; PG8_SCHED;
	global_load_lds_dwordx4 v146, s[54:55]
	s_mov_b32 m0, s74
	ds_read_b128 v[226:229], v171 offset:39936
	global_load_lds_dwordx4 v142, s[54:55]
	s_waitcnt vmcnt(8)
	s_waitcnt lgkmcnt(0)
	s_barrier


; #define PG8_MMA(ai, bj, At, Bt) do { __builtin_amdgcn_s_setprio(1); _Pragma("unroll") for (int m = 0; m < 4; ++m) _Pragma("unroll") for (int n = 0; n < 2; ++n) _Pragma("unroll") for (int k = 0; k < 2; ++k) \
;         acc[ai][bj][m][n] = __builtin_amdgcn_mfma_f32_16x16x32_bf16(Bt[n][k], At[m][k], acc[ai][bj][m][n], 0, 0, 0); __builtin_amdgcn_s_setprio(0); } while (0)
; #define PG8_WAIT_V(n) asm volatile("s_waitcnt vmcnt(" #n ")" ::: "memory")
; #define PG8_WAIT_L(n) asm volatile("s_waitcnt lgkmcnt(" #n ")" ::: "memory")
; #define PG8_BAR __builtin_amdgcn_s_barrier()
; #define PG8_SCHED __builtin_amdgcn_sched_barrier(0)
; template <class Epi, bool ALIGN_EPI>
; __device__ __forceinline__ void gemm_phase(LAS unsigned char* lds, const Gemm g, const StaticOrder& S, const Epi& E, const int tid) {
;     ...
;             PG8_WAIT_V(8); PG8_WAIT_L(0); PG8_BAR; PG8_MMA(0, 0, At, B0); PG8_MMA(0, 1, At, B1); PG8_BAR; PG8_SCHED;
	v_mfma_f32_16x16x32_bf16 v[128:131], v[132:135], v[184:187], v[128:131]
	v_mfma_f32_16x16x32_bf16 v[128:131], v[136:139], v[188:191], v[128:131]
	v_mfma_f32_16x16x32_bf16 v[116:119], v[156:159], v[188:191], v[116:119]
	v_mfma_f32_16x16x32_bf16 v[116:119], v[152:155], v[184:187], v[116:119]
	v_mfma_f32_16x16x32_bf16 v[80:83], v[176:179], v[184:187], v[80:83]
	v_mfma_f32_16x16x32_bf16 v[80:83], v[180:183], v[188:191], v[80:83]
	v_mfma_f32_16x16x32_bf16 v[104:107], v[172:175], v[188:191], v[104:107]
	v_mfma_f32_16x16x32_bf16 v[104:107], v[160:163], v[184:187], v[104:107]
	v_mfma_f32_16x16x32_bf16 v[96:99], v[160:163], v[192:195], v[96:99]
	v_mfma_f32_16x16x32_bf16 v[96:99], v[172:175], v[196:199], v[96:99]
	v_mfma_f32_16x16x32_bf16 v[68:71], v[180:183], v[196:199], v[68:71]
	v_mfma_f32_16x16x32_bf16 v[68:71], v[176:179], v[192:195], v[68:71]
	v_mfma_f32_16x16x32_bf16 v[108:111], v[152:155], v[192:195], v[108:111]
	v_mfma_f32_16x16x32_bf16 v[108:111], v[156:159], v[196:199], v[108:111]
	v_mfma_f32_16x16x32_bf16 v[124:127], v[136:139], v[196:199], v[124:127]
	v_mfma_f32_16x16x32_bf16 v[124:127], v[132:135], v[192:195], v[124:127]


; #define PG8_MMA(ai, bj, At, Bt) do { __builtin_amdgcn_s_setprio(1); _Pragma("unroll") for (int m = 0; m < 4; ++m) _Pragma("unroll") for (int n = 0; n < 2; ++n) _Pragma("unroll") for (int k = 0; k < 2; ++k) \
;         acc[ai][bj][m][n] = __builtin_amdgcn_mfma_f32_16x16x32_bf16(Bt[n][k], At[m][k], acc[ai][bj][m][n], 0, 0, 0); __builtin_amdgcn_s_setprio(0); } while (0)
; #define PG8_WAIT_V(n) asm volatile("s_waitcnt vmcnt(" #n ")" ::: "memory")
; #define PG8_WAIT_L(n) asm volatile("s_waitcnt lgkmcnt(" #n ")" ::: "memory")
; #define PG8_BAR __builtin_amdgcn_s_barrier()
; #define PG8_SCHED __builtin_amdgcn_sched_barrier(0)
; template <class Epi, bool ALIGN_EPI>
; __device__ __forceinline__ void gemm_phase(LAS unsigned char* lds, const Gemm g, const StaticOrder& S, const Epi& E, const int tid) {
;     ...
;             PG8_WAIT_V(8); PG8_WAIT_L(0); PG8_BAR; PG8_MMA(0, 0, At, B0); PG8_MMA(0, 1, At, B1); PG8_BAR; PG8_SCHED;
	v_mfma_f32_16x16x32_bf16 v[120:123], v[132:135], v[214:217], v[120:123]
	v_mfma_f32_16x16x32_bf16 v[120:123], v[136:139], v[218:221], v[120:123]
	v_mfma_f32_16x16x32_bf16 v[100:103], v[156:159], v[218:221], v[100:103]
	v_mfma_f32_16x16x32_bf16 v[100:103], v[152:155], v[214:217], v[100:103]
	v_mfma_f32_16x16x32_bf16 v[60:63], v[176:179], v[214:217], v[60:63]
	v_mfma_f32_16x16x32_bf16 v[60:63], v[180:183], v[218:221], v[60:63]
	v_mfma_f32_16x16x32_bf16 v[88:91], v[172:175], v[218:221], v[88:91]
	v_mfma_f32_16x16x32_bf16 v[88:91], v[160:163], v[214:217], v[88:91]
	v_mfma_f32_16x16x32_bf16 v[76:79], v[160:163], v[222:225], v[76:79]
	v_mfma_f32_16x16x32_bf16 v[76:79], v[172:175], v[226:229], v[76:79]
	v_mfma_f32_16x16x32_bf16 v[48:51], v[180:183], v[226:229], v[48:51]
	v_mfma_f32_16x16x32_bf16 v[48:51], v[176:179], v[222:225], v[48:51]
	v_mfma_f32_16x16x32_bf16 v[92:95], v[152:155], v[222:225], v[92:95]
	v_mfma_f32_16x16x32_bf16 v[92:95], v[156:159], v[226:229], v[92:95]
	v_mfma_f32_16x16x32_bf16 v[112:115], v[136:139], v[226:229], v[112:115]
	v_mfma_f32_16x16x32_bf16 v[112:115], v[132:135], v[222:225], v[112:115]

; #define PG8_STAGE(bufoff, gbase, voff) do { _Pragma("unroll") for (int _i = 0; _i < 2; ++_i) \
;         __builtin_amdgcn_global_load_lds((const unsigned*)((const char*)(gbase) + (voff)[_i]), (LAS unsigned*)(lds + (bufoff) + ldsw + _i * 8192), 16, 0, 0); } while (0)
; #define PG8_LDA(dst, b, h) do { _Pragma("unroll") for (int m = 0; m < 4; ++m) _Pragma("unroll") for (int k = 0; k < 2; ++k) dst[m][k] = *(const LAS bf16x8*)(lds + PG8_SA(b, h) + aoff + m * 2048 + k * 1024); } while (0)
; #define PG8_MMA(ai, bj, At, Bt) do { __builtin_amdgcn_s_setprio(1); _Pragma("unroll") for (int m = 0; m < 4; ++m) _Pragma("unroll") for (int n = 0; n < 2; ++n) _Pragma("unroll") for (int k = 0; k < 2; ++k) \
;         acc[ai][bj][m][n] = __builtin_amdgcn_mfma_f32_16x16x32_bf16(Bt[n][k], At[m][k], acc[ai][bj][m][n], 0, 0, 0); __builtin_amdgcn_s_setprio(0); } while (0)
; #define PG8_WAIT_V(n) asm volatile("s_waitcnt vmcnt(" #n ")" ::: "memory")
; #define PG8_WAIT_L(n) asm volatile("s_waitcnt lgkmcnt(" #n ")" ::: "memory")
; #define PG8_BAR __builtin_amdgcn_s_barrier()
; #define PG8_SCHED __builtin_amdgcn_sched_barrier(0)
; template <class Epi, bool ALIGN_EPI>
; __device__ __forceinline__ void gemm_phase(LAS unsigned char* lds, const Gemm g, const StaticOrder& S, const Epi& E, const int tid) {
;     ...
;             PG8_WAIT_V(8); PG8_WAIT_L(0); PG8_BAR; PG8_MMA(0, 0, At, B0); PG8_MMA(0, 1, At, B1); PG8_BAR; PG8_SCHED;
;             PG8_LDA(At, 1, 1); PG8_STAGE(PG8_SB(1, 0), b3, voffB); PG8_STAGE(PG8_SB(1, 1), b3 + hstepB, voffB); PG8_STAGE(PG8_SA(1, 0), a3, voffA);
	s_barrier
	s_add_u32 s54, s52, 0x8000
	s_addc_u32 s55, s53, 0
	s_add_i32 s89, s89, s61
	s_mov_b32 m0, s89
	ds_read_b128 v[184:187], v171 offset:49152
	ds_read_b128 v[188:191], v171 offset:50176
	ds_read_b128 v[192:195], v171 offset:51200
	ds_read_b128 v[196:199], v171 offset:52224


; #define PG8_STAGE(bufoff, gbase, voff) do { _Pragma("unroll") for (int _i = 0; _i < 2; ++_i) \
;         __builtin_amdgcn_global_load_lds((const unsigned*)((const char*)(gbase) + (voff)[_i]), (LAS unsigned*)(lds + (bufoff) + ldsw + _i * 8192), 16, 0, 0); } while (0)
; #define PG8_LDA(dst, b, h) do { _Pragma("unroll") for (int m = 0; m < 4; ++m) _Pragma("unroll") for (int k = 0; k < 2; ++k) dst[m][k] = *(const LAS bf16x8*)(lds + PG8_SA(b, h) + aoff + m * 2048 + k * 1024); } while (0)
; #define PG8_MMA(ai, bj, At, Bt) do { __builtin_amdgcn_s_setprio(1); _Pragma("unroll") for (int m = 0; m < 4; ++m) _Pragma("unroll") for (int n = 0; n < 2; ++n) _Pragma("unroll") for (int k = 0; k < 2; ++k) \
;         acc[ai][bj][m][n] = __builtin_amdgcn_mfma_f32_16x16x32_bf16(Bt[n][k], At[m][k], acc[ai][bj][m][n], 0, 0, 0); __builtin_amdgcn_s_setprio(0); } while (0)
; #define PG8_WAIT_V(n) asm volatile("s_waitcnt vmcnt(" #n ")" ::: "memory")
; #define PG8_WAIT_L(n) asm volatile("s_waitcnt lgkmcnt(" #n ")" ::: "memory")
; #define PG8_BAR __builtin_amdgcn_s_barrier()
; #define PG8_SCHED __builtin_amdgcn_sched_barrier(0)
; template <class Epi, bool ALIGN_EPI>
; __device__ __forceinline__ void gemm_phase(LAS unsigned char* lds, const Gemm g, const StaticOrder& S, const Epi& E, const int tid) {
;     ...
;             PG8_LDA(At, 1, 1); PG8_STAGE(PG8_SB(1, 0), b3, voffB); PG8_STAGE(PG8_SB(1, 1), b3 + hstepB, voffB); PG8_STAGE(PG8_SA(1, 0), a3, voffA);
;             PG8_WAIT_V(8); PG8_WAIT_L(0); PG8_BAR; PG8_MMA(1, 0, At, B0); PG8_MMA(1, 1, At, B1); PG8_BAR; PG8_SCHED;
	global_load_lds_dwordx4 v144, s[54:55]
	s_add_i32 m0, s89, 0x2000
	s_add_u32 s52, s52, 0xc000
	s_addc_u32 s53, s53, 0
	global_load_lds_dwordx4 v140, s[54:55]
	s_add_i32 s54, s90, s61
	s_mov_b32 m0, s54
	ds_read_b128 v[226:229], v171 offset:56320
	global_load_lds_dwordx4 v144, s[52:53]
	s_add_i32 m0, s54, 0x2000
	ds_read_b128 v[222:225], v171 offset:55296
	global_load_lds_dwordx4 v140, s[52:53]
	s_mov_b32 m0, s77
	ds_read_b128 v[218:221], v171 offset:54272
	global_load_lds_dwordx4 v146, s[50:51]
	s_mov_b32 m0, s78
	ds_read_b128 v[214:217], v171 offset:53248
	global_load_lds_dwordx4 v142, s[50:51]
	s_waitcnt vmcnt(8)
	s_waitcnt lgkmcnt(0)
	s_barrier


; #define PG8_MMA(ai, bj, At, Bt) do { __builtin_amdgcn_s_setprio(1); _Pragma("unroll") for (int m = 0; m < 4; ++m) _Pragma("unroll") for (int n = 0; n < 2; ++n) _Pragma("unroll") for (int k = 0; k < 2; ++k) \
;         acc[ai][bj][m][n] = __builtin_amdgcn_mfma_f32_16x16x32_bf16(Bt[n][k], At[m][k], acc[ai][bj][m][n], 0, 0, 0); __builtin_amdgcn_s_setprio(0); } while (0)
; #define PG8_WAIT_V(n) asm volatile("s_waitcnt vmcnt(" #n ")" ::: "memory")
; #define PG8_WAIT_L(n) asm volatile("s_waitcnt lgkmcnt(" #n ")" ::: "memory")
; #define PG8_BAR __builtin_amdgcn_s_barrier()
; #define PG8_SCHED __builtin_amdgcn_sched_barrier(0)
; template <class Epi, bool ALIGN_EPI>
; __device__ __forceinline__ void gemm_phase(LAS unsigned char* lds, const Gemm g, const StaticOrder& S, const Epi& E, const int tid) {
;     ...
;             PG8_WAIT_V(8); PG8_WAIT_L(0); PG8_BAR; PG8_MMA(1, 0, At, B0); PG8_MMA(1, 1, At, B1); PG8_BAR; PG8_SCHED;
	v_mfma_f32_16x16x32_bf16 v[84:87], v[132:135], v[184:187], v[84:87]
	v_mfma_f32_16x16x32_bf16 v[84:87], v[136:139], v[188:191], v[84:87]
	v_mfma_f32_16x16x32_bf16 v[56:59], v[156:159], v[188:191], v[56:59]
	v_mfma_f32_16x16x32_bf16 v[56:59], v[152:155], v[184:187], v[56:59]
	v_mfma_f32_16x16x32_bf16 v[20:23], v[176:179], v[184:187], v[20:23]
	v_mfma_f32_16x16x32_bf16 v[20:23], v[180:183], v[188:191], v[20:23]
	v_mfma_f32_16x16x32_bf16 v[40:43], v[172:175], v[188:191], v[40:43]
	v_mfma_f32_16x16x32_bf16 v[40:43], v[160:163], v[184:187], v[40:43]
	v_mfma_f32_16x16x32_bf16 v[32:35], v[160:163], v[192:195], v[32:35]
	v_mfma_f32_16x16x32_bf16 v[32:35], v[172:175], v[196:199], v[32:35]
	v_mfma_f32_16x16x32_bf16 v[12:15], v[180:183], v[196:199], v[12:15]
	v_mfma_f32_16x16x32_bf16 v[12:15], v[176:179], v[192:195], v[12:15]
	v_mfma_f32_16x16x32_bf16 v[44:47], v[152:155], v[192:195], v[44:47]
	v_mfma_f32_16x16x32_bf16 v[44:47], v[156:159], v[196:199], v[44:47]
	v_mfma_f32_16x16x32_bf16 v[72:75], v[136:139], v[196:199], v[72:75]
	v_mfma_f32_16x16x32_bf16 v[72:75], v[132:135], v[192:195], v[72:75]


; #define PG8_MMA(ai, bj, At, Bt) do { __builtin_amdgcn_s_setprio(1); _Pragma("unroll") for (int m = 0; m < 4; ++m) _Pragma("unroll") for (int n = 0; n < 2; ++n) _Pragma("unroll") for (int k = 0; k < 2; ++k) \
;         acc[ai][bj][m][n] = __builtin_amdgcn_mfma_f32_16x16x32_bf16(Bt[n][k], At[m][k], acc[ai][bj][m][n], 0, 0, 0); __builtin_amdgcn_s_setprio(0); } while (0)
; #define PG8_WAIT_V(n) asm volatile("s_waitcnt vmcnt(" #n ")" ::: "memory")
; #define PG8_WAIT_L(n) asm volatile("s_waitcnt lgkmcnt(" #n ")" ::: "memory")
; #define PG8_BAR __builtin_amdgcn_s_barrier()
; #define PG8_SCHED __builtin_amdgcn_sched_barrier(0)
; template <class Epi, bool ALIGN_EPI>
; __device__ __forceinline__ void gemm_phase(LAS unsigned char* lds, const Gemm g, const StaticOrder& S, const Epi& E, const int tid) {
;     ...
;             PG8_WAIT_V(8); PG8_WAIT_L(0); PG8_BAR; PG8_MMA(1, 0, At, B0); PG8_MMA(1, 1, At, B1); PG8_BAR; PG8_SCHED;
	v_mfma_f32_16x16x32_bf16 v[64:67], v[132:135], v[214:217], v[64:67]
	v_mfma_f32_16x16x32_bf16 v[64:67], v[136:139], v[218:221], v[64:67]
	v_mfma_f32_16x16x32_bf16 v[36:39], v[156:159], v[218:221], v[36:39]
	v_mfma_f32_16x16x32_bf16 v[36:39], v[152:155], v[214:217], v[36:39]
	v_mfma_f32_16x16x32_bf16 v[6:9], v[176:179], v[214:217], v[8:11]
	v_mfma_f32_16x16x32_bf16 v[8:11], v[180:183], v[218:221], v[6:9]
	v_mfma_f32_16x16x32_bf16 v[24:27], v[172:175], v[218:221], v[24:27]
	v_mfma_f32_16x16x32_bf16 v[24:27], v[160:163], v[214:217], v[24:27]
	v_mfma_f32_16x16x32_bf16 v[16:19], v[160:163], v[222:225], v[16:19]
	v_mfma_f32_16x16x32_bf16 v[16:19], v[172:175], v[226:229], v[16:19]
	v_mfma_f32_16x16x32_bf16 v[2:5], v[176:179], v[222:225], v[2:5]
	v_mfma_f32_16x16x32_bf16 v[4:7], v[180:183], v[226:229], v[2:5]
	v_mfma_f32_16x16x32_bf16 v[28:31], v[156:159], v[226:229], v[28:31]
	v_mfma_f32_16x16x32_bf16 v[28:31], v[152:155], v[222:225], v[28:31]
	v_mfma_f32_16x16x32_bf16 v[52:55], v[132:135], v[222:225], v[52:55]
	v_mfma_f32_16x16x32_bf16 v[52:55], v[136:139], v[226:229], v[52:55]

; #define PG8_STAGE(bufoff, gbase, voff) do { _Pragma("unroll") for (int _i = 0; _i < 2; ++_i) \
;         __builtin_amdgcn_global_load_lds((const unsigned*)((const char*)(gbase) + (voff)[_i]), (LAS unsigned*)(lds + (bufoff) + ldsw + _i * 8192), 16, 0, 0); } while (0)
; #define PG8_LDA(dst, b, h) do { _Pragma("unroll") for (int m = 0; m < 4; ++m) _Pragma("unroll") for (int k = 0; k < 2; ++k) dst[m][k] = *(const LAS bf16x8*)(lds + PG8_SA(b, h) + aoff + m * 2048 + k * 1024); } while (0)
; #define PG8_LDB(dst, b, h) do { _Pragma("unroll") for (int n = 0; n < 2; ++n) _Pragma("unroll") for (int k = 0; k < 2; ++k) dst[n][k] = *(const LAS bf16x8*)(lds + PG8_SB(b, h) + boff + n * 2048 + k * 1024); } while (0)
; #define PG8_BAR __builtin_amdgcn_s_barrier()
; template <class Epi, bool ALIGN_EPI>
; __device__ __forceinline__ void gemm_phase(LAS unsigned char* lds, const Gemm g, const StaticOrder& S, const Epi& E, const int tid) {
;     ...
;         for (int t = 0; t < nt; t += 2) {
;             const bool last = (t == nt - 2);
;             const char* a1 = cA + (size_t)(t + 1) * kstepA;
;             const char* a2 = last ? nA : cA + (size_t)(t + 2) * kstepA; const char* b2 = last ? nB : cB + (size_t)(t + 2) * kstepB;
;             const char* a3 = a2 + kstepA; const char* b3 = b2 + kstepB;
;             PG8_LDB(B0, 0, 0); PG8_LDB(B1, 0, 1); PG8_SCHED; PG8_LDA(At, 0, 0); PG8_STAGE(PG8_SA(1, 1), a1 + hstepA, voffA);
;             PG8_WAIT_V(8); PG8_WAIT_L(0); PG8_BAR; PG8_MMA(0, 0, At, B0); PG8_MMA(0, 1, At, B1); PG8_BAR; PG8_SCHED;
;             PG8_LDA(At, 0, 1); PG8_STAGE(PG8_SB(0, 0), b2, voffB); PG8_STAGE(PG8_SB(0, 1), b2 + hstepB, voffB); PG8_STAGE(PG8_SA(0, 0), a2, voffA);
;             PG8_WAIT_V(8); PG8_WAIT_L(0); PG8_BAR; PG8_MMA(1, 0, At, B0); PG8_MMA(1, 1, At, B1); PG8_BAR; PG8_SCHED;
;             PG8_LDB(B0, 1, 0); PG8_LDB(B1, 1, 1); PG8_SCHED; PG8_LDA(At, 1, 0); PG8_STAGE(PG8_SA(0, 1), a2 + hstepA, voffA);
;             PG8_WAIT_V(8); PG8_WAIT_L(0); PG8_BAR; PG8_MMA(0, 0, At, B0); PG8_MMA(0, 1, At, B1); PG8_BAR; PG8_SCHED;
;             PG8_LDA(At, 1, 1); PG8_STAGE(PG8_SB(1, 0), b3, voffB); PG8_STAGE(PG8_SB(1, 1), b3 + hstepB, voffB); PG8_STAGE(PG8_SA(1, 0), a3, voffA);
;             PG8_WAIT_V(8); PG8_WAIT_L(0); PG8_BAR; PG8_MMA(1, 0, At, B0); PG8_MMA(1, 1, At, B1); PG8_BAR; PG8_SCHED;
;         }
;         if constexpr (ALIGN_EPI) { if (wr == 0) PG8_BAR; }
	s_barrier
	s_add_i32 s88, s88, 2
	s_add_u32 s48, s48, 0x10000
	s_addc_u32 s49, s49, 0
	s_add_u32 s86, s86, 0x10000
	s_addc_u32 s87, s87, 0
	s_cmp_gt_u32 s88, 29
	s_cbranch_scc0 .LBB0_385
	s_and_b64 vcc, exec, s[34:35]
	s_cbranch_vccz .LBB0_388
	s_barrier

; #define PG8_STAGE(bufoff, gbase, voff) do { _Pragma("unroll") for (int _i = 0; _i < 2; ++_i) \
;         __builtin_amdgcn_global_load_lds((const unsigned*)((const char*)(gbase) + (voff)[_i]), (LAS unsigned*)(lds + (bufoff) + ldsw + _i * 8192), 16, 0, 0); } while (0)
; #define PG8_LDA(dst, b, h) do { _Pragma("unroll") for (int m = 0; m < 4; ++m) _Pragma("unroll") for (int k = 0; k < 2; ++k) dst[m][k] = *(const LAS bf16x8*)(lds + PG8_SA(b, h) + aoff + m * 2048 + k * 1024); } while (0)
; #define PG8_LDB(dst, b, h) do { _Pragma("unroll") for (int n = 0; n < 2; ++n) _Pragma("unroll") for (int k = 0; k < 2; ++k) dst[n][k] = *(const LAS bf16x8*)(lds + PG8_SB(b, h) + boff + n * 2048 + k * 1024); } while (0)
; #define PG8_SCHED __builtin_amdgcn_sched_barrier(0)
; template <class Epi, bool ALIGN_EPI>
; __device__ __forceinline__ void gemm_phase(LAS unsigned char* lds, const Gemm g, const StaticOrder& S, const Epi& E, const int tid) {
;     ...
;             const bool last = (t == nt - 2);
;             const char* a1 = cA + (size_t)(t + 1) * kstepA;
;             const char* a2 = last ? nA : cA + (size_t)(t + 2) * kstepA; const char* b2 = last ? nB : cB + (size_t)(t + 2) * kstepB;
;             const char* a3 = a2 + kstepA; const char* b3 = b2 + kstepB;
;             PG8_LDB(B0, 0, 0); PG8_LDB(B1, 0, 1); PG8_SCHED; PG8_LDA(At, 0, 0); PG8_STAGE(PG8_SA(1, 1), a1 + hstepA, voffA);
.LBB0_847:
	s_add_u32 s22, s10, 0xfff80080
	s_addc_u32 s23, s11, -1
	s_add_i32 s87, 0, 0x10000
	s_cmp_eq_u32 s86, 28
	s_cselect_b32 s35, s49, s23
	s_cselect_b32 s34, s82, s22

; #define PG8_STAGE(bufoff, gbase, voff) do { _Pragma("unroll") for (int _i = 0; _i < 2; ++_i) \
;         __builtin_amdgcn_global_load_lds((const unsigned*)((const char*)(gbase) + (voff)[_i]), (LAS unsigned*)(lds + (bufoff) + ldsw + _i * 8192), 16, 0, 0); } while (0)
; #define PG8_LDA(dst, b, h) do { _Pragma("unroll") for (int m = 0; m < 4; ++m) _Pragma("unroll") for (int k = 0; k < 2; ++k) dst[m][k] = *(const LAS bf16x8*)(lds + PG8_SA(b, h) + aoff + m * 2048 + k * 1024); } while (0)
; #define PG8_LDB(dst, b, h) do { _Pragma("unroll") for (int n = 0; n < 2; ++n) _Pragma("unroll") for (int k = 0; k < 2; ++k) dst[n][k] = *(const LAS bf16x8*)(lds + PG8_SB(b, h) + boff + n * 2048 + k * 1024); } while (0)
; #define PG8_SCHED __builtin_amdgcn_sched_barrier(0)
; template <class Epi, bool ALIGN_EPI>
; __device__ __forceinline__ void gemm_phase(LAS unsigned char* lds, const Gemm g, const StaticOrder& S, const Epi& E, const int tid) {
;     ...
;             const char* a2 = last ? nA : cA + (size_t)(t + 2) * kstepA; const char* b2 = last ? nB : cB + (size_t)(t + 2) * kstepB;
;             const char* a3 = a2 + kstepA; const char* b3 = b2 + kstepB;
;             PG8_LDB(B0, 0, 0); PG8_LDB(B1, 0, 1); PG8_SCHED; PG8_LDA(At, 0, 0); PG8_STAGE(PG8_SA(1, 1), a1 + hstepA, voffA);
	s_cselect_b32 s23, s47, s85
	s_cselect_b32 s22, s83, s84
	s_add_i32 s90, 0, 0x14000
	s_waitcnt lgkmcnt(0)
	ds_read_b128 v[132:135], v241
	ds_read_b128 v[148:151], v241 offset:1024
	ds_read_b128 v[156:159], v241 offset:2048
	ds_read_b128 v[160:163], v241 offset:3072

; #define PG8_STAGE(bufoff, gbase, voff) do { _Pragma("unroll") for (int _i = 0; _i < 2; ++_i) \
;         __builtin_amdgcn_global_load_lds((const unsigned*)((const char*)(gbase) + (voff)[_i]), (LAS unsigned*)(lds + (bufoff) + ldsw + _i * 8192), 16, 0, 0); } while (0)
; #define PG8_LDA(dst, b, h) do { _Pragma("unroll") for (int m = 0; m < 4; ++m) _Pragma("unroll") for (int k = 0; k < 2; ++k) dst[m][k] = *(const LAS bf16x8*)(lds + PG8_SA(b, h) + aoff + m * 2048 + k * 1024); } while (0)
; #define PG8_LDB(dst, b, h) do { _Pragma("unroll") for (int n = 0; n < 2; ++n) _Pragma("unroll") for (int k = 0; k < 2; ++k) dst[n][k] = *(const LAS bf16x8*)(lds + PG8_SB(b, h) + boff + n * 2048 + k * 1024); } while (0)
; #define PG8_SCHED __builtin_amdgcn_sched_barrier(0)
; template <class Epi, bool ALIGN_EPI>
; __device__ __forceinline__ void gemm_phase(LAS unsigned char* lds, const Gemm g, const StaticOrder& S, const Epi& E, const int tid) {
;     ...
;             PG8_LDB(B0, 0, 0); PG8_LDB(B1, 0, 1); PG8_SCHED; PG8_LDA(At, 0, 0); PG8_STAGE(PG8_SA(1, 1), a1 + hstepA, voffA);
	ds_read_b128 v[164:167], v242
	ds_read_b128 v[168:171], v242 offset:1024
	ds_read_b128 v[172:175], v242 offset:2048
	ds_read_b128 v[176:179], v242 offset:3072
	s_add_i32 m0, s70, 0xc000
	ds_read_b128 v[180:183], v155
	ds_read_b128 v[184:187], v155 offset:1024
	ds_read_b128 v[188:191], v155 offset:2048
	ds_read_b128 v[192:195], v155 offset:3072
	ds_read_b128 v[196:199], v155 offset:4096
	ds_read_b128 v[214:217], v155 offset:5120
	ds_read_b128 v[218:221], v155 offset:6144

; #define PG8_STAGE(bufoff, gbase, voff) do { _Pragma("unroll") for (int _i = 0; _i < 2; ++_i) \
;         __builtin_amdgcn_global_load_lds((const unsigned*)((const char*)(gbase) + (voff)[_i]), (LAS unsigned*)(lds + (bufoff) + ldsw + _i * 8192), 16, 0, 0); } while (0)
; #define PG8_LDA(dst, b, h) do { _Pragma("unroll") for (int m = 0; m < 4; ++m) _Pragma("unroll") for (int k = 0; k < 2; ++k) dst[m][k] = *(const LAS bf16x8*)(lds + PG8_SA(b, h) + aoff + m * 2048 + k * 1024); } while (0)
; #define PG8_LDB(dst, b, h) do { _Pragma("unroll") for (int n = 0; n < 2; ++n) _Pragma("unroll") for (int k = 0; k < 2; ++k) dst[n][k] = *(const LAS bf16x8*)(lds + PG8_SB(b, h) + boff + n * 2048 + k * 1024); } while (0)
; #define PG8_MMA(ai, bj, At, Bt) do { __builtin_amdgcn_s_setprio(1); _Pragma("unroll") for (int m = 0; m < 4; ++m) _Pragma("unroll") for (int n = 0; n < 2; ++n) _Pragma("unroll") for (int k = 0; k < 2; ++k) \
;         acc[ai][bj][m][n] = __builtin_amdgcn_mfma_f32_16x16x32_bf16(Bt[n][k], At[m][k], acc[ai][bj][m][n], 0, 0, 0); __builtin_amdgcn_s_setprio(0); } while (0)
; #define PG8_WAIT_V(n) asm volatile("s_waitcnt vmcnt(" #n ")" ::: "memory")
; #define PG8_WAIT_L(n) asm volatile("s_waitcnt lgkmcnt(" #n ")" ::: "memory")
; #define PG8_BAR __builtin_amdgcn_s_barrier()
; #define PG8_SCHED __builtin_amdgcn_sched_barrier(0)
; template <class Epi, bool ALIGN_EPI>
; __device__ __forceinline__ void gemm_phase(LAS unsigned char* lds, const Gemm g, const StaticOrder& S, const Epi& E, const int tid) {
;     ...
;             PG8_LDB(B0, 0, 0); PG8_LDB(B1, 0, 1); PG8_SCHED; PG8_LDA(At, 0, 0); PG8_STAGE(PG8_SA(1, 1), a1 + hstepA, voffA);
;             PG8_WAIT_V(8); PG8_WAIT_L(0); PG8_BAR; PG8_MMA(0, 0, At, B0); PG8_MMA(0, 1, At, B1); PG8_BAR; PG8_SCHED;
	global_load_lds_dwordx4 v144, s[10:11]
	s_add_i32 m0, s70, 0xe000
	ds_read_b128 v[222:225], v155 offset:7168
	global_load_lds_dwordx4 v146, s[10:11]
	s_waitcnt vmcnt(8)
	s_waitcnt lgkmcnt(0)
	s_barrier


; #define PG8_MMA(ai, bj, At, Bt) do { __builtin_amdgcn_s_setprio(1); _Pragma("unroll") for (int m = 0; m < 4; ++m) _Pragma("unroll") for (int n = 0; n < 2; ++n) _Pragma("unroll") for (int k = 0; k < 2; ++k) \
;         acc[ai][bj][m][n] = __builtin_amdgcn_mfma_f32_16x16x32_bf16(Bt[n][k], At[m][k], acc[ai][bj][m][n], 0, 0, 0); __builtin_amdgcn_s_setprio(0); } while (0)
; #define PG8_WAIT_V(n) asm volatile("s_waitcnt vmcnt(" #n ")" ::: "memory")
; #define PG8_WAIT_L(n) asm volatile("s_waitcnt lgkmcnt(" #n ")" ::: "memory")
; #define PG8_BAR __builtin_amdgcn_s_barrier()
; #define PG8_SCHED __builtin_amdgcn_sched_barrier(0)
; template <class Epi, bool ALIGN_EPI>
; __device__ __forceinline__ void gemm_phase(LAS unsigned char* lds, const Gemm g, const StaticOrder& S, const Epi& E, const int tid) {
;     ...
;             PG8_WAIT_V(8); PG8_WAIT_L(0); PG8_BAR; PG8_MMA(0, 0, At, B0); PG8_MMA(0, 1, At, B1); PG8_BAR; PG8_SCHED;
	v_mfma_f32_16x16x32_bf16 v[8:11], v[132:135], v[180:183], v[8:11]
	v_mfma_f32_16x16x32_bf16 v[8:11], v[148:151], v[184:187], v[8:11]
	v_mfma_f32_16x16x32_bf16 v[56:59], v[160:163], v[184:187], v[56:59]
	v_mfma_f32_16x16x32_bf16 v[56:59], v[156:159], v[180:183], v[56:59]
	v_mfma_f32_16x16x32_bf16 v[28:31], v[172:175], v[180:183], v[28:31]
	v_mfma_f32_16x16x32_bf16 v[28:31], v[176:179], v[184:187], v[28:31]
	v_mfma_f32_16x16x32_bf16 v[2:5], v[164:167], v[180:183], v[4:7]
	v_mfma_f32_16x16x32_bf16 v[2:5], v[168:171], v[184:187], v[2:5]
	v_mfma_f32_16x16x32_bf16 v[96:99], v[168:171], v[192:195], v[96:99]
	v_mfma_f32_16x16x32_bf16 v[96:99], v[164:167], v[188:191], v[96:99]
	v_mfma_f32_16x16x32_bf16 v[92:95], v[172:175], v[188:191], v[92:95]
	v_mfma_f32_16x16x32_bf16 v[92:95], v[176:179], v[192:195], v[92:95]
	v_mfma_f32_16x16x32_bf16 v[48:51], v[160:163], v[192:195], v[48:51]
	v_mfma_f32_16x16x32_bf16 v[48:51], v[156:159], v[188:191], v[48:51]
	v_mfma_f32_16x16x32_bf16 v[52:55], v[132:135], v[188:191], v[52:55]
	v_mfma_f32_16x16x32_bf16 v[52:55], v[148:151], v[192:195], v[52:55]


; #define PG8_MMA(ai, bj, At, Bt) do { __builtin_amdgcn_s_setprio(1); _Pragma("unroll") for (int m = 0; m < 4; ++m) _Pragma("unroll") for (int n = 0; n < 2; ++n) _Pragma("unroll") for (int k = 0; k < 2; ++k) \
;         acc[ai][bj][m][n] = __builtin_amdgcn_mfma_f32_16x16x32_bf16(Bt[n][k], At[m][k], acc[ai][bj][m][n], 0, 0, 0); __builtin_amdgcn_s_setprio(0); } while (0)
; #define PG8_WAIT_V(n) asm volatile("s_waitcnt vmcnt(" #n ")" ::: "memory")
; #define PG8_WAIT_L(n) asm volatile("s_waitcnt lgkmcnt(" #n ")" ::: "memory")
; #define PG8_BAR __builtin_amdgcn_s_barrier()
; #define PG8_SCHED __builtin_amdgcn_sched_barrier(0)
; template <class Epi, bool ALIGN_EPI>
; __device__ __forceinline__ void gemm_phase(LAS unsigned char* lds, const Gemm g, const StaticOrder& S, const Epi& E, const int tid) {
;     ...
;             PG8_WAIT_V(8); PG8_WAIT_L(0); PG8_BAR; PG8_MMA(0, 0, At, B0); PG8_MMA(0, 1, At, B1); PG8_BAR; PG8_SCHED;
	v_mfma_f32_16x16x32_bf16 v[44:47], v[148:151], v[214:217], v[44:47]
	v_mfma_f32_16x16x32_bf16 v[44:47], v[132:135], v[196:199], v[44:47]
	v_mfma_f32_16x16x32_bf16 v[40:43], v[156:159], v[196:199], v[40:43]
	v_mfma_f32_16x16x32_bf16 v[40:43], v[160:163], v[214:217], v[40:43]
	v_mfma_f32_16x16x32_bf16 v[84:87], v[176:179], v[214:217], v[84:87]
	v_mfma_f32_16x16x32_bf16 v[84:87], v[172:175], v[196:199], v[84:87]
	v_mfma_f32_16x16x32_bf16 v[88:91], v[164:167], v[196:199], v[88:91]
	v_mfma_f32_16x16x32_bf16 v[88:91], v[168:171], v[214:217], v[88:91]
	v_mfma_f32_16x16x32_bf16 v[80:83], v[168:171], v[222:225], v[80:83]
	v_mfma_f32_16x16x32_bf16 v[80:83], v[164:167], v[218:221], v[80:83]
	v_mfma_f32_16x16x32_bf16 v[76:79], v[172:175], v[218:221], v[76:79]
	v_mfma_f32_16x16x32_bf16 v[76:79], v[176:179], v[222:225], v[76:79]
	v_mfma_f32_16x16x32_bf16 v[32:35], v[160:163], v[222:225], v[32:35]
	v_mfma_f32_16x16x32_bf16 v[32:35], v[156:159], v[218:221], v[32:35]
	v_mfma_f32_16x16x32_bf16 v[36:39], v[132:135], v[218:221], v[36:39]
	v_mfma_f32_16x16x32_bf16 v[36:39], v[148:151], v[222:225], v[36:39]

; #define PG8_STAGE(bufoff, gbase, voff) do { _Pragma("unroll") for (int _i = 0; _i < 2; ++_i) \
;         __builtin_amdgcn_global_load_lds((const unsigned*)((const char*)(gbase) + (voff)[_i]), (LAS unsigned*)(lds + (bufoff) + ldsw + _i * 8192), 16, 0, 0); } while (0)
; #define PG8_LDA(dst, b, h) do { _Pragma("unroll") for (int m = 0; m < 4; ++m) _Pragma("unroll") for (int k = 0; k < 2; ++k) dst[m][k] = *(const LAS bf16x8*)(lds + PG8_SA(b, h) + aoff + m * 2048 + k * 1024); } while (0)
; #define PG8_MMA(ai, bj, At, Bt) do { __builtin_amdgcn_s_setprio(1); _Pragma("unroll") for (int m = 0; m < 4; ++m) _Pragma("unroll") for (int n = 0; n < 2; ++n) _Pragma("unroll") for (int k = 0; k < 2; ++k) \
;         acc[ai][bj][m][n] = __builtin_amdgcn_mfma_f32_16x16x32_bf16(Bt[n][k], At[m][k], acc[ai][bj][m][n], 0, 0, 0); __builtin_amdgcn_s_setprio(0); } while (0)
; #define PG8_WAIT_V(n) asm volatile("s_waitcnt vmcnt(" #n ")" ::: "memory")
; #define PG8_WAIT_L(n) asm volatile("s_waitcnt lgkmcnt(" #n ")" ::: "memory")
; #define PG8_BAR __builtin_amdgcn_s_barrier()
; #define PG8_SCHED __builtin_amdgcn_sched_barrier(0)
; template <class Epi, bool ALIGN_EPI>
; __device__ __forceinline__ void gemm_phase(LAS unsigned char* lds, const Gemm g, const StaticOrder& S, const Epi& E, const int tid) {
;     ...
;             PG8_WAIT_V(8); PG8_WAIT_L(0); PG8_BAR; PG8_MMA(0, 0, At, B0); PG8_MMA(0, 1, At, B1); PG8_BAR; PG8_SCHED;
;             PG8_LDA(At, 0, 1); PG8_STAGE(PG8_SB(0, 0), b2, voffB); PG8_STAGE(PG8_SB(0, 1), b2 + hstepB, voffB); PG8_STAGE(PG8_SA(0, 0), a2, voffA);
	s_barrier
	s_add_i32 s87, s87, s61
	s_mov_b32 m0, s87
	ds_read_b128 v[180:183], v155 offset:16384
	ds_read_b128 v[184:187], v155 offset:17408
	ds_read_b128 v[188:191], v155 offset:18432
	ds_read_b128 v[192:195], v155 offset:19456
	ds_read_b128 v[196:199], v155 offset:20480
	ds_read_b128 v[214:217], v155 offset:21504


; #define PG8_STAGE(bufoff, gbase, voff) do { _Pragma("unroll") for (int _i = 0; _i < 2; ++_i) \
;         __builtin_amdgcn_global_load_lds((const unsigned*)((const char*)(gbase) + (voff)[_i]), (LAS unsigned*)(lds + (bufoff) + ldsw + _i * 8192), 16, 0, 0); } while (0)
; #define PG8_LDA(dst, b, h) do { _Pragma("unroll") for (int m = 0; m < 4; ++m) _Pragma("unroll") for (int k = 0; k < 2; ++k) dst[m][k] = *(const LAS bf16x8*)(lds + PG8_SA(b, h) + aoff + m * 2048 + k * 1024); } while (0)
; #define PG8_MMA(ai, bj, At, Bt) do { __builtin_amdgcn_s_setprio(1); _Pragma("unroll") for (int m = 0; m < 4; ++m) _Pragma("unroll") for (int n = 0; n < 2; ++n) _Pragma("unroll") for (int k = 0; k < 2; ++k) \
;         acc[ai][bj][m][n] = __builtin_amdgcn_mfma_f32_16x16x32_bf16(Bt[n][k], At[m][k], acc[ai][bj][m][n], 0, 0, 0); __builtin_amdgcn_s_setprio(0); } while (0)
; #define PG8_WAIT_V(n) asm volatile("s_waitcnt vmcnt(" #n ")" ::: "memory")
; #define PG8_WAIT_L(n) asm volatile("s_waitcnt lgkmcnt(" #n ")" ::: "memory")
; #define PG8_BAR __builtin_amdgcn_s_barrier()
; #define PG8_SCHED __builtin_amdgcn_sched_barrier(0)
; template <class Epi, bool ALIGN_EPI>
; __device__ __forceinline__ void gemm_phase(LAS unsigned char* lds, const Gemm g, const StaticOrder& S, const Epi& E, const int tid) {
;     ...
;             PG8_LDA(At, 0, 1); PG8_STAGE(PG8_SB(0, 0), b2, voffB); PG8_STAGE(PG8_SB(0, 1), b2 + hstepB, voffB); PG8_STAGE(PG8_SA(0, 0), a2, voffA);
;             PG8_WAIT_V(8); PG8_WAIT_L(0); PG8_BAR; PG8_MMA(1, 0, At, B0); PG8_MMA(1, 1, At, B1); PG8_BAR; PG8_SCHED;
	global_load_lds_dwordx4 v140, s[22:23]
	s_add_i32 m0, s87, 0x2000
	s_add_u32 s88, s22, 0x4000
	s_addc_u32 s89, s23, 0
	s_add_i32 s87, s90, s61
	global_load_lds_dwordx4 v136, s[22:23]
	s_mov_b32 m0, s87
	v_lshl_add_u64 v[152:153], s[34:35], 0, v[142:143]
	global_load_lds_dwordx4 v140, s[88:89]
	s_add_i32 m0, s87, 0x2000
	v_lshl_add_u64 v[200:201], s[34:35], 0, v[138:139]
	global_load_lds_dwordx4 v136, s[88:89]
	s_mov_b32 m0, s70
	ds_read_b128 v[222:225], v155 offset:23552
	global_load_lds_dwordx4 v[152:153], off
	s_mov_b32 m0, s71
	ds_read_b128 v[218:221], v155 offset:22528
	global_load_lds_dwordx4 v[200:201], off
	s_waitcnt vmcnt(8)
	s_waitcnt lgkmcnt(0)
	s_barrier


; #define PG8_MMA(ai, bj, At, Bt) do { __builtin_amdgcn_s_setprio(1); _Pragma("unroll") for (int m = 0; m < 4; ++m) _Pragma("unroll") for (int n = 0; n < 2; ++n) _Pragma("unroll") for (int k = 0; k < 2; ++k) \
;         acc[ai][bj][m][n] = __builtin_amdgcn_mfma_f32_16x16x32_bf16(Bt[n][k], At[m][k], acc[ai][bj][m][n], 0, 0, 0); __builtin_amdgcn_s_setprio(0); } while (0)
; #define PG8_WAIT_V(n) asm volatile("s_waitcnt vmcnt(" #n ")" ::: "memory")
; #define PG8_WAIT_L(n) asm volatile("s_waitcnt lgkmcnt(" #n ")" ::: "memory")
; #define PG8_BAR __builtin_amdgcn_s_barrier()
; #define PG8_SCHED __builtin_amdgcn_sched_barrier(0)
; template <class Epi, bool ALIGN_EPI>
; __device__ __forceinline__ void gemm_phase(LAS unsigned char* lds, const Gemm g, const StaticOrder& S, const Epi& E, const int tid) {
;     ...
;             PG8_WAIT_V(8); PG8_WAIT_L(0); PG8_BAR; PG8_MMA(1, 0, At, B0); PG8_MMA(1, 1, At, B1); PG8_BAR; PG8_SCHED;
	v_mfma_f32_16x16x32_bf16 v[24:27], v[132:135], v[180:183], v[24:27]
	v_mfma_f32_16x16x32_bf16 v[24:27], v[148:151], v[184:187], v[24:27]
	v_mfma_f32_16x16x32_bf16 v[20:23], v[160:163], v[184:187], v[20:23]
	v_mfma_f32_16x16x32_bf16 v[20:23], v[156:159], v[180:183], v[20:23]
	v_mfma_f32_16x16x32_bf16 v[124:127], v[172:175], v[180:183], v[124:127]
	v_mfma_f32_16x16x32_bf16 v[124:127], v[176:179], v[184:187], v[124:127]
	v_mfma_f32_16x16x32_bf16 v[128:131], v[168:171], v[184:187], v[128:131]
	v_mfma_f32_16x16x32_bf16 v[128:131], v[164:167], v[180:183], v[128:131]
	v_mfma_f32_16x16x32_bf16 v[120:123], v[164:167], v[188:191], v[120:123]
	v_mfma_f32_16x16x32_bf16 v[120:123], v[168:171], v[192:195], v[120:123]
	v_mfma_f32_16x16x32_bf16 v[116:119], v[176:179], v[192:195], v[116:119]
	v_mfma_f32_16x16x32_bf16 v[116:119], v[172:175], v[188:191], v[116:119]
	v_mfma_f32_16x16x32_bf16 v[72:75], v[156:159], v[188:191], v[72:75]
	v_mfma_f32_16x16x32_bf16 v[72:75], v[160:163], v[192:195], v[72:75]
	v_mfma_f32_16x16x32_bf16 v[64:67], v[148:151], v[192:195], v[64:67]
	v_mfma_f32_16x16x32_bf16 v[64:67], v[132:135], v[188:191], v[64:67]


; #define PG8_MMA(ai, bj, At, Bt) do { __builtin_amdgcn_s_setprio(1); _Pragma("unroll") for (int m = 0; m < 4; ++m) _Pragma("unroll") for (int n = 0; n < 2; ++n) _Pragma("unroll") for (int k = 0; k < 2; ++k) \
;         acc[ai][bj][m][n] = __builtin_amdgcn_mfma_f32_16x16x32_bf16(Bt[n][k], At[m][k], acc[ai][bj][m][n], 0, 0, 0); __builtin_amdgcn_s_setprio(0); } while (0)
; #define PG8_WAIT_V(n) asm volatile("s_waitcnt vmcnt(" #n ")" ::: "memory")
; #define PG8_WAIT_L(n) asm volatile("s_waitcnt lgkmcnt(" #n ")" ::: "memory")
; #define PG8_BAR __builtin_amdgcn_s_barrier()
; #define PG8_SCHED __builtin_amdgcn_sched_barrier(0)
; template <class Epi, bool ALIGN_EPI>
; __device__ __forceinline__ void gemm_phase(LAS unsigned char* lds, const Gemm g, const StaticOrder& S, const Epi& E, const int tid) {
;     ...
;             PG8_WAIT_V(8); PG8_WAIT_L(0); PG8_BAR; PG8_MMA(1, 0, At, B0); PG8_MMA(1, 1, At, B1); PG8_BAR; PG8_SCHED;
	v_mfma_f32_16x16x32_bf16 v[16:19], v[132:135], v[196:199], v[16:19]
	v_mfma_f32_16x16x32_bf16 v[16:19], v[148:151], v[214:217], v[16:19]
	v_mfma_f32_16x16x32_bf16 v[12:15], v[160:163], v[214:217], v[12:15]
	v_mfma_f32_16x16x32_bf16 v[12:15], v[156:159], v[196:199], v[12:15]
	v_mfma_f32_16x16x32_bf16 v[108:111], v[172:175], v[196:199], v[108:111]
	v_mfma_f32_16x16x32_bf16 v[108:111], v[176:179], v[214:217], v[108:111]
	v_mfma_f32_16x16x32_bf16 v[112:115], v[168:171], v[214:217], v[112:115]
	v_mfma_f32_16x16x32_bf16 v[112:115], v[164:167], v[196:199], v[112:115]
	v_mfma_f32_16x16x32_bf16 v[104:107], v[164:167], v[218:221], v[104:107]
	v_mfma_f32_16x16x32_bf16 v[104:107], v[168:171], v[222:225], v[104:107]
	v_mfma_f32_16x16x32_bf16 v[100:103], v[176:179], v[222:225], v[100:103]
	v_mfma_f32_16x16x32_bf16 v[100:103], v[172:175], v[218:221], v[100:103]
	v_mfma_f32_16x16x32_bf16 v[68:71], v[156:159], v[218:221], v[68:71]
	v_mfma_f32_16x16x32_bf16 v[68:71], v[160:163], v[222:225], v[68:71]
	v_mfma_f32_16x16x32_bf16 v[60:63], v[148:151], v[222:225], v[60:63]
	v_mfma_f32_16x16x32_bf16 v[60:63], v[132:135], v[218:221], v[60:63]

; #define PG8_STAGE(bufoff, gbase, voff) do { _Pragma("unroll") for (int _i = 0; _i < 2; ++_i) \
;         __builtin_amdgcn_global_load_lds((const unsigned*)((const char*)(gbase) + (voff)[_i]), (LAS unsigned*)(lds + (bufoff) + ldsw + _i * 8192), 16, 0, 0); } while (0)
; #define PG8_LDA(dst, b, h) do { _Pragma("unroll") for (int m = 0; m < 4; ++m) _Pragma("unroll") for (int k = 0; k < 2; ++k) dst[m][k] = *(const LAS bf16x8*)(lds + PG8_SA(b, h) + aoff + m * 2048 + k * 1024); } while (0)
; #define PG8_LDB(dst, b, h) do { _Pragma("unroll") for (int n = 0; n < 2; ++n) _Pragma("unroll") for (int k = 0; k < 2; ++k) dst[n][k] = *(const LAS bf16x8*)(lds + PG8_SB(b, h) + boff + n * 2048 + k * 1024); } while (0)
; #define PG8_MMA(ai, bj, At, Bt) do { __builtin_amdgcn_s_setprio(1); _Pragma("unroll") for (int m = 0; m < 4; ++m) _Pragma("unroll") for (int n = 0; n < 2; ++n) _Pragma("unroll") for (int k = 0; k < 2; ++k) \
;         acc[ai][bj][m][n] = __builtin_amdgcn_mfma_f32_16x16x32_bf16(Bt[n][k], At[m][k], acc[ai][bj][m][n], 0, 0, 0); __builtin_amdgcn_s_setprio(0); } while (0)
; #define PG8_WAIT_V(n) asm volatile("s_waitcnt vmcnt(" #n ")" ::: "memory")
; #define PG8_WAIT_L(n) asm volatile("s_waitcnt lgkmcnt(" #n ")" ::: "memory")
; #define PG8_BAR __builtin_amdgcn_s_barrier()
; #define PG8_SCHED __builtin_amdgcn_sched_barrier(0)
; template <class Epi, bool ALIGN_EPI>
; __device__ __forceinline__ void gemm_phase(LAS unsigned char* lds, const Gemm g, const StaticOrder& S, const Epi& E, const int tid) {
;     ...
;             PG8_WAIT_V(8); PG8_WAIT_L(0); PG8_BAR; PG8_MMA(1, 0, At, B0); PG8_MMA(1, 1, At, B1); PG8_BAR; PG8_SCHED;
;             PG8_LDB(B0, 1, 0); PG8_LDB(B1, 1, 1); PG8_SCHED; PG8_LDA(At, 1, 0); PG8_STAGE(PG8_SA(0, 1), a2 + hstepA, voffA);
	s_barrier
	s_add_i32 s87, 0, 0x18000

; #define PG8_STAGE(bufoff, gbase, voff) do { _Pragma("unroll") for (int _i = 0; _i < 2; ++_i) \
;         __builtin_amdgcn_global_load_lds((const unsigned*)((const char*)(gbase) + (voff)[_i]), (LAS unsigned*)(lds + (bufoff) + ldsw + _i * 8192), 16, 0, 0); } while (0)
; #define PG8_LDA(dst, b, h) do { _Pragma("unroll") for (int m = 0; m < 4; ++m) _Pragma("unroll") for (int k = 0; k < 2; ++k) dst[m][k] = *(const LAS bf16x8*)(lds + PG8_SA(b, h) + aoff + m * 2048 + k * 1024); } while (0)
; #define PG8_LDB(dst, b, h) do { _Pragma("unroll") for (int n = 0; n < 2; ++n) _Pragma("unroll") for (int k = 0; k < 2; ++k) dst[n][k] = *(const LAS bf16x8*)(lds + PG8_SB(b, h) + boff + n * 2048 + k * 1024); } while (0)
; #define PG8_SCHED __builtin_amdgcn_sched_barrier(0)
; template <class Epi, bool ALIGN_EPI>
; __device__ __forceinline__ void gemm_phase(LAS unsigned char* lds, const Gemm g, const StaticOrder& S, const Epi& E, const int tid) {
;     ...
;             PG8_LDB(B0, 1, 0); PG8_LDB(B1, 1, 1); PG8_SCHED; PG8_LDA(At, 1, 0); PG8_STAGE(PG8_SA(0, 1), a2 + hstepA, voffA);
	s_add_i32 s88, 0, 0x1c000
	ds_read_b128 v[132:135], v243
	ds_read_b128 v[148:151], v243 offset:1024
	ds_read_b128 v[156:159], v243 offset:2048
	ds_read_b128 v[160:163], v243 offset:3072

; #define PG8_STAGE(bufoff, gbase, voff) do { _Pragma("unroll") for (int _i = 0; _i < 2; ++_i) \
;         __builtin_amdgcn_global_load_lds((const unsigned*)((const char*)(gbase) + (voff)[_i]), (LAS unsigned*)(lds + (bufoff) + ldsw + _i * 8192), 16, 0, 0); } while (0)
; #define PG8_LDA(dst, b, h) do { _Pragma("unroll") for (int m = 0; m < 4; ++m) _Pragma("unroll") for (int k = 0; k < 2; ++k) dst[m][k] = *(const LAS bf16x8*)(lds + PG8_SA(b, h) + aoff + m * 2048 + k * 1024); } while (0)
; #define PG8_LDB(dst, b, h) do { _Pragma("unroll") for (int n = 0; n < 2; ++n) _Pragma("unroll") for (int k = 0; k < 2; ++k) dst[n][k] = *(const LAS bf16x8*)(lds + PG8_SB(b, h) + boff + n * 2048 + k * 1024); } while (0)
; #define PG8_SCHED __builtin_amdgcn_sched_barrier(0)
; template <class Epi, bool ALIGN_EPI>
; __device__ __forceinline__ void gemm_phase(LAS unsigned char* lds, const Gemm g, const StaticOrder& S, const Epi& E, const int tid) {
;     ...
;             PG8_LDB(B0, 1, 0); PG8_LDB(B1, 1, 1); PG8_SCHED; PG8_LDA(At, 1, 0); PG8_STAGE(PG8_SA(0, 1), a2 + hstepA, voffA);
	ds_read_b128 v[164:167], v244
	ds_read_b128 v[168:171], v244 offset:1024
	ds_read_b128 v[172:175], v244 offset:2048
	ds_read_b128 v[176:179], v244 offset:3072
	s_add_u32 s34, s34, 0x80000
	s_addc_u32 s35, s35, 0
	s_mov_b32 m0, s72
	ds_read_b128 v[180:183], v155 offset:32768
	ds_read_b128 v[184:187], v155 offset:33792
	ds_read_b128 v[188:191], v155 offset:34816
	ds_read_b128 v[192:195], v155 offset:35840
	ds_read_b128 v[196:199], v155 offset:36864
	ds_read_b128 v[214:217], v155 offset:37888
	ds_read_b128 v[218:221], v155 offset:38912

; #define PG8_STAGE(bufoff, gbase, voff) do { _Pragma("unroll") for (int _i = 0; _i < 2; ++_i) \
;         __builtin_amdgcn_global_load_lds((const unsigned*)((const char*)(gbase) + (voff)[_i]), (LAS unsigned*)(lds + (bufoff) + ldsw + _i * 8192), 16, 0, 0); } while (0)
; #define PG8_LDA(dst, b, h) do { _Pragma("unroll") for (int m = 0; m < 4; ++m) _Pragma("unroll") for (int k = 0; k < 2; ++k) dst[m][k] = *(const LAS bf16x8*)(lds + PG8_SA(b, h) + aoff + m * 2048 + k * 1024); } while (0)
; #define PG8_LDB(dst, b, h) do { _Pragma("unroll") for (int n = 0; n < 2; ++n) _Pragma("unroll") for (int k = 0; k < 2; ++k) dst[n][k] = *(const LAS bf16x8*)(lds + PG8_SB(b, h) + boff + n * 2048 + k * 1024); } while (0)
; #define PG8_MMA(ai, bj, At, Bt) do { __builtin_amdgcn_s_setprio(1); _Pragma("unroll") for (int m = 0; m < 4; ++m) _Pragma("unroll") for (int n = 0; n < 2; ++n) _Pragma("unroll") for (int k = 0; k < 2; ++k) \
;         acc[ai][bj][m][n] = __builtin_amdgcn_mfma_f32_16x16x32_bf16(Bt[n][k], At[m][k], acc[ai][bj][m][n], 0, 0, 0); __builtin_amdgcn_s_setprio(0); } while (0)
; #define PG8_WAIT_V(n) asm volatile("s_waitcnt vmcnt(" #n ")" ::: "memory")
; #define PG8_WAIT_L(n) asm volatile("s_waitcnt lgkmcnt(" #n ")" ::: "memory")
; #define PG8_BAR __builtin_amdgcn_s_barrier()
; #define PG8_SCHED __builtin_amdgcn_sched_barrier(0)
; template <class Epi, bool ALIGN_EPI>
; __device__ __forceinline__ void gemm_phase(LAS unsigned char* lds, const Gemm g, const StaticOrder& S, const Epi& E, const int tid) {
;     ...
;             PG8_LDB(B0, 1, 0); PG8_LDB(B1, 1, 1); PG8_SCHED; PG8_LDA(At, 1, 0); PG8_STAGE(PG8_SA(0, 1), a2 + hstepA, voffA);
;             PG8_WAIT_V(8); PG8_WAIT_L(0); PG8_BAR; PG8_MMA(0, 0, At, B0); PG8_MMA(0, 1, At, B1); PG8_BAR; PG8_SCHED;
	global_load_lds_dwordx4 v142, s[34:35]
	s_mov_b32 m0, s73
	ds_read_b128 v[222:225], v155 offset:39936
	global_load_lds_dwordx4 v138, s[34:35]
	s_waitcnt vmcnt(8)
	s_waitcnt lgkmcnt(0)
	s_barrier


; #define PG8_MMA(ai, bj, At, Bt) do { __builtin_amdgcn_s_setprio(1); _Pragma("unroll") for (int m = 0; m < 4; ++m) _Pragma("unroll") for (int n = 0; n < 2; ++n) _Pragma("unroll") for (int k = 0; k < 2; ++k) \
;         acc[ai][bj][m][n] = __builtin_amdgcn_mfma_f32_16x16x32_bf16(Bt[n][k], At[m][k], acc[ai][bj][m][n], 0, 0, 0); __builtin_amdgcn_s_setprio(0); } while (0)
; #define PG8_WAIT_V(n) asm volatile("s_waitcnt vmcnt(" #n ")" ::: "memory")
; #define PG8_WAIT_L(n) asm volatile("s_waitcnt lgkmcnt(" #n ")" ::: "memory")
; #define PG8_BAR __builtin_amdgcn_s_barrier()
; #define PG8_SCHED __builtin_amdgcn_sched_barrier(0)
; template <class Epi, bool ALIGN_EPI>
; __device__ __forceinline__ void gemm_phase(LAS unsigned char* lds, const Gemm g, const StaticOrder& S, const Epi& E, const int tid) {
;     ...
;             PG8_WAIT_V(8); PG8_WAIT_L(0); PG8_BAR; PG8_MMA(0, 0, At, B0); PG8_MMA(0, 1, At, B1); PG8_BAR; PG8_SCHED;
	v_mfma_f32_16x16x32_bf16 v[6:9], v[132:135], v[180:183], v[8:11]
	v_mfma_f32_16x16x32_bf16 v[8:11], v[148:151], v[184:187], v[6:9]
	v_mfma_f32_16x16x32_bf16 v[56:59], v[160:163], v[184:187], v[56:59]
	v_mfma_f32_16x16x32_bf16 v[56:59], v[156:159], v[180:183], v[56:59]
	v_mfma_f32_16x16x32_bf16 v[28:31], v[172:175], v[180:183], v[28:31]
	v_mfma_f32_16x16x32_bf16 v[28:31], v[176:179], v[184:187], v[28:31]
	v_mfma_f32_16x16x32_bf16 v[2:5], v[164:167], v[180:183], v[2:5]
	v_mfma_f32_16x16x32_bf16 v[4:7], v[168:171], v[184:187], v[2:5]
	v_mfma_f32_16x16x32_bf16 v[96:99], v[168:171], v[192:195], v[96:99]
	v_mfma_f32_16x16x32_bf16 v[96:99], v[164:167], v[188:191], v[96:99]
	v_mfma_f32_16x16x32_bf16 v[92:95], v[172:175], v[188:191], v[92:95]
	v_mfma_f32_16x16x32_bf16 v[92:95], v[176:179], v[192:195], v[92:95]
	v_mfma_f32_16x16x32_bf16 v[48:51], v[160:163], v[192:195], v[48:51]
	v_mfma_f32_16x16x32_bf16 v[48:51], v[156:159], v[188:191], v[48:51]
	v_mfma_f32_16x16x32_bf16 v[52:55], v[132:135], v[188:191], v[52:55]
	v_mfma_f32_16x16x32_bf16 v[52:55], v[148:151], v[192:195], v[52:55]


; #define PG8_MMA(ai, bj, At, Bt) do { __builtin_amdgcn_s_setprio(1); _Pragma("unroll") for (int m = 0; m < 4; ++m) _Pragma("unroll") for (int n = 0; n < 2; ++n) _Pragma("unroll") for (int k = 0; k < 2; ++k) \
;         acc[ai][bj][m][n] = __builtin_amdgcn_mfma_f32_16x16x32_bf16(Bt[n][k], At[m][k], acc[ai][bj][m][n], 0, 0, 0); __builtin_amdgcn_s_setprio(0); } while (0)
; #define PG8_WAIT_V(n) asm volatile("s_waitcnt vmcnt(" #n ")" ::: "memory")
; #define PG8_WAIT_L(n) asm volatile("s_waitcnt lgkmcnt(" #n ")" ::: "memory")
; #define PG8_BAR __builtin_amdgcn_s_barrier()
; #define PG8_SCHED __builtin_amdgcn_sched_barrier(0)
; template <class Epi, bool ALIGN_EPI>
; __device__ __forceinline__ void gemm_phase(LAS unsigned char* lds, const Gemm g, const StaticOrder& S, const Epi& E, const int tid) {
;     ...
;             PG8_WAIT_V(8); PG8_WAIT_L(0); PG8_BAR; PG8_MMA(0, 0, At, B0); PG8_MMA(0, 1, At, B1); PG8_BAR; PG8_SCHED;
	v_mfma_f32_16x16x32_bf16 v[44:47], v[148:151], v[214:217], v[44:47]
	v_mfma_f32_16x16x32_bf16 v[44:47], v[132:135], v[196:199], v[44:47]
	v_mfma_f32_16x16x32_bf16 v[40:43], v[156:159], v[196:199], v[40:43]
	v_mfma_f32_16x16x32_bf16 v[40:43], v[160:163], v[214:217], v[40:43]
	v_mfma_f32_16x16x32_bf16 v[84:87], v[176:179], v[214:217], v[84:87]
	v_mfma_f32_16x16x32_bf16 v[84:87], v[172:175], v[196:199], v[84:87]
	v_mfma_f32_16x16x32_bf16 v[88:91], v[164:167], v[196:199], v[88:91]
	v_mfma_f32_16x16x32_bf16 v[88:91], v[168:171], v[214:217], v[88:91]
	v_mfma_f32_16x16x32_bf16 v[80:83], v[168:171], v[222:225], v[80:83]
	v_mfma_f32_16x16x32_bf16 v[80:83], v[164:167], v[218:221], v[80:83]
	v_mfma_f32_16x16x32_bf16 v[76:79], v[172:175], v[218:221], v[76:79]
	v_mfma_f32_16x16x32_bf16 v[76:79], v[176:179], v[222:225], v[76:79]
	v_mfma_f32_16x16x32_bf16 v[32:35], v[160:163], v[222:225], v[32:35]
	v_mfma_f32_16x16x32_bf16 v[32:35], v[156:159], v[218:221], v[32:35]
	v_mfma_f32_16x16x32_bf16 v[36:39], v[132:135], v[218:221], v[36:39]
	v_mfma_f32_16x16x32_bf16 v[36:39], v[148:151], v[222:225], v[36:39]

; #define PG8_STAGE(bufoff, gbase, voff) do { _Pragma("unroll") for (int _i = 0; _i < 2; ++_i) \
;         __builtin_amdgcn_global_load_lds((const unsigned*)((const char*)(gbase) + (voff)[_i]), (LAS unsigned*)(lds + (bufoff) + ldsw + _i * 8192), 16, 0, 0); } while (0)
; #define PG8_LDA(dst, b, h) do { _Pragma("unroll") for (int m = 0; m < 4; ++m) _Pragma("unroll") for (int k = 0; k < 2; ++k) dst[m][k] = *(const LAS bf16x8*)(lds + PG8_SA(b, h) + aoff + m * 2048 + k * 1024); } while (0)
; #define PG8_MMA(ai, bj, At, Bt) do { __builtin_amdgcn_s_setprio(1); _Pragma("unroll") for (int m = 0; m < 4; ++m) _Pragma("unroll") for (int n = 0; n < 2; ++n) _Pragma("unroll") for (int k = 0; k < 2; ++k) \
;         acc[ai][bj][m][n] = __builtin_amdgcn_mfma_f32_16x16x32_bf16(Bt[n][k], At[m][k], acc[ai][bj][m][n], 0, 0, 0); __builtin_amdgcn_s_setprio(0); } while (0)
; #define PG8_WAIT_V(n) asm volatile("s_waitcnt vmcnt(" #n ")" ::: "memory")
; #define PG8_WAIT_L(n) asm volatile("s_waitcnt lgkmcnt(" #n ")" ::: "memory")
; #define PG8_BAR __builtin_amdgcn_s_barrier()
; #define PG8_SCHED __builtin_amdgcn_sched_barrier(0)
; template <class Epi, bool ALIGN_EPI>
; __device__ __forceinline__ void gemm_phase(LAS unsigned char* lds, const Gemm g, const StaticOrder& S, const Epi& E, const int tid) {
;     ...
;             PG8_WAIT_V(8); PG8_WAIT_L(0); PG8_BAR; PG8_MMA(0, 0, At, B0); PG8_MMA(0, 1, At, B1); PG8_BAR; PG8_SCHED;
;             PG8_LDA(At, 1, 1); PG8_STAGE(PG8_SB(1, 0), b3, voffB); PG8_STAGE(PG8_SB(1, 1), b3 + hstepB, voffB); PG8_STAGE(PG8_SA(1, 0), a3, voffA);
	s_barrier
	s_add_u32 s34, s22, 0x8000
	s_addc_u32 s35, s23, 0
	s_add_i32 s87, s87, s61
	s_mov_b32 m0, s87
	ds_read_b128 v[180:183], v155 offset:49152
	ds_read_b128 v[184:187], v155 offset:50176
	ds_read_b128 v[188:191], v155 offset:51200
	ds_read_b128 v[192:195], v155 offset:52224


; #define PG8_STAGE(bufoff, gbase, voff) do { _Pragma("unroll") for (int _i = 0; _i < 2; ++_i) \
;         __builtin_amdgcn_global_load_lds((const unsigned*)((const char*)(gbase) + (voff)[_i]), (LAS unsigned*)(lds + (bufoff) + ldsw + _i * 8192), 16, 0, 0); } while (0)
; #define PG8_LDA(dst, b, h) do { _Pragma("unroll") for (int m = 0; m < 4; ++m) _Pragma("unroll") for (int k = 0; k < 2; ++k) dst[m][k] = *(const LAS bf16x8*)(lds + PG8_SA(b, h) + aoff + m * 2048 + k * 1024); } while (0)
; #define PG8_MMA(ai, bj, At, Bt) do { __builtin_amdgcn_s_setprio(1); _Pragma("unroll") for (int m = 0; m < 4; ++m) _Pragma("unroll") for (int n = 0; n < 2; ++n) _Pragma("unroll") for (int k = 0; k < 2; ++k) \
;         acc[ai][bj][m][n] = __builtin_amdgcn_mfma_f32_16x16x32_bf16(Bt[n][k], At[m][k], acc[ai][bj][m][n], 0, 0, 0); __builtin_amdgcn_s_setprio(0); } while (0)
; #define PG8_WAIT_V(n) asm volatile("s_waitcnt vmcnt(" #n ")" ::: "memory")
; #define PG8_WAIT_L(n) asm volatile("s_waitcnt lgkmcnt(" #n ")" ::: "memory")
; #define PG8_BAR __builtin_amdgcn_s_barrier()
; #define PG8_SCHED __builtin_amdgcn_sched_barrier(0)
; template <class Epi, bool ALIGN_EPI>
; __device__ __forceinline__ void gemm_phase(LAS unsigned char* lds, const Gemm g, const StaticOrder& S, const Epi& E, const int tid) {
;     ...
;             PG8_LDA(At, 1, 1); PG8_STAGE(PG8_SB(1, 0), b3, voffB); PG8_STAGE(PG8_SB(1, 1), b3 + hstepB, voffB); PG8_STAGE(PG8_SA(1, 0), a3, voffA);
;             PG8_WAIT_V(8); PG8_WAIT_L(0); PG8_BAR; PG8_MMA(1, 0, At, B0); PG8_MMA(1, 1, At, B1); PG8_BAR; PG8_SCHED;
	global_load_lds_dwordx4 v140, s[34:35]
	s_add_i32 m0, s87, 0x2000
	s_add_u32 s22, s22, 0xc000
	s_addc_u32 s23, s23, 0
	global_load_lds_dwordx4 v136, s[34:35]
	s_add_i32 s34, s88, s61
	s_mov_b32 m0, s34
	ds_read_b128 v[222:225], v155 offset:56320
	global_load_lds_dwordx4 v140, s[22:23]
	s_add_i32 m0, s34, 0x2000
	ds_read_b128 v[218:221], v155 offset:55296
	global_load_lds_dwordx4 v136, s[22:23]
	v_lshl_add_u64 v[2:3], v[152:153], 0, s[6:7]
	s_mov_b32 m0, s78
	ds_read_b128 v[214:217], v155 offset:54272
	global_load_lds_dwordx4 v[2:3], off
	v_lshl_add_u64 v[2:3], v[200:201], 0, s[6:7]
	s_mov_b32 m0, s79
	ds_read_b128 v[196:199], v155 offset:53248
	global_load_lds_dwordx4 v[2:3], off
	s_waitcnt vmcnt(8)
	s_waitcnt lgkmcnt(0)
	s_barrier


; #define PG8_MMA(ai, bj, At, Bt) do { __builtin_amdgcn_s_setprio(1); _Pragma("unroll") for (int m = 0; m < 4; ++m) _Pragma("unroll") for (int n = 0; n < 2; ++n) _Pragma("unroll") for (int k = 0; k < 2; ++k) \
;         acc[ai][bj][m][n] = __builtin_amdgcn_mfma_f32_16x16x32_bf16(Bt[n][k], At[m][k], acc[ai][bj][m][n], 0, 0, 0); __builtin_amdgcn_s_setprio(0); } while (0)
; #define PG8_WAIT_V(n) asm volatile("s_waitcnt vmcnt(" #n ")" ::: "memory")
; #define PG8_WAIT_L(n) asm volatile("s_waitcnt lgkmcnt(" #n ")" ::: "memory")
; #define PG8_BAR __builtin_amdgcn_s_barrier()
; #define PG8_SCHED __builtin_amdgcn_sched_barrier(0)
; template <class Epi, bool ALIGN_EPI>
; __device__ __forceinline__ void gemm_phase(LAS unsigned char* lds, const Gemm g, const StaticOrder& S, const Epi& E, const int tid) {
;     ...
;             PG8_WAIT_V(8); PG8_WAIT_L(0); PG8_BAR; PG8_MMA(1, 0, At, B0); PG8_MMA(1, 1, At, B1); PG8_BAR; PG8_SCHED;
	v_mfma_f32_16x16x32_bf16 v[24:27], v[132:135], v[180:183], v[24:27]
	v_mfma_f32_16x16x32_bf16 v[24:27], v[148:151], v[184:187], v[24:27]
	v_mfma_f32_16x16x32_bf16 v[20:23], v[160:163], v[184:187], v[20:23]
	v_mfma_f32_16x16x32_bf16 v[20:23], v[156:159], v[180:183], v[20:23]
	v_mfma_f32_16x16x32_bf16 v[124:127], v[172:175], v[180:183], v[124:127]
	v_mfma_f32_16x16x32_bf16 v[124:127], v[176:179], v[184:187], v[124:127]
	v_mfma_f32_16x16x32_bf16 v[128:131], v[168:171], v[184:187], v[128:131]
	v_mfma_f32_16x16x32_bf16 v[128:131], v[164:167], v[180:183], v[128:131]
	v_mfma_f32_16x16x32_bf16 v[120:123], v[164:167], v[188:191], v[120:123]
	v_mfma_f32_16x16x32_bf16 v[120:123], v[168:171], v[192:195], v[120:123]
	v_mfma_f32_16x16x32_bf16 v[116:119], v[176:179], v[192:195], v[116:119]
	v_mfma_f32_16x16x32_bf16 v[116:119], v[172:175], v[188:191], v[116:119]
	v_mfma_f32_16x16x32_bf16 v[72:75], v[156:159], v[188:191], v[72:75]
	v_mfma_f32_16x16x32_bf16 v[72:75], v[160:163], v[192:195], v[72:75]
	v_mfma_f32_16x16x32_bf16 v[64:67], v[148:151], v[192:195], v[64:67]
	v_mfma_f32_16x16x32_bf16 v[64:67], v[132:135], v[188:191], v[64:67]


; #define PG8_MMA(ai, bj, At, Bt) do { __builtin_amdgcn_s_setprio(1); _Pragma("unroll") for (int m = 0; m < 4; ++m) _Pragma("unroll") for (int n = 0; n < 2; ++n) _Pragma("unroll") for (int k = 0; k < 2; ++k) \
;         acc[ai][bj][m][n] = __builtin_amdgcn_mfma_f32_16x16x32_bf16(Bt[n][k], At[m][k], acc[ai][bj][m][n], 0, 0, 0); __builtin_amdgcn_s_setprio(0); } while (0)
; #define PG8_WAIT_V(n) asm volatile("s_waitcnt vmcnt(" #n ")" ::: "memory")
; #define PG8_WAIT_L(n) asm volatile("s_waitcnt lgkmcnt(" #n ")" ::: "memory")
; #define PG8_BAR __builtin_amdgcn_s_barrier()
; #define PG8_SCHED __builtin_amdgcn_sched_barrier(0)
; template <class Epi, bool ALIGN_EPI>
; __device__ __forceinline__ void gemm_phase(LAS unsigned char* lds, const Gemm g, const StaticOrder& S, const Epi& E, const int tid) {
;     ...
;             PG8_WAIT_V(8); PG8_WAIT_L(0); PG8_BAR; PG8_MMA(1, 0, At, B0); PG8_MMA(1, 1, At, B1); PG8_BAR; PG8_SCHED;
	v_mfma_f32_16x16x32_bf16 v[16:19], v[132:135], v[196:199], v[16:19]
	v_mfma_f32_16x16x32_bf16 v[16:19], v[148:151], v[214:217], v[16:19]
	v_mfma_f32_16x16x32_bf16 v[12:15], v[160:163], v[214:217], v[12:15]
	v_mfma_f32_16x16x32_bf16 v[12:15], v[156:159], v[196:199], v[12:15]
	v_mfma_f32_16x16x32_bf16 v[108:111], v[172:175], v[196:199], v[108:111]
	v_mfma_f32_16x16x32_bf16 v[108:111], v[176:179], v[214:217], v[108:111]
	v_mfma_f32_16x16x32_bf16 v[112:115], v[168:171], v[214:217], v[112:115]
	v_mfma_f32_16x16x32_bf16 v[112:115], v[164:167], v[196:199], v[112:115]
	v_mfma_f32_16x16x32_bf16 v[104:107], v[164:167], v[218:221], v[104:107]
	v_mfma_f32_16x16x32_bf16 v[104:107], v[168:171], v[222:225], v[104:107]
	v_mfma_f32_16x16x32_bf16 v[100:103], v[176:179], v[222:225], v[100:103]
	v_mfma_f32_16x16x32_bf16 v[100:103], v[172:175], v[218:221], v[100:103]
	v_mfma_f32_16x16x32_bf16 v[68:71], v[156:159], v[218:221], v[68:71]
	v_mfma_f32_16x16x32_bf16 v[68:71], v[160:163], v[222:225], v[68:71]
	v_mfma_f32_16x16x32_bf16 v[60:63], v[148:151], v[222:225], v[60:63]
	v_mfma_f32_16x16x32_bf16 v[60:63], v[132:135], v[218:221], v[60:63]

; #define PG8_MMA(ai, bj, At, Bt) do { __builtin_amdgcn_s_setprio(1); _Pragma("unroll") for (int m = 0; m < 4; ++m) _Pragma("unroll") for (int n = 0; n < 2; ++n) _Pragma("unroll") for (int k = 0; k < 2; ++k) \
;         acc[ai][bj][m][n] = __builtin_amdgcn_mfma_f32_16x16x32_bf16(Bt[n][k], At[m][k], acc[ai][bj][m][n], 0, 0, 0); __builtin_amdgcn_s_setprio(0); } while (0)
; #define PG8_WAIT_V(n) asm volatile("s_waitcnt vmcnt(" #n ")" ::: "memory")
; #define PG8_WAIT_L(n) asm volatile("s_waitcnt lgkmcnt(" #n ")" ::: "memory")
; #define PG8_BAR __builtin_amdgcn_s_barrier()
; #define PG8_SCHED __builtin_amdgcn_sched_barrier(0)
; __device__ __forceinline__ u32x4 zero_frag() { unsigned z_ = 0u; asm volatile("" : "+v"(z_)); return (u32x4){z_, z_, z_, z_}; }
; __device__ __forceinline__ void epi_lane(int& fr, int& fq) { unsigned ones = ~0u; asm volatile("" : "+s"(ones)); const int ln = (int)__builtin_amdgcn_mbcnt_hi(ones, __builtin_amdgcn_mbcnt_lo(ones, 0u)); fr = ln & 15; fq = ln >> 4; }
; template <class Epi, bool ALIGN_EPI>
; __device__ __forceinline__ void gemm_phase(LAS unsigned char* lds, const Gemm g, const StaticOrder& S, const Epi& E, const int tid) {
;     ...
;             PG8_WAIT_V(8); PG8_WAIT_L(0); PG8_BAR; PG8_MMA(1, 0, At, B0); PG8_MMA(1, 1, At, B1); PG8_BAR; PG8_SCHED;
;         }
;         if constexpr (ALIGN_EPI) { if (wr == 0) PG8_BAR; }
;     __device__ __forceinline__ void operator()(f32x4 (&acc)[2][2][4][2], const Unit& u, int wr, int wc, LAS unsigned char* lds, int& rs_pm) const {
;         int fr, fq; epi_lane(fr, fq);
;         const int row0 = u.pm * BM + wr * 64 + fr, col0 = u.pn * BM + wc * 32 + 8 * fq; u32x4 zb = zero_frag();
; #pragma unroll
;         for (int ai = 0; ai < 2; ++ai)
; #pragma unroll
;             for (int m = 0; m < 4; ++m) { float ss = 0.f;
;                 bf16* const xrow = xb + (((size_t)(u.pm * 32 + u.pn * 4 + (wc >> 1)) * BM + (wr * 64 + fr + ai * HALF + m * 16)) * 64 + (wc & 1) * 32 + 8 * fq);
; #pragma unroll
;                 for (int bj = 0; bj < 2; ++bj) {
;                     const u32x4 xw = *(const u32x4*)(xrow + (size_t)bj * (2 * BM * 64));
	s_barrier
	s_add_i32 s86, s86, 2
	s_add_u32 s10, s10, 0x100
	s_addc_u32 s11, s11, 0
	s_add_u32 s84, s84, 0x10000
	s_addc_u32 s85, s85, 0
	s_cmp_gt_u32 s86, 29
	s_cbranch_scc0 .LBB0_847
	v_and_b32_e32 v222, 15, v238
	v_lshrrev_b32_e32 v156, 4, v238
	s_lshl_b32 s100, s40, 5
	s_lshl_b32 s101, s41, 2
	v_lshlrev_b32_e32 v222, 7, v222
	s_add_i32 s100, s100, s101
	s_or_b32 s100, s100, s80
	v_lshl_or_b32 v222, v156, 4, v222
	s_ashr_i32 s101, s100, 31
	s_lshl_b64 s[100:101], s[100:101], 15
	s_add_u32 s98, s74, s100
	s_addc_u32 s99, s75, s101
	s_add_u32 s98, s98, s30
	s_addc_u32 s99, s99, s31
	s_lshl_b32 s100, s77, 7
	s_add_u32 s98, s98, s100
	s_addc_u32 s99, s99, 0
	s_lshl_b32 s100, s40, 15
	s_lshl_b32 s101, s77, 7
	s_add_i32 s100, s100, s101
	s_lshl_b32 s101, s41, 4
	s_add_i32 s100, s100, s101
	s_lshl_b32 s101, s76, 2
	s_add_i32 s100, s100, s101
	s_add_u32 s22, s42, s100
	s_addc_u32 s23, s43, 0
	global_load_dwordx4 v[176:179], v222, s[98:99]
	s_add_u32 s100, s98, 0x10000
	s_addc_u32 s101, s99, 0
	global_load_dwordx4 v[180:183], v222, s[100:101]
	global_load_dwordx4 v[184:187], v222, s[98:99] offset:2048
	s_add_u32 s100, s98, 0x10000
	s_addc_u32 s101, s99, 0
	global_load_dwordx4 v[188:191], v222, s[100:101] offset:2048
	s_add_u32 s100, s98, 0x1000
	s_addc_u32 s101, s99, 0
	global_load_dwordx4 v[192:195], v222, s[100:101]
	s_add_u32 s100, s98, 0x11000
	s_addc_u32 s101, s99, 0
	global_load_dwordx4 v[196:199], v222, s[100:101]
	s_add_u32 s100, s98, 0x1000
	s_addc_u32 s101, s99, 0
	global_load_dwordx4 v[214:217], v222, s[100:101] offset:2048
	s_add_u32 s100, s98, 0x11000
	s_addc_u32 s101, s99, 0
	global_load_dwordx4 v[218:221], v222, s[100:101] offset:2048
	s_and_b64 vcc, exec, s[44:45]
	s_cbranch_vccz .LBB0_850
	s_barrier
